# a+b plus (c): s_setprio 0 moved from before to after the end-of-MMA barrier at 28 sites (one issue slot off the MMA hand-off path)
# baseline (speedup 1.0000x reference)
; #define PG8_STAGE(bufoff, gbase, voff) do { const char* _gb = (const char*)(gbase); asm volatile("" : "+s"(_gb)); _Pragma("unroll") for (int _i = 0; _i < 2; ++_i) { asm volatile("" : "+v"((voff)[_i])); \
;         __builtin_amdgcn_global_load_lds((const unsigned*)(_gb + (voff)[_i]), (PG8_LAS unsigned*)(lds + (bufoff) + ldsw + _i * 8192), 16, 0, 0); } } while (0)
; #define PG8_LDA(dst, b, h) do { _Pragma("unroll") for (int m = 0; m < 4; ++m) _Pragma("unroll") for (int k = 0; k < 2; ++k) dst[m][k] = *(const PG8_LAS bf16x8*)(lds + PG8_SA(b, h) + aoff + m * 2048 + k * 1024); } while (0)
; #define PG8_LDB(dst, b, h) do { _Pragma("unroll") for (int n = 0; n < 2; ++n) _Pragma("unroll") for (int k = 0; k < 2; ++k) dst[n][k] = *(const PG8_LAS bf16x8*)(lds + PG8_SB(b, h) + boff + n * 2048 + k * 1024); } while (0)
; #define PG8_WAIT_V(n) asm volatile("s_waitcnt vmcnt(" #n ")" ::: "memory")
; #define PG8_WAIT_L(n) asm volatile("s_waitcnt lgkmcnt(" #n ")" ::: "memory")
; #define PG8_BAR __builtin_amdgcn_s_barrier()
; #define PG8_SCHED __builtin_amdgcn_sched_barrier(0)
; #define PG8_STAGE(bufoff, gbase, voff) do { const char* _gb = (const char*)(gbase); asm volatile("" : "+s"(_gb)); _Pragma("unroll") for (int _i = 0; _i < 2; ++_i) { asm volatile("" : "+v"((voff)[_i])); \
;         __builtin_amdgcn_global_load_lds((const unsigned*)(_gb + (voff)[_i]), (PG8_LAS unsigned*)(lds + (bufoff) + ldsw + _i * 8192), 16, 0, 0); } } while (0)
; #define PG8_LDA(dst, b, h) do { _Pragma("unroll") for (int m = 0; m < 4; ++m) _Pragma("unroll") for (int k = 0; k < 2; ++k) dst[m][k] = *(const PG8_LAS bf16x8*)(lds + PG8_SA(b, h) + aoff + m * 2048 + k * 1024); } while (0)
; #define PG8_WAIT_V(n) asm volatile("s_waitcnt vmcnt(" #n ")" ::: "memory")
; template <class Epi, class Sched, bool ALIGN_EPI = false, bool SP2 = false>
; __device__ __forceinline__ void gemm_phase(PG8_LAS unsigned char* lds, const Gemm g, const Sched& S, const Epi& E) {
;     ...
;             PG8_LDB(B0, 0, 0); PG8_LDB(B1, 0, 1); PG8_SCHED; PG8_LDA(At, 0, 0); PG8_STAGE(PG8_SA(1, 1), a1 + hstep, voffA);
;             PG8_WAIT_V(8); PG8_WAIT_L(0); PG8_BAR; PG8_MMA2(0); PG8_BAR; PG8_SCHED;
;             PG8_LDA(At, 0, 1); PG8_STAGE(PG8_SB(0, 0), b2, voffB); PG8_STAGE(PG8_SB(0, 1), b2 + hstep, voffB); PG8_STAGE(PG8_SA(0, 0), a2, voffA);
;             PG8_WAIT_V(8); PG8_WAIT_L(0); PG8_BAR; PG8_MMA2(1); PG8_BAR; PG8_SCHED;
.LBB0_313:
	ds_read_b128 v[136:139], v150
	ds_read_b128 v[140:143], v150 offset:1024
	ds_read_b128 v[154:157], v150 offset:2048
	ds_read_b128 v[158:161], v150 offset:3072
	ds_read_b128 v[162:165], v151
	ds_read_b128 v[166:169], v151 offset:1024
	ds_read_b128 v[170:173], v151 offset:2048
	ds_read_b128 v[174:177], v151 offset:3072
	s_add_u32 s14, s8, 0x100
	s_addc_u32 s15, s9, 0
	s_cmp_eq_u32 s43, 60
	s_cselect_b32 s24, s13, s14
	s_cselect_b32 s25, s11, s15
	s_cselect_b32 s16, s36, s37
	s_cselect_b32 s17, s33, s42
	s_add_u32 s2, s24, 0x80
	s_addc_u32 s3, s25, 0
	s_add_u32 s8, s8, 0x100080
	s_addc_u32 s9, s9, 0
	s_add_i32 m0, s63, 0xc000
	ds_read_b128 v[178:181], v152
	ds_read_b128 v[182:185], v152 offset:1024
	ds_read_b128 v[186:189], v152 offset:2048
	ds_read_b128 v[190:193], v152 offset:3072
	ds_read_b128 v[194:197], v152 offset:4096
	ds_read_b128 v[198:201], v152 offset:5120
	ds_read_b128 v[202:205], v152 offset:6144
	ds_read_b128 v[206:209], v152 offset:7168
	s_nop 0
	global_load_lds_dwordx4 v1, s[8:9]
	s_add_i32 m0, s63, 0xe000
	s_nop 0
	global_load_lds_dwordx4 v145, s[8:9]
	s_waitcnt vmcnt(8)
	s_waitcnt lgkmcnt(0)
	s_setprio 1
	s_waitcnt lgkmcnt(0)
	s_barrier
	v_mfma_f32_16x16x32_bf16 v[126:129], v[136:139], v[178:181], v[126:129]
	v_mfma_f32_16x16x32_bf16 v[122:125], v[154:157], v[178:181], v[122:125]
	v_mfma_f32_16x16x32_bf16 v[110:113], v[136:139], v[186:189], v[110:113]
	v_mfma_f32_16x16x32_bf16 v[106:109], v[154:157], v[186:189], v[106:109]
	v_mfma_f32_16x16x32_bf16 v[94:97], v[136:139], v[194:197], v[94:97]
	v_mfma_f32_16x16x32_bf16 v[90:93], v[154:157], v[194:197], v[90:93]
	v_mfma_f32_16x16x32_bf16 v[78:81], v[136:139], v[202:205], v[78:81]
	v_mfma_f32_16x16x32_bf16 v[74:77], v[154:157], v[202:205], v[74:77]
	v_mfma_f32_16x16x32_bf16 v[118:121], v[162:165], v[178:181], v[118:121]
	v_mfma_f32_16x16x32_bf16 v[114:117], v[170:173], v[178:181], v[114:117]
	v_mfma_f32_16x16x32_bf16 v[102:105], v[162:165], v[186:189], v[102:105]
	v_mfma_f32_16x16x32_bf16 v[98:101], v[170:173], v[186:189], v[98:101]
	v_mfma_f32_16x16x32_bf16 v[86:89], v[162:165], v[194:197], v[86:89]
	v_mfma_f32_16x16x32_bf16 v[82:85], v[170:173], v[194:197], v[82:85]
	v_mfma_f32_16x16x32_bf16 v[70:73], v[162:165], v[202:205], v[70:73]
	v_mfma_f32_16x16x32_bf16 v[66:69], v[170:173], v[202:205], v[66:69]
	v_mfma_f32_16x16x32_bf16 v[126:129], v[140:143], v[182:185], v[126:129]
	v_mfma_f32_16x16x32_bf16 v[122:125], v[158:161], v[182:185], v[122:125]
	v_mfma_f32_16x16x32_bf16 v[110:113], v[140:143], v[190:193], v[110:113]
	v_mfma_f32_16x16x32_bf16 v[106:109], v[158:161], v[190:193], v[106:109]
	v_mfma_f32_16x16x32_bf16 v[94:97], v[140:143], v[198:201], v[94:97]
	v_mfma_f32_16x16x32_bf16 v[90:93], v[158:161], v[198:201], v[90:93]
	v_mfma_f32_16x16x32_bf16 v[78:81], v[140:143], v[206:209], v[78:81]
	v_mfma_f32_16x16x32_bf16 v[74:77], v[158:161], v[206:209], v[74:77]
	v_mfma_f32_16x16x32_bf16 v[118:121], v[166:169], v[182:185], v[118:121]
	v_mfma_f32_16x16x32_bf16 v[114:117], v[174:177], v[182:185], v[114:117]
	v_mfma_f32_16x16x32_bf16 v[102:105], v[166:169], v[190:193], v[102:105]
	v_mfma_f32_16x16x32_bf16 v[98:101], v[174:177], v[190:193], v[98:101]
	v_mfma_f32_16x16x32_bf16 v[86:89], v[166:169], v[198:201], v[86:89]
	v_mfma_f32_16x16x32_bf16 v[82:85], v[174:177], v[198:201], v[82:85]
	v_mfma_f32_16x16x32_bf16 v[70:73], v[166:169], v[206:209], v[70:73]
	v_mfma_f32_16x16x32_bf16 v[66:69], v[174:177], v[206:209], v[66:69]
	s_barrier
	s_setprio 0
	s_add_i32 s44, s95, s61
	s_mov_b64 s[8:9], s[16:17]
	s_mov_b32 m0, s44
	ds_read_b128 v[178:181], v152 offset:16384
	ds_read_b128 v[182:185], v152 offset:17408
	ds_read_b128 v[186:189], v152 offset:18432
	ds_read_b128 v[190:193], v152 offset:19456
	ds_read_b128 v[194:197], v152 offset:20480
	ds_read_b128 v[198:201], v152 offset:21504
	ds_read_b128 v[202:205], v152 offset:22528
	ds_read_b128 v[206:209], v152 offset:23552
	s_nop 0
	global_load_lds_dwordx4 v144, s[8:9]
	s_add_i32 m0, s44, 0x2000
	s_nop 0
	global_load_lds_dwordx4 v146, s[8:9]
	s_add_u32 s8, s16, 0x100000
	s_addc_u32 s9, s17, 0
	s_add_i32 s44, s96, s61
	s_mov_b32 m0, s44
	s_nop 0
	global_load_lds_dwordx4 v144, s[8:9]
	s_add_i32 m0, s44, 0x2000
	s_nop 0
	global_load_lds_dwordx4 v146, s[8:9]
	s_mov_b64 s[8:9], s[24:25]
	s_mov_b32 m0, s63
	s_nop 0
	global_load_lds_dwordx4 v1, s[8:9]
	s_mov_b32 m0, s65
	s_nop 0
	global_load_lds_dwordx4 v145, s[8:9]
	s_waitcnt vmcnt(8)
	s_waitcnt lgkmcnt(0)
	s_setprio 1
	s_waitcnt lgkmcnt(0)
	s_barrier
	v_mfma_f32_16x16x32_bf16 v[62:65], v[136:139], v[178:181], v[62:65]
	v_mfma_f32_16x16x32_bf16 v[58:61], v[154:157], v[178:181], v[58:61]
	v_mfma_f32_16x16x32_bf16 v[46:49], v[136:139], v[186:189], v[46:49]
	v_mfma_f32_16x16x32_bf16 v[42:45], v[154:157], v[186:189], v[42:45]
	v_mfma_f32_16x16x32_bf16 v[30:33], v[136:139], v[194:197], v[30:33]
	v_mfma_f32_16x16x32_bf16 v[26:29], v[154:157], v[194:197], v[26:29]
	v_mfma_f32_16x16x32_bf16 v[14:17], v[136:139], v[202:205], v[14:17]
	v_mfma_f32_16x16x32_bf16 v[10:13], v[154:157], v[202:205], v[10:13]
	v_mfma_f32_16x16x32_bf16 v[54:57], v[162:165], v[178:181], v[54:57]
	v_mfma_f32_16x16x32_bf16 v[50:53], v[170:173], v[178:181], v[50:53]
	v_mfma_f32_16x16x32_bf16 v[38:41], v[162:165], v[186:189], v[38:41]
	v_mfma_f32_16x16x32_bf16 v[34:37], v[170:173], v[186:189], v[34:37]
	v_mfma_f32_16x16x32_bf16 v[22:25], v[162:165], v[194:197], v[22:25]
	v_mfma_f32_16x16x32_bf16 v[18:21], v[170:173], v[194:197], v[18:21]
	v_mfma_f32_16x16x32_bf16 v[6:9], v[162:165], v[202:205], v[6:9]
	v_mfma_f32_16x16x32_bf16 v[2:5], v[170:173], v[202:205], v[2:5]
	v_mfma_f32_16x16x32_bf16 v[62:65], v[140:143], v[182:185], v[62:65]
	v_mfma_f32_16x16x32_bf16 v[58:61], v[158:161], v[182:185], v[58:61]
	v_mfma_f32_16x16x32_bf16 v[46:49], v[140:143], v[190:193], v[46:49]
	v_mfma_f32_16x16x32_bf16 v[42:45], v[158:161], v[190:193], v[42:45]
	v_mfma_f32_16x16x32_bf16 v[30:33], v[140:143], v[198:201], v[30:33]
	v_mfma_f32_16x16x32_bf16 v[26:29], v[158:161], v[198:201], v[26:29]
	v_mfma_f32_16x16x32_bf16 v[14:17], v[140:143], v[206:209], v[14:17]
	v_mfma_f32_16x16x32_bf16 v[10:13], v[158:161], v[206:209], v[10:13]
	v_mfma_f32_16x16x32_bf16 v[54:57], v[166:169], v[182:185], v[54:57]
	v_mfma_f32_16x16x32_bf16 v[50:53], v[174:177], v[182:185], v[50:53]
	v_mfma_f32_16x16x32_bf16 v[38:41], v[166:169], v[190:193], v[38:41]
	v_mfma_f32_16x16x32_bf16 v[34:37], v[174:177], v[190:193], v[34:37]
	v_mfma_f32_16x16x32_bf16 v[22:25], v[166:169], v[198:201], v[22:25]
	v_mfma_f32_16x16x32_bf16 v[18:21], v[174:177], v[198:201], v[18:21]
	v_mfma_f32_16x16x32_bf16 v[6:9], v[166:169], v[206:209], v[6:9]
	v_mfma_f32_16x16x32_bf16 v[2:5], v[174:177], v[206:209], v[2:5]
	s_barrier
; #define PG8_STAGE(bufoff, gbase, voff) do { const char* _gb = (const char*)(gbase); asm volatile("" : "+s"(_gb)); _Pragma("unroll") for (int _i = 0; _i < 2; ++_i) { asm volatile("" : "+v"((voff)[_i])); \
;         __builtin_amdgcn_global_load_lds((const unsigned*)(_gb + (voff)[_i]), (PG8_LAS unsigned*)(lds + (bufoff) + ldsw + _i * 8192), 16, 0, 0); } } while (0)
; template <class Epi, class Sched, bool ALIGN_EPI = false, bool SP2 = false>
; __device__ __forceinline__ void gemm_phase(PG8_LAS unsigned char* lds, const Gemm g, const Sched& S, const Epi& E) {
;     ...
;             PG8_LDB(B0, 1, 0); PG8_LDB(B1, 1, 1); PG8_SCHED; PG8_LDA(At, 1, 0); PG8_STAGE(PG8_SA(0, 1), a2 + hstep, voffA);
;             PG8_WAIT_V(8); PG8_WAIT_L(0); PG8_BAR; PG8_MMA2(0); PG8_BAR; PG8_SCHED;
;             PG8_LDA(At, 1, 1); PG8_STAGE(PG8_SB(1, 0), b3, voffB); PG8_STAGE(PG8_SB(1, 1), b3 + hstep, voffB); PG8_STAGE(PG8_SA(1, 0), a3, voffA);
;             PG8_WAIT_V(8); PG8_WAIT_L(0); PG8_BAR; PG8_MMA2(1); PG8_BAR; PG8_SCHED;
;             } else {
;             PG8_LDB(B0, 0, 0); PG8_SCHED; PG8_LDA(At, 0, 0); PG8_STAGE(PG8_SA(1, 1), a1 + hstep, voffA);
;             PG8_WAIT_L(8); PG8_BAR; PG8_WAIT_L(0); PG8_MMA(0, 0, At, B0); PG8_BAR; PG8_SCHED;
;             PG8_LDB(B1, 0, 1); PG8_STAGE(PG8_SB(0, 0), b2, voffB);
;             PG8_BAR; PG8_WAIT_L(0); PG8_MMA(0, 1, At, B1); PG8_BAR;
;             PG8_LDA(At, 0, 1); PG8_STAGE(PG8_SA(0, 0), a2, voffA);
;             PG8_BAR; PG8_WAIT_L(0); PG8_MMA(1, 0, At, B0); PG8_BAR; PG8_SCHED;
;             PG8_STAGE(PG8_SB(0, 1), b2 + hstep, voffB);
;             PG8_WAIT_V(6); PG8_BAR; PG8_MMA(1, 1, At, B1); PG8_BAR;
;             PG8_LDB(B0, 1, 0); PG8_SCHED; PG8_LDA(At, 1, 0); PG8_STAGE(PG8_SA(0, 1), a2 + hstep, voffA);
;             PG8_WAIT_L(8); PG8_BAR; PG8_WAIT_L(0); PG8_MMA(0, 0, At, B0); PG8_BAR; PG8_SCHED;
;             PG8_LDB(B1, 1, 1); PG8_STAGE(PG8_SB(1, 0), b3, voffB);
;             PG8_BAR; PG8_WAIT_L(0); PG8_MMA(0, 1, At, B1); PG8_BAR;
;             PG8_LDA(At, 1, 1); PG8_STAGE(PG8_SA(1, 0), a3, voffA);
;             PG8_BAR; PG8_WAIT_L(0); PG8_MMA(1, 0, At, B0); PG8_BAR; PG8_SCHED;
;             PG8_STAGE(PG8_SB(1, 1), b3 + hstep, voffB);
;             PG8_WAIT_V(6); PG8_BAR; PG8_MMA(1, 1, At, B1); PG8_BAR;
;             }
;         }
;         if constexpr (ALIGN_EPI) { if (wr == 0) PG8_BAR; }
	s_setprio 0
	s_add_i32 s44, 0, 0x18000
	v_add_u32_e32 v135, s44, v148
	s_add_i32 s45, 0, 0x1c000
	ds_read_b128 v[136:139], v135
	ds_read_b128 v[140:143], v135 offset:1024
	ds_read_b128 v[154:157], v135 offset:2048
	ds_read_b128 v[158:161], v135 offset:3072
	v_add_u32_e32 v135, s45, v148
	ds_read_b128 v[162:165], v135
	ds_read_b128 v[166:169], v135 offset:1024
	ds_read_b128 v[170:173], v135 offset:2048
	ds_read_b128 v[174:177], v135 offset:3072
	s_add_u32 s8, s24, 0x100000
	s_addc_u32 s9, s25, 0
	s_mov_b32 m0, s88
	ds_read_b128 v[178:181], v152 offset:32768
	ds_read_b128 v[182:185], v152 offset:33792
	ds_read_b128 v[186:189], v152 offset:34816
	ds_read_b128 v[190:193], v152 offset:35840
	ds_read_b128 v[194:197], v152 offset:36864
	ds_read_b128 v[198:201], v152 offset:37888
	ds_read_b128 v[202:205], v152 offset:38912
	ds_read_b128 v[206:209], v152 offset:39936
	s_nop 0
	global_load_lds_dwordx4 v1, s[8:9]
	s_mov_b32 m0, s89
	s_nop 0
	global_load_lds_dwordx4 v145, s[8:9]
	s_waitcnt vmcnt(8)
	s_waitcnt lgkmcnt(0)
	s_setprio 1
	s_waitcnt lgkmcnt(0)
	s_barrier
	v_mfma_f32_16x16x32_bf16 v[126:129], v[136:139], v[178:181], v[126:129]
	v_mfma_f32_16x16x32_bf16 v[122:125], v[154:157], v[178:181], v[122:125]
	v_mfma_f32_16x16x32_bf16 v[110:113], v[136:139], v[186:189], v[110:113]
	v_mfma_f32_16x16x32_bf16 v[106:109], v[154:157], v[186:189], v[106:109]
	v_mfma_f32_16x16x32_bf16 v[94:97], v[136:139], v[194:197], v[94:97]
	v_mfma_f32_16x16x32_bf16 v[90:93], v[154:157], v[194:197], v[90:93]
	v_mfma_f32_16x16x32_bf16 v[78:81], v[136:139], v[202:205], v[78:81]
	v_mfma_f32_16x16x32_bf16 v[74:77], v[154:157], v[202:205], v[74:77]
	v_mfma_f32_16x16x32_bf16 v[118:121], v[162:165], v[178:181], v[118:121]
	v_mfma_f32_16x16x32_bf16 v[114:117], v[170:173], v[178:181], v[114:117]
	v_mfma_f32_16x16x32_bf16 v[102:105], v[162:165], v[186:189], v[102:105]
	v_mfma_f32_16x16x32_bf16 v[98:101], v[170:173], v[186:189], v[98:101]
	v_mfma_f32_16x16x32_bf16 v[86:89], v[162:165], v[194:197], v[86:89]
	v_mfma_f32_16x16x32_bf16 v[82:85], v[170:173], v[194:197], v[82:85]
	v_mfma_f32_16x16x32_bf16 v[70:73], v[162:165], v[202:205], v[70:73]
	v_mfma_f32_16x16x32_bf16 v[66:69], v[170:173], v[202:205], v[66:69]
	v_mfma_f32_16x16x32_bf16 v[126:129], v[140:143], v[182:185], v[126:129]
	v_mfma_f32_16x16x32_bf16 v[122:125], v[158:161], v[182:185], v[122:125]
	v_mfma_f32_16x16x32_bf16 v[110:113], v[140:143], v[190:193], v[110:113]
	v_mfma_f32_16x16x32_bf16 v[106:109], v[158:161], v[190:193], v[106:109]
	v_mfma_f32_16x16x32_bf16 v[94:97], v[140:143], v[198:201], v[94:97]
	v_mfma_f32_16x16x32_bf16 v[90:93], v[158:161], v[198:201], v[90:93]
	v_mfma_f32_16x16x32_bf16 v[78:81], v[140:143], v[206:209], v[78:81]
	v_mfma_f32_16x16x32_bf16 v[74:77], v[158:161], v[206:209], v[74:77]
	v_mfma_f32_16x16x32_bf16 v[118:121], v[166:169], v[182:185], v[118:121]
	v_mfma_f32_16x16x32_bf16 v[114:117], v[174:177], v[182:185], v[114:117]
	v_mfma_f32_16x16x32_bf16 v[102:105], v[166:169], v[190:193], v[102:105]
	v_mfma_f32_16x16x32_bf16 v[98:101], v[174:177], v[190:193], v[98:101]
	v_mfma_f32_16x16x32_bf16 v[86:89], v[166:169], v[198:201], v[86:89]
	v_mfma_f32_16x16x32_bf16 v[82:85], v[174:177], v[198:201], v[82:85]
	v_mfma_f32_16x16x32_bf16 v[70:73], v[166:169], v[206:209], v[70:73]
	v_mfma_f32_16x16x32_bf16 v[66:69], v[174:177], v[206:209], v[66:69]
	s_barrier
	s_setprio 0
	s_add_u32 s8, s16, 0x80
	s_addc_u32 s9, s17, 0
	s_add_i32 s24, s44, s61
	s_mov_b32 m0, s24
	ds_read_b128 v[178:181], v152 offset:49152
	ds_read_b128 v[182:185], v152 offset:50176
	ds_read_b128 v[186:189], v152 offset:51200
	ds_read_b128 v[190:193], v152 offset:52224
	ds_read_b128 v[194:197], v152 offset:53248
	ds_read_b128 v[198:201], v152 offset:54272
	ds_read_b128 v[202:205], v152 offset:55296
	ds_read_b128 v[206:209], v152 offset:56320
	s_nop 0
	global_load_lds_dwordx4 v144, s[8:9]
	s_add_i32 m0, s24, 0x2000
	s_nop 0
	global_load_lds_dwordx4 v146, s[8:9]
	s_add_u32 s8, s16, 0x100080
	s_addc_u32 s9, s17, 0
	s_add_i32 s16, s45, s61
	s_mov_b32 m0, s16
	s_nop 0
	global_load_lds_dwordx4 v144, s[8:9]
	s_add_i32 m0, s16, 0x2000
	s_nop 0
	global_load_lds_dwordx4 v146, s[8:9]
	s_mov_b32 m0, s91
	s_nop 0
	global_load_lds_dwordx4 v1, s[2:3]
	s_mov_b32 m0, s92
	s_nop 0
	global_load_lds_dwordx4 v145, s[2:3]
	s_waitcnt vmcnt(8)
	s_waitcnt lgkmcnt(0)
	s_setprio 1
	s_waitcnt lgkmcnt(0)
	s_barrier
	v_mfma_f32_16x16x32_bf16 v[62:65], v[136:139], v[178:181], v[62:65]
	v_mfma_f32_16x16x32_bf16 v[58:61], v[154:157], v[178:181], v[58:61]
	v_mfma_f32_16x16x32_bf16 v[46:49], v[136:139], v[186:189], v[46:49]
	v_mfma_f32_16x16x32_bf16 v[42:45], v[154:157], v[186:189], v[42:45]
	v_mfma_f32_16x16x32_bf16 v[30:33], v[136:139], v[194:197], v[30:33]
	v_mfma_f32_16x16x32_bf16 v[26:29], v[154:157], v[194:197], v[26:29]
	v_mfma_f32_16x16x32_bf16 v[14:17], v[136:139], v[202:205], v[14:17]
	v_mfma_f32_16x16x32_bf16 v[10:13], v[154:157], v[202:205], v[10:13]
	v_mfma_f32_16x16x32_bf16 v[54:57], v[162:165], v[178:181], v[54:57]
	v_mfma_f32_16x16x32_bf16 v[50:53], v[170:173], v[178:181], v[50:53]
	v_mfma_f32_16x16x32_bf16 v[38:41], v[162:165], v[186:189], v[38:41]
	v_mfma_f32_16x16x32_bf16 v[34:37], v[170:173], v[186:189], v[34:37]
	v_mfma_f32_16x16x32_bf16 v[22:25], v[162:165], v[194:197], v[22:25]
	v_mfma_f32_16x16x32_bf16 v[18:21], v[170:173], v[194:197], v[18:21]
	v_mfma_f32_16x16x32_bf16 v[6:9], v[162:165], v[202:205], v[6:9]
	v_mfma_f32_16x16x32_bf16 v[2:5], v[170:173], v[202:205], v[2:5]
	v_mfma_f32_16x16x32_bf16 v[62:65], v[140:143], v[182:185], v[62:65]
	v_mfma_f32_16x16x32_bf16 v[58:61], v[158:161], v[182:185], v[58:61]
	v_mfma_f32_16x16x32_bf16 v[46:49], v[140:143], v[190:193], v[46:49]
	v_mfma_f32_16x16x32_bf16 v[42:45], v[158:161], v[190:193], v[42:45]
	v_mfma_f32_16x16x32_bf16 v[30:33], v[140:143], v[198:201], v[30:33]
	v_mfma_f32_16x16x32_bf16 v[26:29], v[158:161], v[198:201], v[26:29]
	v_mfma_f32_16x16x32_bf16 v[14:17], v[140:143], v[206:209], v[14:17]
	v_mfma_f32_16x16x32_bf16 v[10:13], v[158:161], v[206:209], v[10:13]
	v_mfma_f32_16x16x32_bf16 v[54:57], v[166:169], v[182:185], v[54:57]
	v_mfma_f32_16x16x32_bf16 v[50:53], v[174:177], v[182:185], v[50:53]
	v_mfma_f32_16x16x32_bf16 v[38:41], v[166:169], v[190:193], v[38:41]
	v_mfma_f32_16x16x32_bf16 v[34:37], v[174:177], v[190:193], v[34:37]
	v_mfma_f32_16x16x32_bf16 v[22:25], v[166:169], v[198:201], v[22:25]
	v_mfma_f32_16x16x32_bf16 v[18:21], v[174:177], v[198:201], v[18:21]
	v_mfma_f32_16x16x32_bf16 v[6:9], v[166:169], v[206:209], v[6:9]
	v_mfma_f32_16x16x32_bf16 v[2:5], v[174:177], v[206:209], v[2:5]
	s_barrier
	s_setprio 0
	s_add_i32 s43, s43, 2
	s_add_u32 s37, s37, 0x100
	s_addc_u32 s42, s42, 0
	s_cmp_gt_u32 s43, 61
	s_mov_b64 s[8:9], s[14:15]
	s_cbranch_scc0 .LBB0_313
	s_and_b64 vcc, exec, s[58:59]
	s_cbranch_vccz .LBB0_333
	s_barrier
	s_cmp_lt_i32 s12, 24
	s_cbranch_scc0 .LBB0_334

.LBB0_746:
	ds_read_b128 v[118:121], v172
	ds_read_b128 v[134:137], v172 offset:1024
	ds_read_b128 v[138:141], v172 offset:2048
	ds_read_b128 v[142:145], v172 offset:3072
	ds_read_b128 v[146:149], v173
	ds_read_b128 v[150:153], v173 offset:1024
	ds_read_b128 v[154:157], v173 offset:2048
	ds_read_b128 v[176:179], v173 offset:3072
	s_add_u32 s16, s0, 0x100
	s_addc_u32 s17, s1, 0
	s_cmp_eq_u32 s33, 28
	s_cselect_b32 s26, s30, s16
	s_cselect_b32 s27, s31, s17
	s_cselect_b32 s24, s78, s5
	s_cselect_b32 s25, s79, s21
	s_add_u32 s2, s26, 0x80
	s_addc_u32 s3, s27, 0
	s_add_u32 s0, s0, 0x100080
	s_addc_u32 s1, s1, 0
	s_add_i32 s76, s46, 0xc000
	s_mov_b32 m0, s76
	s_add_i32 s77, s46, 0xe000
	ds_read_b128 v[180:183], v174
	ds_read_b128 v[184:187], v174 offset:1024
	ds_read_b128 v[188:191], v174 offset:2048
	ds_read_b128 v[192:195], v174 offset:3072
	ds_read_b128 v[196:199], v174 offset:4096
	ds_read_b128 v[200:203], v174 offset:5120
	ds_read_b128 v[204:207], v174 offset:6144
	ds_read_b128 v[208:211], v174 offset:7168
	s_nop 0
	global_load_lds_dwordx4 v1, s[0:1]
	s_mov_b32 m0, s77
	s_nop 0
	global_load_lds_dwordx4 v165, s[0:1]
	s_waitcnt vmcnt(8)
	s_waitcnt lgkmcnt(0)
	s_setprio 1
	s_waitcnt lgkmcnt(0)
	s_barrier
	v_mfma_f32_16x16x32_bf16 v[34:37], v[118:121], v[180:183], v[34:37]
	v_mfma_f32_16x16x32_bf16 v[30:33], v[138:141], v[180:183], v[30:33]
	v_mfma_f32_16x16x32_bf16 v[46:49], v[118:121], v[188:191], v[46:49]
	v_mfma_f32_16x16x32_bf16 v[62:65], v[138:141], v[188:191], v[62:65]
	v_mfma_f32_16x16x32_bf16 v[78:81], v[118:121], v[196:199], v[78:81]
	v_mfma_f32_16x16x32_bf16 v[90:93], v[138:141], v[196:199], v[90:93]
	v_mfma_f32_16x16x32_bf16 v[130:133], v[118:121], v[204:207], v[130:133]
	v_mfma_f32_16x16x32_bf16 v[114:117], v[138:141], v[204:207], v[114:117]
	v_mfma_f32_16x16x32_bf16 v[26:29], v[146:149], v[180:183], v[26:29]
	v_mfma_f32_16x16x32_bf16 v[50:53], v[154:157], v[180:183], v[50:53]
	v_mfma_f32_16x16x32_bf16 v[58:61], v[146:149], v[188:191], v[58:61]
	v_mfma_f32_16x16x32_bf16 v[82:85], v[154:157], v[188:191], v[82:85]
	v_mfma_f32_16x16x32_bf16 v[110:113], v[146:149], v[196:199], v[110:113]
	v_mfma_f32_16x16x32_bf16 v[106:109], v[154:157], v[196:199], v[106:109]
	v_mfma_f32_16x16x32_bf16 v[122:125], v[146:149], v[204:207], v[122:125]
	v_mfma_f32_16x16x32_bf16 v[126:129], v[154:157], v[204:207], v[126:129]
	v_mfma_f32_16x16x32_bf16 v[34:37], v[134:137], v[184:187], v[34:37]
	v_mfma_f32_16x16x32_bf16 v[30:33], v[142:145], v[184:187], v[30:33]
	v_mfma_f32_16x16x32_bf16 v[46:49], v[134:137], v[192:195], v[46:49]
	v_mfma_f32_16x16x32_bf16 v[62:65], v[142:145], v[192:195], v[62:65]
	v_mfma_f32_16x16x32_bf16 v[78:81], v[134:137], v[200:203], v[78:81]
	v_mfma_f32_16x16x32_bf16 v[90:93], v[142:145], v[200:203], v[90:93]
	v_mfma_f32_16x16x32_bf16 v[130:133], v[134:137], v[208:211], v[130:133]
	v_mfma_f32_16x16x32_bf16 v[114:117], v[142:145], v[208:211], v[114:117]
	v_mfma_f32_16x16x32_bf16 v[26:29], v[150:153], v[184:187], v[26:29]
	v_mfma_f32_16x16x32_bf16 v[50:53], v[176:179], v[184:187], v[50:53]
	v_mfma_f32_16x16x32_bf16 v[58:61], v[150:153], v[192:195], v[58:61]
	v_mfma_f32_16x16x32_bf16 v[82:85], v[176:179], v[192:195], v[82:85]
	v_mfma_f32_16x16x32_bf16 v[110:113], v[150:153], v[200:203], v[110:113]
	v_mfma_f32_16x16x32_bf16 v[106:109], v[176:179], v[200:203], v[106:109]
	v_mfma_f32_16x16x32_bf16 v[122:125], v[150:153], v[208:211], v[122:125]
	v_mfma_f32_16x16x32_bf16 v[126:129], v[176:179], v[208:211], v[126:129]
	s_barrier
	s_setprio 0
	s_add_i32 s80, s72, s45
	s_mov_b64 s[0:1], s[24:25]
	s_mov_b32 m0, s80
	s_add_i32 s81, s80, 0x2000
	ds_read_b128 v[180:183], v174 offset:16384
	ds_read_b128 v[184:187], v174 offset:17408
	ds_read_b128 v[188:191], v174 offset:18432
	ds_read_b128 v[192:195], v174 offset:19456
	ds_read_b128 v[196:199], v174 offset:20480
	ds_read_b128 v[200:203], v174 offset:21504
	ds_read_b128 v[204:207], v174 offset:22528
	ds_read_b128 v[208:211], v174 offset:23552
	s_nop 0
	global_load_lds_dwordx4 v164, s[0:1]
	s_mov_b32 m0, s81
	s_nop 0
	global_load_lds_dwordx4 v166, s[0:1]
	s_add_u32 s0, s24, 0x100000
	s_addc_u32 s1, s25, 0
	s_add_i32 s82, s73, s45
	s_mov_b32 m0, s82
	s_add_i32 s83, s82, 0x2000
	s_nop 0
	global_load_lds_dwordx4 v164, s[0:1]
	s_mov_b32 m0, s83
	s_nop 0
	global_load_lds_dwordx4 v166, s[0:1]
	s_mov_b64 s[0:1], s[26:27]
	s_mov_b32 m0, s46
	s_nop 0
	global_load_lds_dwordx4 v1, s[0:1]
	s_mov_b32 m0, s47
	s_nop 0
	global_load_lds_dwordx4 v165, s[0:1]
	s_waitcnt vmcnt(8)
	s_waitcnt lgkmcnt(0)
	s_setprio 1
	s_waitcnt lgkmcnt(0)
	s_barrier
	v_mfma_f32_16x16x32_bf16 v[102:105], v[118:121], v[180:183], v[102:105]
	v_mfma_f32_16x16x32_bf16 v[98:101], v[138:141], v[180:183], v[98:101]
	v_mfma_f32_16x16x32_bf16 v[74:77], v[118:121], v[188:191], v[74:77]
	v_mfma_f32_16x16x32_bf16 v[70:73], v[138:141], v[188:191], v[70:73]
	v_mfma_f32_16x16x32_bf16 v[42:45], v[118:121], v[196:199], v[42:45]
	v_mfma_f32_16x16x32_bf16 v[38:41], v[138:141], v[196:199], v[38:41]
	v_mfma_f32_16x16x32_bf16 v[18:21], v[118:121], v[204:207], v[18:21]
	v_mfma_f32_16x16x32_bf16 v[10:13], v[138:141], v[204:207], v[10:13]
	v_mfma_f32_16x16x32_bf16 v[94:97], v[146:149], v[180:183], v[94:97]
	v_mfma_f32_16x16x32_bf16 v[86:89], v[154:157], v[180:183], v[86:89]
	v_mfma_f32_16x16x32_bf16 v[66:69], v[146:149], v[188:191], v[66:69]
	v_mfma_f32_16x16x32_bf16 v[54:57], v[154:157], v[188:191], v[54:57]
	v_mfma_f32_16x16x32_bf16 v[22:25], v[146:149], v[196:199], v[22:25]
	v_mfma_f32_16x16x32_bf16 v[14:17], v[154:157], v[196:199], v[14:17]
	v_mfma_f32_16x16x32_bf16 v[6:9], v[146:149], v[204:207], v[6:9]
	v_mfma_f32_16x16x32_bf16 v[2:5], v[154:157], v[204:207], v[2:5]
	v_mfma_f32_16x16x32_bf16 v[102:105], v[134:137], v[184:187], v[102:105]
	v_mfma_f32_16x16x32_bf16 v[98:101], v[142:145], v[184:187], v[98:101]
	v_mfma_f32_16x16x32_bf16 v[74:77], v[134:137], v[192:195], v[74:77]
	v_mfma_f32_16x16x32_bf16 v[70:73], v[142:145], v[192:195], v[70:73]
	v_mfma_f32_16x16x32_bf16 v[42:45], v[134:137], v[200:203], v[42:45]
	v_mfma_f32_16x16x32_bf16 v[38:41], v[142:145], v[200:203], v[38:41]
	v_mfma_f32_16x16x32_bf16 v[18:21], v[134:137], v[208:211], v[18:21]
	v_mfma_f32_16x16x32_bf16 v[10:13], v[142:145], v[208:211], v[10:13]
	v_mfma_f32_16x16x32_bf16 v[94:97], v[150:153], v[184:187], v[94:97]
	v_mfma_f32_16x16x32_bf16 v[86:89], v[176:179], v[184:187], v[86:89]
	v_mfma_f32_16x16x32_bf16 v[66:69], v[150:153], v[192:195], v[66:69]
	v_mfma_f32_16x16x32_bf16 v[54:57], v[176:179], v[192:195], v[54:57]
	v_mfma_f32_16x16x32_bf16 v[22:25], v[150:153], v[200:203], v[22:25]
	v_mfma_f32_16x16x32_bf16 v[14:17], v[176:179], v[200:203], v[14:17]
	v_mfma_f32_16x16x32_bf16 v[6:9], v[150:153], v[208:211], v[6:9]
	v_mfma_f32_16x16x32_bf16 v[2:5], v[176:179], v[208:211], v[2:5]
	s_barrier
	s_setprio 0
	s_add_i32 s84, 0, 0x18000
	s_add_i32 s86, 0, 0x1c000
	v_add_u32_e32 v175, s84, v170
	v_add_u32_e32 v176, s86, v170
	ds_read_b128 v[118:121], v175
	ds_read_b128 v[134:137], v175 offset:1024
	ds_read_b128 v[138:141], v175 offset:2048
	ds_read_b128 v[142:145], v175 offset:3072
	ds_read_b128 v[146:149], v176
	ds_read_b128 v[150:153], v176 offset:1024
	ds_read_b128 v[154:157], v176 offset:2048
	ds_read_b128 v[178:181], v176 offset:3072
	s_add_u32 s0, s26, 0x100000
	s_addc_u32 s1, s27, 0
	s_mov_b32 m0, s48
	ds_read_b128 v[182:185], v174 offset:32768
	ds_read_b128 v[186:189], v174 offset:33792
	ds_read_b128 v[190:193], v174 offset:34816
	ds_read_b128 v[194:197], v174 offset:35840
	ds_read_b128 v[198:201], v174 offset:36864
	ds_read_b128 v[202:205], v174 offset:37888
	ds_read_b128 v[206:209], v174 offset:38912
	ds_read_b128 v[210:213], v174 offset:39936
	s_nop 0
	global_load_lds_dwordx4 v1, s[0:1]
	s_mov_b32 m0, s49
	s_nop 0
	global_load_lds_dwordx4 v165, s[0:1]
	s_waitcnt vmcnt(8)
	s_waitcnt lgkmcnt(0)
	s_setprio 1
	s_waitcnt lgkmcnt(0)
	s_barrier
	v_mfma_f32_16x16x32_bf16 v[34:37], v[118:121], v[182:185], v[34:37]
	v_mfma_f32_16x16x32_bf16 v[30:33], v[138:141], v[182:185], v[30:33]
	v_mfma_f32_16x16x32_bf16 v[46:49], v[118:121], v[190:193], v[46:49]
	v_mfma_f32_16x16x32_bf16 v[62:65], v[138:141], v[190:193], v[62:65]
	v_mfma_f32_16x16x32_bf16 v[78:81], v[118:121], v[198:201], v[78:81]
	v_mfma_f32_16x16x32_bf16 v[90:93], v[138:141], v[198:201], v[90:93]
	v_mfma_f32_16x16x32_bf16 v[130:133], v[118:121], v[206:209], v[130:133]
	v_mfma_f32_16x16x32_bf16 v[114:117], v[138:141], v[206:209], v[114:117]
	v_mfma_f32_16x16x32_bf16 v[26:29], v[146:149], v[182:185], v[26:29]
	v_mfma_f32_16x16x32_bf16 v[50:53], v[154:157], v[182:185], v[50:53]
	v_mfma_f32_16x16x32_bf16 v[58:61], v[146:149], v[190:193], v[58:61]
	v_mfma_f32_16x16x32_bf16 v[82:85], v[154:157], v[190:193], v[82:85]
	v_mfma_f32_16x16x32_bf16 v[110:113], v[146:149], v[198:201], v[110:113]
	v_mfma_f32_16x16x32_bf16 v[106:109], v[154:157], v[198:201], v[106:109]
	v_mfma_f32_16x16x32_bf16 v[122:125], v[146:149], v[206:209], v[122:125]
	v_mfma_f32_16x16x32_bf16 v[126:129], v[154:157], v[206:209], v[126:129]
	v_mfma_f32_16x16x32_bf16 v[34:37], v[134:137], v[186:189], v[34:37]
	v_mfma_f32_16x16x32_bf16 v[30:33], v[142:145], v[186:189], v[30:33]
	v_mfma_f32_16x16x32_bf16 v[46:49], v[134:137], v[194:197], v[46:49]
	v_mfma_f32_16x16x32_bf16 v[62:65], v[142:145], v[194:197], v[62:65]
	v_mfma_f32_16x16x32_bf16 v[78:81], v[134:137], v[202:205], v[78:81]
	v_mfma_f32_16x16x32_bf16 v[90:93], v[142:145], v[202:205], v[90:93]
	v_mfma_f32_16x16x32_bf16 v[130:133], v[134:137], v[210:213], v[130:133]
	v_mfma_f32_16x16x32_bf16 v[114:117], v[142:145], v[210:213], v[114:117]
	v_mfma_f32_16x16x32_bf16 v[26:29], v[150:153], v[186:189], v[26:29]
	v_mfma_f32_16x16x32_bf16 v[50:53], v[178:181], v[186:189], v[50:53]
	v_mfma_f32_16x16x32_bf16 v[58:61], v[150:153], v[194:197], v[58:61]
	v_mfma_f32_16x16x32_bf16 v[82:85], v[178:181], v[194:197], v[82:85]
	v_mfma_f32_16x16x32_bf16 v[110:113], v[150:153], v[202:205], v[110:113]
	v_mfma_f32_16x16x32_bf16 v[106:109], v[178:181], v[202:205], v[106:109]
	v_mfma_f32_16x16x32_bf16 v[122:125], v[150:153], v[210:213], v[122:125]
	v_mfma_f32_16x16x32_bf16 v[126:129], v[178:181], v[210:213], v[126:129]
	s_barrier
;     __device__ __forceinline__ void mid(f32x4 (&acc)[2][2][4][2], const Unit& u, int wr, int wc, int fr, int fq) const {
;     ...
;         const int row0 = u.pm * BM + wr * 64 + fr, col0 = u.pn * BM + wc * 32 + 8 * fq;
; #pragma unroll
;         for (int ai = 0; ai < 2; ++ai)
; #pragma unroll
;             for (int m = 0; m < 4; ++m) { const size_t off = (size_t)(row0 + ai * HALF + m * 16) * 4096 + col0;
; #pragma unroll
;                 for (int bj = 0; bj < 2; ++bj) { const u32x4 ga = *(const u32x4*)(SGA + off + bj * HALF), gb = *(const u32x4*)(SGB + off + bj * HALF);
; template <class Epi, class Sched>
; __device__ __forceinline__ void gemm_phase_dual(PG8_LAS unsigned char* lds, const Gemm g  , const bf16_t* A0, const bf16_t* Bt0, int K0, const Sched& S, const Epi& E) {
;     ...
;     const int nt0 = K0 / BK, nt1 = K / BK;
;     for (;;) {
;         const char* mA = (const char*)g.A + (size_t)cur.pm * tstep; const char* mB = (const char*)g.Bt + (size_t)cur.pn * tstep;
;         PG8_KLOOP(nt0, cA, cB, mA, mB)
;         E.mid(acc, cur, wr, wc, fr, fq);
	s_setprio 0
	s_add_u32 s0, s24, 0x80
	s_addc_u32 s1, s25, 0
	s_add_i32 s84, s84, s45
	s_mov_b32 m0, s84
	s_add_i32 s85, s84, 0x2000
	ds_read_b128 v[182:185], v174 offset:49152
	ds_read_b128 v[186:189], v174 offset:50176
	ds_read_b128 v[190:193], v174 offset:51200
	ds_read_b128 v[194:197], v174 offset:52224
	ds_read_b128 v[198:201], v174 offset:53248
	ds_read_b128 v[202:205], v174 offset:54272
	ds_read_b128 v[206:209], v174 offset:55296
	ds_read_b128 v[210:213], v174 offset:56320
	s_nop 0
	global_load_lds_dwordx4 v164, s[0:1]
	s_mov_b32 m0, s85
	s_nop 0
	global_load_lds_dwordx4 v166, s[0:1]
	s_add_u32 s0, s24, 0x100080
	s_addc_u32 s1, s25, 0
	s_add_i32 s86, s86, s45
	s_mov_b32 m0, s86
	s_add_i32 s87, s86, 0x2000
	s_nop 0
	global_load_lds_dwordx4 v164, s[0:1]
	s_mov_b32 m0, s87
	s_nop 0
	global_load_lds_dwordx4 v166, s[0:1]
	s_mov_b32 m0, s57
	s_nop 0
	global_load_lds_dwordx4 v1, s[2:3]
	s_mov_b32 m0, s62
	s_nop 0
	global_load_lds_dwordx4 v165, s[2:3]
	s_waitcnt vmcnt(8)
	s_waitcnt lgkmcnt(0)
	s_setprio 1
	s_waitcnt lgkmcnt(0)
	s_barrier
	v_mfma_f32_16x16x32_bf16 v[102:105], v[118:121], v[182:185], v[102:105]
	v_mfma_f32_16x16x32_bf16 v[98:101], v[138:141], v[182:185], v[98:101]
	v_mfma_f32_16x16x32_bf16 v[74:77], v[118:121], v[190:193], v[74:77]
	v_mfma_f32_16x16x32_bf16 v[70:73], v[138:141], v[190:193], v[70:73]
	v_mfma_f32_16x16x32_bf16 v[42:45], v[118:121], v[198:201], v[42:45]
	v_mfma_f32_16x16x32_bf16 v[38:41], v[138:141], v[198:201], v[38:41]
	v_mfma_f32_16x16x32_bf16 v[18:21], v[118:121], v[206:209], v[18:21]
	v_mfma_f32_16x16x32_bf16 v[10:13], v[138:141], v[206:209], v[10:13]
	v_mfma_f32_16x16x32_bf16 v[94:97], v[146:149], v[182:185], v[94:97]
	v_mfma_f32_16x16x32_bf16 v[86:89], v[154:157], v[182:185], v[86:89]
	v_mfma_f32_16x16x32_bf16 v[66:69], v[146:149], v[190:193], v[66:69]
	v_mfma_f32_16x16x32_bf16 v[54:57], v[154:157], v[190:193], v[54:57]
	v_mfma_f32_16x16x32_bf16 v[22:25], v[146:149], v[198:201], v[22:25]
	v_mfma_f32_16x16x32_bf16 v[14:17], v[154:157], v[198:201], v[14:17]
	v_mfma_f32_16x16x32_bf16 v[6:9], v[146:149], v[206:209], v[6:9]
	v_mfma_f32_16x16x32_bf16 v[2:5], v[154:157], v[206:209], v[2:5]
	v_mfma_f32_16x16x32_bf16 v[102:105], v[134:137], v[186:189], v[102:105]
	v_mfma_f32_16x16x32_bf16 v[98:101], v[142:145], v[186:189], v[98:101]
	v_mfma_f32_16x16x32_bf16 v[74:77], v[134:137], v[194:197], v[74:77]
	v_mfma_f32_16x16x32_bf16 v[70:73], v[142:145], v[194:197], v[70:73]
	v_mfma_f32_16x16x32_bf16 v[42:45], v[134:137], v[202:205], v[42:45]
	v_mfma_f32_16x16x32_bf16 v[38:41], v[142:145], v[202:205], v[38:41]
	v_mfma_f32_16x16x32_bf16 v[18:21], v[134:137], v[210:213], v[18:21]
	v_mfma_f32_16x16x32_bf16 v[10:13], v[142:145], v[210:213], v[10:13]
	v_mfma_f32_16x16x32_bf16 v[94:97], v[150:153], v[186:189], v[94:97]
	v_mfma_f32_16x16x32_bf16 v[86:89], v[178:181], v[186:189], v[86:89]
	v_mfma_f32_16x16x32_bf16 v[66:69], v[150:153], v[194:197], v[66:69]
	v_mfma_f32_16x16x32_bf16 v[54:57], v[178:181], v[194:197], v[54:57]
	v_mfma_f32_16x16x32_bf16 v[22:25], v[150:153], v[202:205], v[22:25]
	v_mfma_f32_16x16x32_bf16 v[14:17], v[178:181], v[202:205], v[14:17]
	v_mfma_f32_16x16x32_bf16 v[6:9], v[150:153], v[210:213], v[6:9]
	v_mfma_f32_16x16x32_bf16 v[2:5], v[178:181], v[210:213], v[2:5]
	s_barrier
	s_setprio 0
	s_add_i32 s33, s33, 2
	s_add_u32 s5, s5, 0x100
	s_addc_u32 s21, s21, 0
	s_cmp_gt_u32 s33, 29
	s_mov_b64 s[0:1], s[16:17]
	s_cbranch_scc0 .LBB0_746
	v_mov_b32_e32 v119, v167
	v_mov_b32_e32 v118, v168
	s_lshl_b32 s89, s20, 8
	s_lshl_b32 s88, s4, 8
	s_or_b32 s0, s89, s56
	v_lshl_add_u32 v118, v118, 3, s0
	s_add_i32 s0, s88, s55
	v_add_u32_e32 v120, s0, v119
	v_ashrrev_i32_e32 v121, 31, v120
	v_ashrrev_i32_e32 v119, 31, v118
	v_lshlrev_b64 v[120:121], 12, v[120:121]
	v_lshl_add_u64 v[118:119], v[120:121], 0, v[118:119]
	v_lshlrev_b64 v[162:163], 1, v[118:119]
	v_lshl_add_u64 v[138:139], s[12:13], 0, v[162:163]
	global_load_dwordx4 v[134:137], v[138:139], off
	v_lshl_add_u64 v[140:141], s[10:11], 0, v[162:163]
	global_load_dwordx4 v[118:121], v[140:141], off
	global_load_dwordx4 v[150:153], v[138:139], off offset:256
	global_load_dwordx4 v[146:149], v[140:141], off offset:256
	s_mov_b64 s[0:1], 0x20000
	v_lshl_add_u64 v[138:139], v[162:163], 0, s[0:1]
	v_lshl_add_u64 v[154:155], s[10:11], 0, v[138:139]
	v_lshl_add_u64 v[156:157], s[12:13], 0, v[138:139]
	global_load_dwordx4 v[138:141], v[154:155], off
	global_load_dwordx4 v[142:145], v[156:157], off
	s_mov_b64 s[0:1], 0x40000
	s_add_i32 s50, s50, 1
	v_readlane_b32 s2, v238, 45
	s_waitcnt vmcnt(0)
; __device__ __forceinline__ float bf_lo(unsigned w) { return __uint_as_float(w << 16); }
; __device__ __forceinline__ float bf_hi(unsigned w) { return __uint_as_float(w & 0xffff0000u); }
;     __device__ __forceinline__ void mid(f32x4 (&acc)[2][2][4][2], const Unit& u, int wr, int wc, int fr, int fq) const {
;     ...
;             for (int m = 0; m < 4; ++m) { const size_t off = (size_t)(row0 + ai * HALF + m * 16) * 4096 + col0;
; #pragma unroll
;                 for (int bj = 0; bj < 2; ++bj) { const u32x4 ga = *(const u32x4*)(SGA + off + bj * HALF), gb = *(const u32x4*)(SGB + off + bj * HALF);
;                     const unsigned wa[4] = {ga.x, ga.y, ga.z, ga.w}, wb[4] = {gb.x, gb.y, gb.z, gb.w};
; #pragma unroll
;                     for (int p = 0; p < 4; ++p) { const float rl = bf_lo(wa[p]) * __builtin_amdgcn_rcpf(fmaxf(bf_lo(wb[p]), 1e-20f)), rh = bf_hi(wa[p]) * __builtin_amdgcn_rcpf(fmaxf(bf_hi(wb[p]), 1e-20f));
;                         acc[ai][bj][m][p >> 1][(p & 1) * 2] *= rl; acc[ai][bj][m][p >> 1][(p & 1) * 2 + 1] *= rh; } }
	v_lshlrev_b32_e32 v178, 16, v118
	v_and_b32_e32 v180, 0xffff0000, v134
	v_lshlrev_b32_e32 v181, 16, v135
	v_and_b32_e32 v182, 0xffff0000, v135
	v_lshlrev_b32_e32 v183, 16, v136
	v_and_b32_e32 v184, 0xffff0000, v136
	v_lshlrev_b32_e32 v185, 16, v137
	v_and_b32_e32 v186, 0xffff0000, v137
	v_lshlrev_b32_e32 v187, 16, v150
	v_and_b32_e32 v150, 0xffff0000, v150
	v_lshlrev_b32_e32 v188, 16, v151
	v_and_b32_e32 v151, 0xffff0000, v151
	v_max_f32_e32 v180, v180, v180
	v_max_f32_e32 v181, v181, v181
	v_max_f32_e32 v182, v182, v182
	v_max_f32_e32 v183, v183, v183
	v_max_f32_e32 v184, v184, v184
	v_max_f32_e32 v185, v185, v185
	v_max_f32_e32 v186, v186, v186
	v_max_f32_e32 v187, v187, v187
	v_max_f32_e32 v150, v150, v150
	v_max_f32_e32 v188, v188, v188
	v_max_f32_e32 v151, v151, v151
	v_max_f32_e32 v180, 0x1e3ce508, v180
	v_max_f32_e32 v181, 0x1e3ce508, v181
	v_max_f32_e32 v182, 0x1e3ce508, v182
	v_max_f32_e32 v183, 0x1e3ce508, v183
	v_max_f32_e32 v184, 0x1e3ce508, v184
	v_max_f32_e32 v185, 0x1e3ce508, v185
	v_max_f32_e32 v186, 0x1e3ce508, v186
	v_max_f32_e32 v187, 0x1e3ce508, v187
	v_max_f32_e32 v189, 0x1e3ce508, v150
	v_max_f32_e32 v188, 0x1e3ce508, v188
	v_max_f32_e32 v190, 0x1e3ce508, v151
	v_rcp_f32_e32 v151, v180
	v_rcp_f32_e32 v180, v181
	v_rcp_f32_e32 v181, v182
	v_rcp_f32_e32 v182, v183
	v_rcp_f32_e32 v183, v184
	v_rcp_f32_e32 v184, v185
	v_rcp_f32_e32 v185, v186
	v_rcp_f32_e32 v186, v187
	v_rcp_f32_e32 v187, v189
	v_rcp_f32_e32 v188, v188
	v_rcp_f32_e32 v189, v190
	v_and_b32_e32 v179, 0xffff0000, v118
	v_lshlrev_b32_e32 v118, 16, v119
	v_and_b32_e32 v119, 0xffff0000, v119
	v_lshlrev_b32_e32 v177, 16, v134
	v_lshlrev_b32_e32 v134, 16, v120
	v_and_b32_e32 v135, 0xffff0000, v120
	v_lshlrev_b32_e32 v120, 16, v121
	v_and_b32_e32 v121, 0xffff0000, v121
	v_lshlrev_b32_e32 v136, 16, v146
	v_and_b32_e32 v137, 0xffff0000, v146
	v_lshlrev_b32_e32 v146, 16, v147
	v_and_b32_e32 v147, 0xffff0000, v147
	v_pk_mul_f32 v[118:119], v[180:181], v[118:119]
	v_pk_mul_f32 v[134:135], v[182:183], v[134:135]
	v_pk_mul_f32 v[120:121], v[184:185], v[120:121]
	v_pk_mul_f32 v[36:37], v[36:37], v[118:119]
	v_pk_mul_f32 v[118:119], v[188:189], v[146:147]
	v_pk_mul_f32 v[30:31], v[30:31], v[134:135]
	v_pk_mul_f32 v[32:33], v[32:33], v[120:121]
	v_pk_mul_f32 v[28:29], v[28:29], v[118:119]
	global_load_dwordx4 v[118:121], v[156:157], off offset:256
	v_lshlrev_b32_e32 v134, 16, v152
	v_max_f32_e32 v134, v134, v134
	v_max_f32_e32 v134, 0x1e3ce508, v134
	v_rcp_f32_e32 v146, v134
	v_and_b32_e32 v134, 0xffff0000, v152
	v_max_f32_e32 v134, v134, v134
	v_pk_mul_f32 v[136:137], v[186:187], v[136:137]
	v_max_f32_e32 v134, 0x1e3ce508, v134
	v_pk_mul_f32 v[26:27], v[26:27], v[136:137]
	v_rcp_f32_e32 v147, v134
	global_load_dwordx4 v[134:137], v[154:155], off offset:256
	v_max_f32_e32 v177, v177, v177
	v_max_f32_e32 v177, 0x1e3ce508, v177
	v_rcp_f32_e32 v150, v177
	s_nop 0
	v_pk_mul_f32 v[150:151], v[150:151], v[178:179]
	s_nop 0
	v_pk_mul_f32 v[34:35], v[34:35], v[150:151]
	v_lshlrev_b32_e32 v150, 16, v148
	v_and_b32_e32 v151, 0xffff0000, v148
	v_lshlrev_b32_e32 v148, 16, v153
	v_max_f32_e32 v148, v148, v148
	v_max_f32_e32 v148, 0x1e3ce508, v148
	v_pk_mul_f32 v[146:147], v[146:147], v[150:151]
	v_rcp_f32_e32 v150, v148
	v_and_b32_e32 v148, 0xffff0000, v153
	v_max_f32_e32 v148, v148, v148
	v_max_f32_e32 v148, 0x1e3ce508, v148
	v_rcp_f32_e32 v151, v148
	v_pk_mul_f32 v[50:51], v[50:51], v[146:147]
	v_lshlrev_b32_e32 v146, 16, v149
	v_and_b32_e32 v147, 0xffff0000, v149
	v_pk_mul_f32 v[146:147], v[150:151], v[146:147]
	v_lshlrev_b32_e32 v148, 16, v142
	v_and_b32_e32 v142, 0xffff0000, v142
	v_pk_mul_f32 v[52:53], v[52:53], v[146:147]
	v_lshlrev_b32_e32 v146, 16, v138
	v_and_b32_e32 v147, 0xffff0000, v138
	v_lshlrev_b32_e32 v138, 16, v143
	v_max_f32_e32 v148, v148, v148
	v_max_f32_e32 v142, v142, v142
	v_max_f32_e32 v138, v138, v138
	v_max_f32_e32 v148, 0x1e3ce508, v148
	v_max_f32_e32 v142, 0x1e3ce508, v142
	v_max_f32_e32 v138, 0x1e3ce508, v138
	v_rcp_f32_e32 v148, v148
	v_rcp_f32_e32 v149, v142
	v_rcp_f32_e32 v142, v138
	v_and_b32_e32 v138, 0xffff0000, v143
	v_max_f32_e32 v138, v138, v138
	v_max_f32_e32 v138, 0x1e3ce508, v138
	v_rcp_f32_e32 v143, v138
	v_lshl_add_u64 v[150:151], v[162:163], 0, s[0:1]
	v_pk_mul_f32 v[146:147], v[148:149], v[146:147]
	v_lshl_add_u64 v[154:155], s[12:13], 0, v[150:151]
	v_pk_mul_f32 v[46:47], v[46:47], v[146:147]
	global_load_dwordx4 v[146:149], v[154:155], off
	v_lshlrev_b32_e32 v138, 16, v139
	v_and_b32_e32 v139, 0xffff0000, v139
	v_pk_mul_f32 v[138:139], v[142:143], v[138:139]
	v_lshlrev_b32_e32 v142, 16, v144
	v_max_f32_e32 v142, v142, v142
	v_max_f32_e32 v142, 0x1e3ce508, v142
	v_rcp_f32_e32 v156, v142
	v_lshl_add_u64 v[142:143], s[10:11], 0, v[150:151]
	global_load_dwordx4 v[150:153], v[142:143], off
	v_and_b32_e32 v144, 0xffff0000, v144
	v_pk_mul_f32 v[48:49], v[48:49], v[138:139]
	v_lshlrev_b32_e32 v138, 16, v140
	v_and_b32_e32 v139, 0xffff0000, v140
	v_lshlrev_b32_e32 v140, 16, v145
	v_max_f32_e32 v144, v144, v144
	v_max_f32_e32 v140, v140, v140
	v_max_f32_e32 v144, 0x1e3ce508, v144
	v_max_f32_e32 v140, 0x1e3ce508, v140
	v_rcp_f32_e32 v157, v144
	v_rcp_f32_e32 v144, v140
	v_and_b32_e32 v140, 0xffff0000, v145
	v_max_f32_e32 v140, v140, v140
	v_max_f32_e32 v140, 0x1e3ce508, v140
	v_rcp_f32_e32 v145, v140
	s_waitcnt vmcnt(3)
	v_lshlrev_b32_e32 v140, 16, v118
	v_and_b32_e32 v118, 0xffff0000, v118
	v_max_f32_e32 v140, v140, v140
	v_max_f32_e32 v118, v118, v118
	v_pk_mul_f32 v[138:139], v[156:157], v[138:139]
	v_max_f32_e32 v140, 0x1e3ce508, v140
	v_max_f32_e32 v118, 0x1e3ce508, v118
	v_pk_mul_f32 v[62:63], v[62:63], v[138:139]
	v_lshlrev_b32_e32 v138, 16, v141
	v_and_b32_e32 v139, 0xffff0000, v141
	v_rcp_f32_e32 v140, v140
	v_rcp_f32_e32 v141, v118
	v_pk_mul_f32 v[138:139], v[144:145], v[138:139]
	global_load_dwordx4 v[142:145], v[142:143], off offset:256
	v_pk_mul_f32 v[64:65], v[64:65], v[138:139]
	s_waitcnt vmcnt(3)
; __device__ __forceinline__ float bf_lo(unsigned w) { return __uint_as_float(w << 16); }
; __device__ __forceinline__ float bf_hi(unsigned w) { return __uint_as_float(w & 0xffff0000u); }
;     __device__ __forceinline__ void mid(f32x4 (&acc)[2][2][4][2], const Unit& u, int wr, int wc, int fr, int fq) const {
;     ...
;             for (int m = 0; m < 4; ++m) { const size_t off = (size_t)(row0 + ai * HALF + m * 16) * 4096 + col0;
; #pragma unroll
;                 for (int bj = 0; bj < 2; ++bj) { const u32x4 ga = *(const u32x4*)(SGA + off + bj * HALF), gb = *(const u32x4*)(SGB + off + bj * HALF);
;                     const unsigned wa[4] = {ga.x, ga.y, ga.z, ga.w}, wb[4] = {gb.x, gb.y, gb.z, gb.w};
; #pragma unroll
;                     for (int p = 0; p < 4; ++p) { const float rl = bf_lo(wa[p]) * __builtin_amdgcn_rcpf(fmaxf(bf_lo(wb[p]), 1e-20f)), rh = bf_hi(wa[p]) * __builtin_amdgcn_rcpf(fmaxf(bf_hi(wb[p]), 1e-20f));
;                         acc[ai][bj][m][p >> 1][(p & 1) * 2] *= rl; acc[ai][bj][m][p >> 1][(p & 1) * 2 + 1] *= rh; } }
	v_lshlrev_b32_e32 v138, 16, v134
	v_and_b32_e32 v139, 0xffff0000, v134
	v_pk_mul_f32 v[138:139], v[140:141], v[138:139]
	v_lshlrev_b32_e32 v118, 16, v119
	v_pk_mul_f32 v[58:59], v[58:59], v[138:139]
	global_load_dwordx4 v[138:141], v[154:155], off offset:256
	v_and_b32_e32 v119, 0xffff0000, v119
	v_max_f32_e32 v118, v118, v118
	v_max_f32_e32 v119, v119, v119
	v_max_f32_e32 v118, 0x1e3ce508, v118
	v_max_f32_e32 v119, 0x1e3ce508, v119
	v_rcp_f32_e32 v118, v118
	v_rcp_f32_e32 v119, v119
	v_lshlrev_b32_e32 v134, 16, v135
	v_and_b32_e32 v135, 0xffff0000, v135
	s_mov_b64 s[0:1], 0x60000
	v_pk_mul_f32 v[118:119], v[118:119], v[134:135]
	v_lshlrev_b32_e32 v134, 16, v136
	v_pk_mul_f32 v[60:61], v[60:61], v[118:119]
	v_lshlrev_b32_e32 v118, 16, v120
	v_and_b32_e32 v119, 0xffff0000, v120
	v_max_f32_e32 v118, v118, v118
	v_max_f32_e32 v119, v119, v119
	v_max_f32_e32 v118, 0x1e3ce508, v118
	v_max_f32_e32 v119, 0x1e3ce508, v119
	v_lshlrev_b32_e32 v120, 16, v121
	v_and_b32_e32 v121, 0xffff0000, v121
	v_rcp_f32_e32 v118, v118
	v_rcp_f32_e32 v119, v119
	v_max_f32_e32 v120, v120, v120
	v_max_f32_e32 v121, v121, v121
	v_max_f32_e32 v120, 0x1e3ce508, v120
	v_max_f32_e32 v121, 0x1e3ce508, v121
	v_rcp_f32_e32 v120, v120
	v_rcp_f32_e32 v121, v121
	v_and_b32_e32 v135, 0xffff0000, v136
	v_pk_mul_f32 v[118:119], v[118:119], v[134:135]
	s_nop 0
	v_pk_mul_f32 v[82:83], v[82:83], v[118:119]
	v_lshlrev_b32_e32 v118, 16, v137
	v_and_b32_e32 v119, 0xffff0000, v137
	v_pk_mul_f32 v[118:119], v[120:121], v[118:119]
	s_waitcnt vmcnt(3)
	v_lshlrev_b32_e32 v120, 16, v146
	v_and_b32_e32 v121, 0xffff0000, v146
	v_max_f32_e32 v120, v120, v120
	v_max_f32_e32 v121, v121, v121
	v_max_f32_e32 v120, 0x1e3ce508, v120
	v_max_f32_e32 v121, 0x1e3ce508, v121
	v_rcp_f32_e32 v120, v120
	v_rcp_f32_e32 v121, v121
	v_pk_mul_f32 v[84:85], v[84:85], v[118:119]
	s_waitcnt vmcnt(2)
	v_lshlrev_b32_e32 v118, 16, v150
	v_and_b32_e32 v119, 0xffff0000, v150
	v_pk_mul_f32 v[118:119], v[120:121], v[118:119]
	v_lshlrev_b32_e32 v150, 16, v151
	v_pk_mul_f32 v[78:79], v[78:79], v[118:119]
	v_lshlrev_b32_e32 v118, 16, v147
	v_and_b32_e32 v119, 0xffff0000, v147
	v_lshl_add_u64 v[146:147], v[162:163], 0, s[0:1]
	v_lshl_add_u64 v[120:121], s[12:13], 0, v[146:147]
	v_max_f32_e32 v118, v118, v118
	v_max_f32_e32 v119, v119, v119
	global_load_dwordx4 v[134:137], v[120:121], off
	v_max_f32_e32 v118, 0x1e3ce508, v118
	v_max_f32_e32 v119, 0x1e3ce508, v119
	v_rcp_f32_e32 v118, v118
	v_rcp_f32_e32 v119, v119
	v_and_b32_e32 v151, 0xffff0000, v151
	s_mov_b64 s[0:1], 0x120000
	v_pk_mul_f32 v[150:151], v[118:119], v[150:151]
	v_lshlrev_b32_e32 v118, 16, v148
	v_max_f32_e32 v118, v118, v118
	v_max_f32_e32 v118, 0x1e3ce508, v118
	v_rcp_f32_e32 v178, v118
	v_lshl_add_u64 v[118:119], s[10:11], 0, v[146:147]
	global_load_dwordx4 v[154:157], v[118:119], off
	v_and_b32_e32 v146, 0xffff0000, v148
	v_max_f32_e32 v146, v146, v146
	v_max_f32_e32 v146, 0x1e3ce508, v146
	v_lshlrev_b32_e32 v148, 16, v149
	v_and_b32_e32 v149, 0xffff0000, v149
	v_rcp_f32_e32 v179, v146
	v_max_f32_e32 v148, v148, v148
	v_max_f32_e32 v149, v149, v149
	v_max_f32_e32 v148, 0x1e3ce508, v148
	v_max_f32_e32 v149, 0x1e3ce508, v149
	v_rcp_f32_e32 v148, v148
	v_rcp_f32_e32 v149, v149
	v_lshlrev_b32_e32 v146, 16, v152
	v_and_b32_e32 v147, 0xffff0000, v152
	v_pk_mul_f32 v[146:147], v[178:179], v[146:147]
	v_pk_mul_f32 v[80:81], v[80:81], v[150:151]
	v_pk_mul_f32 v[90:91], v[90:91], v[146:147]
	v_lshlrev_b32_e32 v146, 16, v153
	v_and_b32_e32 v147, 0xffff0000, v153
	v_pk_mul_f32 v[146:147], v[148:149], v[146:147]
	s_waitcnt vmcnt(2)
	v_lshlrev_b32_e32 v148, 16, v138
	v_and_b32_e32 v138, 0xffff0000, v138
	v_max_f32_e32 v148, v148, v148
	v_max_f32_e32 v138, v138, v138
	v_max_f32_e32 v148, 0x1e3ce508, v148
	v_max_f32_e32 v138, 0x1e3ce508, v138
	global_load_dwordx4 v[150:153], v[120:121], off offset:256
	v_rcp_f32_e32 v148, v148
	v_rcp_f32_e32 v149, v138
	v_pk_mul_f32 v[92:93], v[92:93], v[146:147]
	v_lshlrev_b32_e32 v146, 16, v142
	v_and_b32_e32 v147, 0xffff0000, v142
	v_pk_mul_f32 v[146:147], v[148:149], v[146:147]
	v_lshlrev_b32_e32 v138, 16, v139
	v_pk_mul_f32 v[110:111], v[110:111], v[146:147]
	global_load_dwordx4 v[146:149], v[118:119], off offset:256
	v_and_b32_e32 v139, 0xffff0000, v139
	v_max_f32_e32 v138, v138, v138
	v_max_f32_e32 v139, v139, v139
	v_max_f32_e32 v138, 0x1e3ce508, v138
	v_max_f32_e32 v120, 0x1e3ce508, v139
	v_rcp_f32_e32 v138, v138
	v_rcp_f32_e32 v139, v120
	v_lshlrev_b32_e32 v120, 16, v143
	v_and_b32_e32 v121, 0xffff0000, v143
	v_and_b32_e32 v119, 0xffff0000, v140
	v_pk_mul_f32 v[120:121], v[138:139], v[120:121]
	v_lshlrev_b32_e32 v138, 16, v140
	v_max_f32_e32 v138, v138, v138
	v_max_f32_e32 v119, v119, v119
	v_max_f32_e32 v118, 0x1e3ce508, v138
	v_max_f32_e32 v119, 0x1e3ce508, v119
	v_rcp_f32_e32 v118, v118
	v_rcp_f32_e32 v119, v119
	v_pk_mul_f32 v[112:113], v[112:113], v[120:121]
	v_lshlrev_b32_e32 v120, 16, v144
	v_and_b32_e32 v121, 0xffff0000, v144
	v_pk_mul_f32 v[118:119], v[118:119], v[120:121]
	v_lshlrev_b32_e32 v120, 16, v141
	v_and_b32_e32 v121, 0xffff0000, v141
	v_max_f32_e32 v120, v120, v120
	v_max_f32_e32 v121, v121, v121
	v_max_f32_e32 v120, 0x1e3ce508, v120
	v_max_f32_e32 v121, 0x1e3ce508, v121
	v_rcp_f32_e32 v120, v120
	v_rcp_f32_e32 v121, v121
	v_pk_mul_f32 v[118:119], v[106:107], v[118:119]
	v_lshlrev_b32_e32 v106, 16, v145
	v_and_b32_e32 v107, 0xffff0000, v145
	v_pk_mul_f32 v[106:107], v[120:121], v[106:107]
	s_waitcnt vmcnt(3)
; __device__ __forceinline__ float bf_lo(unsigned w) { return __uint_as_float(w << 16); }
; __device__ __forceinline__ float bf_hi(unsigned w) { return __uint_as_float(w & 0xffff0000u); }
;     __device__ __forceinline__ void mid(f32x4 (&acc)[2][2][4][2], const Unit& u, int wr, int wc, int fr, int fq) const {
;     ...
;             for (int m = 0; m < 4; ++m) { const size_t off = (size_t)(row0 + ai * HALF + m * 16) * 4096 + col0;
; #pragma unroll
;                 for (int bj = 0; bj < 2; ++bj) { const u32x4 ga = *(const u32x4*)(SGA + off + bj * HALF), gb = *(const u32x4*)(SGB + off + bj * HALF);
;                     const unsigned wa[4] = {ga.x, ga.y, ga.z, ga.w}, wb[4] = {gb.x, gb.y, gb.z, gb.w};
; #pragma unroll
;                     for (int p = 0; p < 4; ++p) { const float rl = bf_lo(wa[p]) * __builtin_amdgcn_rcpf(fmaxf(bf_lo(wb[p]), 1e-20f)), rh = bf_hi(wa[p]) * __builtin_amdgcn_rcpf(fmaxf(bf_hi(wb[p]), 1e-20f));
;                         acc[ai][bj][m][p >> 1][(p & 1) * 2] *= rl; acc[ai][bj][m][p >> 1][(p & 1) * 2 + 1] *= rh; } }
	v_lshlrev_b32_e32 v120, 16, v134
	v_max_f32_e32 v120, v120, v120
	v_max_f32_e32 v120, 0x1e3ce508, v120
	v_rcp_f32_e32 v138, v120
	v_and_b32_e32 v120, 0xffff0000, v134
	v_max_f32_e32 v120, v120, v120
	v_max_f32_e32 v120, 0x1e3ce508, v120
	v_rcp_f32_e32 v139, v120
	v_pk_mul_f32 v[120:121], v[108:109], v[106:107]
	v_lshlrev_b32_e32 v108, 16, v135
	v_and_b32_e32 v109, 0xffff0000, v135
	v_max_f32_e32 v108, v108, v108
	v_max_f32_e32 v109, v109, v109
	v_max_f32_e32 v108, 0x1e3ce508, v108
	v_max_f32_e32 v109, 0x1e3ce508, v109
	v_rcp_f32_e32 v108, v108
	v_rcp_f32_e32 v109, v109
	s_waitcnt vmcnt(2)
	v_lshlrev_b32_e32 v106, 16, v154
	v_and_b32_e32 v107, 0xffff0000, v154
	v_pk_mul_f32 v[106:107], v[138:139], v[106:107]
	v_lshl_add_u64 v[140:141], v[162:163], 0, s[0:1]
	v_pk_mul_f32 v[106:107], v[130:131], v[106:107]
	v_lshlrev_b32_e32 v130, 16, v155
	v_and_b32_e32 v131, 0xffff0000, v155
	v_pk_mul_f32 v[108:109], v[108:109], v[130:131]
	v_lshlrev_b32_e32 v130, 16, v136
	v_and_b32_e32 v131, 0xffff0000, v136
	v_max_f32_e32 v130, v130, v130
	v_max_f32_e32 v131, v131, v131
	v_max_f32_e32 v130, 0x1e3ce508, v130
	v_max_f32_e32 v131, 0x1e3ce508, v131
	v_rcp_f32_e32 v130, v130
	v_rcp_f32_e32 v131, v131
	v_pk_mul_f32 v[108:109], v[132:133], v[108:109]
	v_lshlrev_b32_e32 v132, 16, v156
	v_and_b32_e32 v133, 0xffff0000, v156
	v_pk_mul_f32 v[130:131], v[130:131], v[132:133]
	v_lshlrev_b32_e32 v132, 16, v137
	v_and_b32_e32 v133, 0xffff0000, v137
	v_max_f32_e32 v132, v132, v132
	v_max_f32_e32 v133, v133, v133
	v_max_f32_e32 v132, 0x1e3ce508, v132
	v_max_f32_e32 v133, 0x1e3ce508, v133
	v_rcp_f32_e32 v132, v132
	v_rcp_f32_e32 v133, v133
	v_pk_mul_f32 v[114:115], v[114:115], v[130:131]
	v_lshlrev_b32_e32 v130, 16, v157
	v_and_b32_e32 v131, 0xffff0000, v157
	v_pk_mul_f32 v[130:131], v[132:133], v[130:131]
	s_waitcnt vmcnt(1)
	v_lshlrev_b32_e32 v132, 16, v150
	v_and_b32_e32 v133, 0xffff0000, v150
	v_max_f32_e32 v132, v132, v132
	v_max_f32_e32 v133, v133, v133
	v_max_f32_e32 v132, 0x1e3ce508, v132
	v_max_f32_e32 v133, 0x1e3ce508, v133
	v_rcp_f32_e32 v132, v132
	v_rcp_f32_e32 v133, v133
	v_pk_mul_f32 v[116:117], v[116:117], v[130:131]
	s_waitcnt vmcnt(0)
	v_lshlrev_b32_e32 v130, 16, v146
	v_and_b32_e32 v131, 0xffff0000, v146
	v_pk_mul_f32 v[130:131], v[132:133], v[130:131]
	v_lshlrev_b32_e32 v132, 16, v151
	v_and_b32_e32 v133, 0xffff0000, v151
	v_max_f32_e32 v132, v132, v132
	v_max_f32_e32 v133, v133, v133
	v_max_f32_e32 v132, 0x1e3ce508, v132
	v_max_f32_e32 v133, 0x1e3ce508, v133
	v_rcp_f32_e32 v132, v132
	v_rcp_f32_e32 v133, v133
	v_pk_mul_f32 v[122:123], v[122:123], v[130:131]
	v_lshlrev_b32_e32 v130, 16, v147
	v_and_b32_e32 v131, 0xffff0000, v147
	v_pk_mul_f32 v[130:131], v[132:133], v[130:131]
	v_lshlrev_b32_e32 v132, 16, v152
	v_and_b32_e32 v133, 0xffff0000, v152
	v_max_f32_e32 v132, v132, v132
	v_max_f32_e32 v133, v133, v133
	v_max_f32_e32 v132, 0x1e3ce508, v132
	v_max_f32_e32 v133, 0x1e3ce508, v133
	v_rcp_f32_e32 v132, v132
	v_rcp_f32_e32 v133, v133
	v_pk_mul_f32 v[124:125], v[124:125], v[130:131]
	v_lshlrev_b32_e32 v130, 16, v148
	v_and_b32_e32 v131, 0xffff0000, v148
	v_pk_mul_f32 v[130:131], v[132:133], v[130:131]
	v_lshlrev_b32_e32 v132, 16, v153
	v_and_b32_e32 v133, 0xffff0000, v153
	v_max_f32_e32 v132, v132, v132
	v_max_f32_e32 v133, v133, v133
	v_max_f32_e32 v132, 0x1e3ce508, v132
	v_max_f32_e32 v133, 0x1e3ce508, v133
	v_rcp_f32_e32 v132, v132
	v_rcp_f32_e32 v133, v133
	v_pk_mul_f32 v[126:127], v[126:127], v[130:131]
	v_lshlrev_b32_e32 v130, 16, v149
	v_and_b32_e32 v131, 0xffff0000, v149
	v_pk_mul_f32 v[130:131], v[132:133], v[130:131]
	v_lshl_add_u64 v[154:155], s[12:13], 0, v[140:141]
	v_pk_mul_f32 v[128:129], v[128:129], v[130:131]
	v_lshl_add_u64 v[130:131], v[162:163], 0, s[8:9]
	v_lshl_add_u64 v[132:133], s[12:13], 0, v[130:131]
	global_load_dwordx4 v[150:153], v[132:133], off
	v_lshl_add_u64 v[130:131], s[10:11], 0, v[130:131]
	global_load_dwordx4 v[146:149], v[130:131], off
	global_load_dwordx4 v[142:145], v[132:133], off offset:256
	global_load_dwordx4 v[134:137], v[130:131], off offset:256
	s_mov_b64 s[0:1], 0x140000
	s_waitcnt vmcnt(3)
	v_lshlrev_b32_e32 v130, 16, v150
	v_and_b32_e32 v131, 0xffff0000, v150
	v_max_f32_e32 v130, v130, v130
	v_max_f32_e32 v131, v131, v131
	v_max_f32_e32 v130, 0x1e3ce508, v130
	v_max_f32_e32 v131, 0x1e3ce508, v131
	v_rcp_f32_e32 v130, v130
	v_rcp_f32_e32 v131, v131
	s_waitcnt vmcnt(2)
	v_lshlrev_b32_e32 v132, 16, v146
	v_and_b32_e32 v133, 0xffff0000, v146
	v_lshlrev_b32_e32 v146, 16, v147
	v_pk_mul_f32 v[130:131], v[130:131], v[132:133]
	v_and_b32_e32 v147, 0xffff0000, v147
	v_pk_mul_f32 v[102:103], v[102:103], v[130:131]
	v_lshlrev_b32_e32 v130, 16, v151
	v_max_f32_e32 v130, v130, v130
	v_max_f32_e32 v130, 0x1e3ce508, v130
	v_rcp_f32_e32 v138, v130
	v_and_b32_e32 v130, 0xffff0000, v151
	v_max_f32_e32 v130, v130, v130
	v_max_f32_e32 v130, 0x1e3ce508, v130
	v_rcp_f32_e32 v139, v130
	global_load_dwordx4 v[130:133], v[154:155], off
	v_lshl_add_u64 v[150:151], s[10:11], 0, v[140:141]
	v_pk_mul_f32 v[146:147], v[138:139], v[146:147]
	v_lshlrev_b32_e32 v138, 16, v152
	v_max_f32_e32 v138, v138, v138
	v_max_f32_e32 v138, 0x1e3ce508, v138
	v_rcp_f32_e32 v156, v138
	global_load_dwordx4 v[138:141], v[150:151], off
	v_and_b32_e32 v152, 0xffff0000, v152
	v_pk_mul_f32 v[104:105], v[104:105], v[146:147]
	v_lshlrev_b32_e32 v146, 16, v148
	v_and_b32_e32 v147, 0xffff0000, v148
	v_lshlrev_b32_e32 v148, 16, v153
	v_max_f32_e32 v152, v152, v152
	v_max_f32_e32 v148, v148, v148
	v_max_f32_e32 v152, 0x1e3ce508, v152
	v_max_f32_e32 v148, 0x1e3ce508, v148
	v_rcp_f32_e32 v157, v152
	v_rcp_f32_e32 v152, v148
	v_and_b32_e32 v148, 0xffff0000, v153
	v_max_f32_e32 v148, v148, v148
	v_max_f32_e32 v148, 0x1e3ce508, v148
	v_rcp_f32_e32 v153, v148
	s_waitcnt vmcnt(3)
; __device__ __forceinline__ float bf_lo(unsigned w) { return __uint_as_float(w << 16); }
; __device__ __forceinline__ float bf_hi(unsigned w) { return __uint_as_float(w & 0xffff0000u); }
;     __device__ __forceinline__ void mid(f32x4 (&acc)[2][2][4][2], const Unit& u, int wr, int wc, int fr, int fq) const {
;     ...
;             for (int m = 0; m < 4; ++m) { const size_t off = (size_t)(row0 + ai * HALF + m * 16) * 4096 + col0;
; #pragma unroll
;                 for (int bj = 0; bj < 2; ++bj) { const u32x4 ga = *(const u32x4*)(SGA + off + bj * HALF), gb = *(const u32x4*)(SGB + off + bj * HALF);
;                     const unsigned wa[4] = {ga.x, ga.y, ga.z, ga.w}, wb[4] = {gb.x, gb.y, gb.z, gb.w};
; #pragma unroll
;                     for (int p = 0; p < 4; ++p) { const float rl = bf_lo(wa[p]) * __builtin_amdgcn_rcpf(fmaxf(bf_lo(wb[p]), 1e-20f)), rh = bf_hi(wa[p]) * __builtin_amdgcn_rcpf(fmaxf(bf_hi(wb[p]), 1e-20f));
;                         acc[ai][bj][m][p >> 1][(p & 1) * 2] *= rl; acc[ai][bj][m][p >> 1][(p & 1) * 2 + 1] *= rh; } }
	v_lshlrev_b32_e32 v148, 16, v142
	v_and_b32_e32 v142, 0xffff0000, v142
	v_max_f32_e32 v148, v148, v148
	v_max_f32_e32 v142, v142, v142
	v_pk_mul_f32 v[146:147], v[156:157], v[146:147]
	v_max_f32_e32 v148, 0x1e3ce508, v148
	v_max_f32_e32 v142, 0x1e3ce508, v142
	v_pk_mul_f32 v[98:99], v[98:99], v[146:147]
	v_lshlrev_b32_e32 v146, 16, v149
	v_and_b32_e32 v147, 0xffff0000, v149
	v_rcp_f32_e32 v148, v148
	v_rcp_f32_e32 v149, v142
	v_pk_mul_f32 v[146:147], v[152:153], v[146:147]
	global_load_dwordx4 v[150:153], v[150:151], off offset:256
	v_pk_mul_f32 v[100:101], v[100:101], v[146:147]
	s_waitcnt vmcnt(3)
	v_lshlrev_b32_e32 v146, 16, v134
	v_and_b32_e32 v147, 0xffff0000, v134
	v_pk_mul_f32 v[146:147], v[148:149], v[146:147]
	v_lshlrev_b32_e32 v134, 16, v143
	v_pk_mul_f32 v[94:95], v[94:95], v[146:147]
	global_load_dwordx4 v[146:149], v[154:155], off offset:256
	v_max_f32_e32 v134, v134, v134
	v_max_f32_e32 v134, 0x1e3ce508, v134
	v_rcp_f32_e32 v142, v134
	v_and_b32_e32 v134, 0xffff0000, v143
	v_max_f32_e32 v134, v134, v134
	v_max_f32_e32 v134, 0x1e3ce508, v134
	v_rcp_f32_e32 v143, v134
	v_lshlrev_b32_e32 v134, 16, v135
	v_and_b32_e32 v135, 0xffff0000, v135
	v_pk_mul_f32 v[134:135], v[142:143], v[134:135]
	s_nop 0
	v_pk_mul_f32 v[96:97], v[96:97], v[134:135]
	v_lshlrev_b32_e32 v134, 16, v144
	v_and_b32_e32 v135, 0xffff0000, v144
	v_max_f32_e32 v134, v134, v134
	v_max_f32_e32 v135, v135, v135
	v_max_f32_e32 v134, 0x1e3ce508, v134
	v_max_f32_e32 v135, 0x1e3ce508, v135
	v_rcp_f32_e32 v134, v134
	v_rcp_f32_e32 v135, v135
	v_lshlrev_b32_e32 v142, 16, v136
	v_and_b32_e32 v143, 0xffff0000, v136
	v_lshlrev_b32_e32 v136, 16, v145
	v_max_f32_e32 v136, v136, v136
	v_max_f32_e32 v136, 0x1e3ce508, v136
	v_pk_mul_f32 v[134:135], v[134:135], v[142:143]
	v_rcp_f32_e32 v142, v136
	v_and_b32_e32 v136, 0xffff0000, v145
	v_max_f32_e32 v136, v136, v136
	v_max_f32_e32 v136, 0x1e3ce508, v136
	v_rcp_f32_e32 v143, v136
	v_pk_mul_f32 v[86:87], v[86:87], v[134:135]
	v_lshlrev_b32_e32 v134, 16, v137
	v_and_b32_e32 v135, 0xffff0000, v137
	v_pk_mul_f32 v[134:135], v[142:143], v[134:135]
	s_waitcnt vmcnt(3)
	v_lshlrev_b32_e32 v136, 16, v130
	v_and_b32_e32 v130, 0xffff0000, v130
	v_max_f32_e32 v130, v130, v130
	v_max_f32_e32 v130, 0x1e3ce508, v130
	v_rcp_f32_e32 v137, v130
	v_lshlrev_b32_e32 v130, 16, v131
	v_max_f32_e32 v136, v136, v136
	v_max_f32_e32 v130, v130, v130
	v_max_f32_e32 v136, 0x1e3ce508, v136
	v_max_f32_e32 v130, 0x1e3ce508, v130
	v_rcp_f32_e32 v136, v136
	v_rcp_f32_e32 v142, v130
	v_and_b32_e32 v130, 0xffff0000, v131
	v_max_f32_e32 v130, v130, v130
	v_max_f32_e32 v130, 0x1e3ce508, v130
	v_pk_mul_f32 v[88:89], v[88:89], v[134:135]
	s_waitcnt vmcnt(2)
	v_lshlrev_b32_e32 v134, 16, v138
	v_and_b32_e32 v135, 0xffff0000, v138
	v_rcp_f32_e32 v143, v130
	v_lshl_add_u64 v[144:145], v[162:163], 0, s[0:1]
	v_pk_mul_f32 v[134:135], v[136:137], v[134:135]
	v_lshl_add_u64 v[130:131], s[12:13], 0, v[144:145]
	v_pk_mul_f32 v[74:75], v[74:75], v[134:135]
	global_load_dwordx4 v[134:137], v[130:131], off
	v_lshlrev_b32_e32 v138, 16, v139
	v_and_b32_e32 v139, 0xffff0000, v139
	v_pk_mul_f32 v[154:155], v[142:143], v[138:139]
	v_lshlrev_b32_e32 v138, 16, v132
	v_max_f32_e32 v138, v138, v138
	v_and_b32_e32 v132, 0xffff0000, v132
	v_max_f32_e32 v138, 0x1e3ce508, v138
	v_max_f32_e32 v132, v132, v132
	v_rcp_f32_e32 v156, v138
	v_lshl_add_u64 v[138:139], s[10:11], 0, v[144:145]
	v_max_f32_e32 v132, 0x1e3ce508, v132
	global_load_dwordx4 v[142:145], v[138:139], off
	v_rcp_f32_e32 v157, v132
	v_lshlrev_b32_e32 v132, 16, v133
	v_and_b32_e32 v133, 0xffff0000, v133
	v_max_f32_e32 v132, v132, v132
	v_max_f32_e32 v133, v133, v133
	v_max_f32_e32 v132, 0x1e3ce508, v132
	v_max_f32_e32 v133, 0x1e3ce508, v133
	v_rcp_f32_e32 v132, v132
	v_rcp_f32_e32 v133, v133
	v_pk_mul_f32 v[76:77], v[76:77], v[154:155]
	v_lshlrev_b32_e32 v154, 16, v140
	v_and_b32_e32 v155, 0xffff0000, v140
	v_lshlrev_b32_e32 v140, 16, v141
	v_and_b32_e32 v141, 0xffff0000, v141
	v_pk_mul_f32 v[132:133], v[132:133], v[140:141]
	s_waitcnt vmcnt(2)
	v_lshlrev_b32_e32 v140, 16, v146
	v_and_b32_e32 v141, 0xffff0000, v146
	v_max_f32_e32 v140, v140, v140
	v_max_f32_e32 v141, v141, v141
	v_max_f32_e32 v140, 0x1e3ce508, v140
	v_max_f32_e32 v141, 0x1e3ce508, v141
	v_rcp_f32_e32 v140, v140
	v_rcp_f32_e32 v141, v141
	v_pk_mul_f32 v[72:73], v[72:73], v[132:133]
	v_lshlrev_b32_e32 v132, 16, v150
	v_and_b32_e32 v133, 0xffff0000, v150
	v_pk_mul_f32 v[132:133], v[140:141], v[132:133]
	v_lshlrev_b32_e32 v140, 16, v147
	v_and_b32_e32 v141, 0xffff0000, v147
	v_max_f32_e32 v140, v140, v140
	v_max_f32_e32 v141, v141, v141
	v_max_f32_e32 v140, 0x1e3ce508, v140
	v_max_f32_e32 v141, 0x1e3ce508, v141
	v_rcp_f32_e32 v140, v140
	v_rcp_f32_e32 v141, v141
	v_pk_mul_f32 v[66:67], v[66:67], v[132:133]
	v_lshlrev_b32_e32 v132, 16, v151
	v_and_b32_e32 v133, 0xffff0000, v151
	v_pk_mul_f32 v[132:133], v[140:141], v[132:133]
	v_lshlrev_b32_e32 v140, 16, v148
	v_pk_mul_f32 v[68:69], v[68:69], v[132:133]
	global_load_dwordx4 v[130:133], v[130:131], off offset:256
	v_max_f32_e32 v140, v140, v140
	v_max_f32_e32 v140, 0x1e3ce508, v140
	v_rcp_f32_e32 v146, v140
	v_and_b32_e32 v140, 0xffff0000, v148
	v_max_f32_e32 v140, v140, v140
	v_max_f32_e32 v140, 0x1e3ce508, v140
	v_rcp_f32_e32 v147, v140
	global_load_dwordx4 v[138:141], v[138:139], off offset:256
	v_lshlrev_b32_e32 v148, 16, v149
	v_and_b32_e32 v149, 0xffff0000, v149
	v_max_f32_e32 v148, v148, v148
	v_max_f32_e32 v149, v149, v149
	v_max_f32_e32 v148, 0x1e3ce508, v148
	v_max_f32_e32 v149, 0x1e3ce508, v149
	v_rcp_f32_e32 v148, v148
	v_rcp_f32_e32 v149, v149
	v_lshlrev_b32_e32 v150, 16, v152
	v_and_b32_e32 v151, 0xffff0000, v152
	v_pk_mul_f32 v[146:147], v[146:147], v[150:151]
	s_mov_b64 s[0:1], 0x160000
	v_pk_mul_f32 v[54:55], v[54:55], v[146:147]
	v_lshlrev_b32_e32 v146, 16, v153
	v_and_b32_e32 v147, 0xffff0000, v153
	v_pk_mul_f32 v[146:147], v[148:149], v[146:147]
	v_pk_mul_f32 v[154:155], v[156:157], v[154:155]
	s_waitcnt vmcnt(3)
; __device__ __forceinline__ float bf_lo(unsigned w) { return __uint_as_float(w << 16); }
; __device__ __forceinline__ float bf_hi(unsigned w) { return __uint_as_float(w & 0xffff0000u); }
;     __device__ __forceinline__ void mid(f32x4 (&acc)[2][2][4][2], const Unit& u, int wr, int wc, int fr, int fq) const {
;     ...
;             for (int m = 0; m < 4; ++m) { const size_t off = (size_t)(row0 + ai * HALF + m * 16) * 4096 + col0;
; #pragma unroll
;                 for (int bj = 0; bj < 2; ++bj) { const u32x4 ga = *(const u32x4*)(SGA + off + bj * HALF), gb = *(const u32x4*)(SGB + off + bj * HALF);
;                     const unsigned wa[4] = {ga.x, ga.y, ga.z, ga.w}, wb[4] = {gb.x, gb.y, gb.z, gb.w};
; #pragma unroll
;                     for (int p = 0; p < 4; ++p) { const float rl = bf_lo(wa[p]) * __builtin_amdgcn_rcpf(fmaxf(bf_lo(wb[p]), 1e-20f)), rh = bf_hi(wa[p]) * __builtin_amdgcn_rcpf(fmaxf(bf_hi(wb[p]), 1e-20f));
;                         acc[ai][bj][m][p >> 1][(p & 1) * 2] *= rl; acc[ai][bj][m][p >> 1][(p & 1) * 2 + 1] *= rh; } }
	v_lshlrev_b32_e32 v148, 16, v134
	v_and_b32_e32 v134, 0xffff0000, v134
	v_max_f32_e32 v148, v148, v148
	v_max_f32_e32 v134, v134, v134
	v_max_f32_e32 v148, 0x1e3ce508, v148
	v_max_f32_e32 v134, 0x1e3ce508, v134
	v_rcp_f32_e32 v148, v148
	v_rcp_f32_e32 v149, v134
	v_pk_mul_f32 v[56:57], v[56:57], v[146:147]
	v_lshl_add_u64 v[150:151], v[162:163], 0, s[0:1]
	v_pk_mul_f32 v[70:71], v[70:71], v[154:155]
	v_lshlrev_b32_e32 v134, 16, v135
	s_waitcnt vmcnt(2)
	v_lshlrev_b32_e32 v146, 16, v142
	v_and_b32_e32 v147, 0xffff0000, v142
	v_pk_mul_f32 v[146:147], v[148:149], v[146:147]
	v_and_b32_e32 v135, 0xffff0000, v135
	v_lshl_add_u64 v[154:155], s[12:13], 0, v[150:151]
	v_pk_mul_f32 v[42:43], v[42:43], v[146:147]
	v_max_f32_e32 v134, v134, v134
	v_max_f32_e32 v135, v135, v135
	global_load_dwordx4 v[146:149], v[154:155], off
	v_max_f32_e32 v134, 0x1e3ce508, v134
	v_max_f32_e32 v135, 0x1e3ce508, v135
	v_rcp_f32_e32 v134, v134
	v_rcp_f32_e32 v135, v135
	v_lshlrev_b32_e32 v142, 16, v143
	v_and_b32_e32 v143, 0xffff0000, v143
	s_mul_i32 s0, s50, s63
	v_pk_mul_f32 v[142:143], v[134:135], v[142:143]
	v_lshlrev_b32_e32 v134, 16, v136
	v_max_f32_e32 v134, v134, v134
	v_max_f32_e32 v134, 0x1e3ce508, v134
	v_rcp_f32_e32 v156, v134
	v_lshl_add_u64 v[134:135], s[10:11], 0, v[150:151]
	global_load_dwordx4 v[150:153], v[134:135], off
	v_and_b32_e32 v136, 0xffff0000, v136
	v_max_f32_e32 v136, v136, v136
	v_max_f32_e32 v136, 0x1e3ce508, v136
	v_rcp_f32_e32 v157, v136
	v_lshlrev_b32_e32 v136, 16, v137
	v_and_b32_e32 v137, 0xffff0000, v137
	v_max_f32_e32 v136, v136, v136
	v_max_f32_e32 v137, v137, v137
	v_max_f32_e32 v136, 0x1e3ce508, v136
	v_max_f32_e32 v137, 0x1e3ce508, v137
	v_rcp_f32_e32 v136, v136
	v_rcp_f32_e32 v137, v137
	v_pk_mul_f32 v[44:45], v[44:45], v[142:143]
	v_lshlrev_b32_e32 v142, 16, v144
	v_and_b32_e32 v143, 0xffff0000, v144
	v_pk_mul_f32 v[142:143], v[156:157], v[142:143]
	s_mul_hi_u32 s1, s50, s2
	v_pk_mul_f32 v[38:39], v[38:39], v[142:143]
	v_lshlrev_b32_e32 v142, 16, v145
	v_and_b32_e32 v143, 0xffff0000, v145
	v_pk_mul_f32 v[136:137], v[136:137], v[142:143]
	s_waitcnt vmcnt(3)
	v_lshlrev_b32_e32 v142, 16, v130
	v_and_b32_e32 v130, 0xffff0000, v130
	v_max_f32_e32 v142, v142, v142
	v_max_f32_e32 v130, v130, v130
	v_max_f32_e32 v142, 0x1e3ce508, v142
	v_max_f32_e32 v130, 0x1e3ce508, v130
	v_rcp_f32_e32 v142, v142
	v_rcp_f32_e32 v143, v130
	v_lshlrev_b32_e32 v130, 16, v131
	v_and_b32_e32 v131, 0xffff0000, v131
	v_pk_mul_f32 v[40:41], v[40:41], v[136:137]
	s_waitcnt vmcnt(2)
	v_lshlrev_b32_e32 v136, 16, v138
	v_and_b32_e32 v137, 0xffff0000, v138
	v_max_f32_e32 v130, v130, v130
	v_max_f32_e32 v131, v131, v131
	v_pk_mul_f32 v[136:137], v[142:143], v[136:137]
	v_max_f32_e32 v130, 0x1e3ce508, v130
	global_load_dwordx4 v[142:145], v[154:155], off offset:256
	v_max_f32_e32 v131, 0x1e3ce508, v131
	v_rcp_f32_e32 v130, v130
	v_rcp_f32_e32 v131, v131
	v_pk_mul_f32 v[22:23], v[22:23], v[136:137]
	v_lshlrev_b32_e32 v136, 16, v139
	v_and_b32_e32 v137, 0xffff0000, v139
	v_pk_mul_f32 v[130:131], v[130:131], v[136:137]
	v_lshlrev_b32_e32 v136, 16, v132
	v_max_f32_e32 v138, v136, v136
	global_load_dwordx4 v[134:137], v[134:135], off offset:256
	v_and_b32_e32 v132, 0xffff0000, v132
	v_max_f32_e32 v132, v132, v132
	v_max_f32_e32 v132, 0x1e3ce508, v132
	v_max_f32_e32 v138, 0x1e3ce508, v138
	v_rcp_f32_e32 v139, v132
	v_lshlrev_b32_e32 v132, 16, v133
	v_and_b32_e32 v133, 0xffff0000, v133
	v_rcp_f32_e32 v138, v138
	v_max_f32_e32 v132, v132, v132
	v_max_f32_e32 v133, v133, v133
	v_max_f32_e32 v132, 0x1e3ce508, v132
	v_max_f32_e32 v133, 0x1e3ce508, v133
	v_rcp_f32_e32 v132, v132
	v_rcp_f32_e32 v133, v133
	v_pk_mul_f32 v[24:25], v[24:25], v[130:131]
	v_lshlrev_b32_e32 v130, 16, v140
	v_and_b32_e32 v131, 0xffff0000, v140
	v_pk_mul_f32 v[130:131], v[138:139], v[130:131]
	s_add_i32 s1, s1, s0
	v_pk_mul_f32 v[130:131], v[14:15], v[130:131]
	v_lshlrev_b32_e32 v14, 16, v141
	v_and_b32_e32 v15, 0xffff0000, v141
	v_pk_mul_f32 v[14:15], v[132:133], v[14:15]
	s_waitcnt vmcnt(3)
; __device__ __forceinline__ float bf_lo(unsigned w) { return __uint_as_float(w << 16); }
; __device__ __forceinline__ float bf_hi(unsigned w) { return __uint_as_float(w & 0xffff0000u); }
;     __host__ __device__ bool next(int i, Unit& u) const {
;         const long L = (long)i * G + c; if (L >= nwg) return false;
;         int wgid = (int)L; { const int q = nwg / NXCD, r = nwg % NXCD, xcd = wgid % NXCD, off = wgid / NXCD; wgid = (xcd < r ? xcd * (q + 1) : r * (q + 1) + (xcd - r) * q) + off; }
;         const int nig = WGM * nN, gid = wgid / nig, fm = gid * WGM, gsz = (nM - fm) < WGM ? (nM - fm) : WGM;
;         u.pm = fm + ((wgid % nig) % gsz); u.pn = (wgid % nig) / gsz; return true;
;     __device__ __forceinline__ void mid(f32x4 (&acc)[2][2][4][2], const Unit& u, int wr, int wc, int fr, int fq) const {
;     ...
;             for (int m = 0; m < 4; ++m) { const size_t off = (size_t)(row0 + ai * HALF + m * 16) * 4096 + col0;
; #pragma unroll
;                 for (int bj = 0; bj < 2; ++bj) { const u32x4 ga = *(const u32x4*)(SGA + off + bj * HALF), gb = *(const u32x4*)(SGB + off + bj * HALF);
;                     const unsigned wa[4] = {ga.x, ga.y, ga.z, ga.w}, wb[4] = {gb.x, gb.y, gb.z, gb.w};
; #pragma unroll
;                     for (int p = 0; p < 4; ++p) { const float rl = bf_lo(wa[p]) * __builtin_amdgcn_rcpf(fmaxf(bf_lo(wb[p]), 1e-20f)), rh = bf_hi(wa[p]) * __builtin_amdgcn_rcpf(fmaxf(bf_hi(wb[p]), 1e-20f));
;                         acc[ai][bj][m][p >> 1][(p & 1) * 2] *= rl; acc[ai][bj][m][p >> 1][(p & 1) * 2 + 1] *= rh; } }
	v_lshlrev_b32_e32 v132, 16, v146
	v_max_f32_e32 v132, v132, v132
	v_max_f32_e32 v132, 0x1e3ce508, v132
	v_rcp_f32_e32 v138, v132
	v_and_b32_e32 v132, 0xffff0000, v146
	v_max_f32_e32 v132, v132, v132
	v_max_f32_e32 v132, 0x1e3ce508, v132
	v_rcp_f32_e32 v139, v132
	v_pk_mul_f32 v[132:133], v[16:17], v[14:15]
	v_lshlrev_b32_e32 v16, 16, v147
	v_and_b32_e32 v17, 0xffff0000, v147
	v_max_f32_e32 v16, v16, v16
	v_max_f32_e32 v17, v17, v17
	v_max_f32_e32 v16, 0x1e3ce508, v16
	v_max_f32_e32 v17, 0x1e3ce508, v17
	v_rcp_f32_e32 v16, v16
	v_rcp_f32_e32 v17, v17
	s_waitcnt vmcnt(2)
	v_lshlrev_b32_e32 v14, 16, v150
	v_and_b32_e32 v15, 0xffff0000, v150
	v_pk_mul_f32 v[14:15], v[138:139], v[14:15]
	s_mul_i32 s0, s50, s2
	v_pk_mul_f32 v[14:15], v[18:19], v[14:15]
	v_lshlrev_b32_e32 v18, 16, v151
	v_and_b32_e32 v19, 0xffff0000, v151
	v_pk_mul_f32 v[16:17], v[16:17], v[18:19]
	v_lshlrev_b32_e32 v18, 16, v148
	v_and_b32_e32 v19, 0xffff0000, v148
	v_max_f32_e32 v18, v18, v18
	v_max_f32_e32 v19, v19, v19
	v_max_f32_e32 v18, 0x1e3ce508, v18
	v_max_f32_e32 v19, 0x1e3ce508, v19
	v_rcp_f32_e32 v18, v18
	v_rcp_f32_e32 v19, v19
	v_pk_mul_f32 v[16:17], v[20:21], v[16:17]
	v_lshlrev_b32_e32 v20, 16, v152
	v_and_b32_e32 v21, 0xffff0000, v152
	v_pk_mul_f32 v[18:19], v[18:19], v[20:21]
	v_lshlrev_b32_e32 v20, 16, v149
	v_and_b32_e32 v21, 0xffff0000, v149
	v_max_f32_e32 v20, v20, v20
	v_max_f32_e32 v21, v21, v21
	v_max_f32_e32 v20, 0x1e3ce508, v20
	v_max_f32_e32 v21, 0x1e3ce508, v21
	v_rcp_f32_e32 v20, v20
	v_rcp_f32_e32 v21, v21
	v_pk_mul_f32 v[10:11], v[10:11], v[18:19]
	v_lshlrev_b32_e32 v18, 16, v153
	v_and_b32_e32 v19, 0xffff0000, v153
	v_pk_mul_f32 v[18:19], v[20:21], v[18:19]
	s_waitcnt vmcnt(1)
	v_lshlrev_b32_e32 v20, 16, v142
	v_and_b32_e32 v21, 0xffff0000, v142
	v_max_f32_e32 v20, v20, v20
	v_max_f32_e32 v21, v21, v21
	v_max_f32_e32 v20, 0x1e3ce508, v20
	v_max_f32_e32 v21, 0x1e3ce508, v21
	v_rcp_f32_e32 v20, v20
	v_rcp_f32_e32 v21, v21
	v_pk_mul_f32 v[12:13], v[12:13], v[18:19]
	s_waitcnt vmcnt(0)
	v_lshlrev_b32_e32 v18, 16, v134
	v_and_b32_e32 v19, 0xffff0000, v134
	v_pk_mul_f32 v[18:19], v[20:21], v[18:19]
	v_lshlrev_b32_e32 v20, 16, v143
	v_and_b32_e32 v21, 0xffff0000, v143
	v_max_f32_e32 v20, v20, v20
	v_max_f32_e32 v21, v21, v21
	v_max_f32_e32 v20, 0x1e3ce508, v20
	v_max_f32_e32 v21, 0x1e3ce508, v21
	v_rcp_f32_e32 v20, v20
	v_rcp_f32_e32 v21, v21
	v_pk_mul_f32 v[6:7], v[6:7], v[18:19]
	v_lshlrev_b32_e32 v18, 16, v135
	v_and_b32_e32 v19, 0xffff0000, v135
	v_pk_mul_f32 v[18:19], v[20:21], v[18:19]
	v_lshlrev_b32_e32 v20, 16, v144
	v_and_b32_e32 v21, 0xffff0000, v144
	v_max_f32_e32 v20, v20, v20
	v_max_f32_e32 v21, v21, v21
	v_max_f32_e32 v20, 0x1e3ce508, v20
	v_max_f32_e32 v21, 0x1e3ce508, v21
	v_rcp_f32_e32 v20, v20
	v_rcp_f32_e32 v21, v21
	v_pk_mul_f32 v[8:9], v[8:9], v[18:19]
	v_lshlrev_b32_e32 v18, 16, v136
	v_and_b32_e32 v19, 0xffff0000, v136
	v_pk_mul_f32 v[18:19], v[20:21], v[18:19]
	v_lshlrev_b32_e32 v20, 16, v145
	v_and_b32_e32 v21, 0xffff0000, v145
	v_max_f32_e32 v20, v20, v20
	v_max_f32_e32 v21, v21, v21
	v_max_f32_e32 v20, 0x1e3ce508, v20
	v_max_f32_e32 v21, 0x1e3ce508, v21
	v_rcp_f32_e32 v20, v20
	v_rcp_f32_e32 v21, v21
	v_pk_mul_f32 v[2:3], v[2:3], v[18:19]
	v_lshlrev_b32_e32 v18, 16, v137
	v_and_b32_e32 v19, 0xffff0000, v137
	v_pk_mul_f32 v[18:19], v[20:21], v[18:19]
	v_readlane_b32 s2, v238, 44
	v_pk_mul_f32 v[4:5], v[4:5], v[18:19]
	s_add_u32 s2, s0, s2
	s_addc_u32 s3, s1, s28
	v_cmp_gt_i64_e32 vcc, s[2:3], v[160:161]
	v_cmp_lt_i64_e64 s[0:1], s[2:3], v[158:159]
	s_cbranch_vccnz .LBB0_753
	s_ashr_i32 s3, s2, 31
	s_lshr_b32 s3, s3, 29
	s_add_i32 s4, s2, s3
	s_and_b32 s3, s4, -8
	s_sub_i32 s5, s2, s3
	s_cmp_gt_i32 s5, -1
	s_mov_b64 s[2:3], -1
	s_cbranch_scc0 .LBB0_750
	s_lshl_b32 s16, s5, 6
	s_mov_b64 s[2:3], 0

.LBB0_754:
	ds_read_b128 v[18:21], v172
	ds_read_b128 v[134:137], v172 offset:1024
	ds_read_b128 v[138:141], v172 offset:2048
	ds_read_b128 v[142:145], v172 offset:3072
	ds_read_b128 v[146:149], v173
	ds_read_b128 v[150:153], v173 offset:1024
	ds_read_b128 v[154:157], v173 offset:2048
	ds_read_b128 v[178:181], v173 offset:3072
	s_add_u32 s2, s30, 0x100
	s_addc_u32 s3, s31, 0
	s_cmp_eq_u32 s37, 60
	s_cselect_b32 s26, s33, s2
	s_cselect_b32 s27, s5, s3
	s_cselect_b32 s24, s36, s34
	s_cselect_b32 s25, s21, s35
	s_add_u32 s16, s26, 0x80
	s_addc_u32 s17, s27, 0
	s_add_u32 s30, s30, 0x100080
	s_addc_u32 s31, s31, 0
	s_mov_b32 m0, s76
	ds_read_b128 v[182:185], v174
	ds_read_b128 v[186:189], v174 offset:1024
	ds_read_b128 v[190:193], v174 offset:2048
	ds_read_b128 v[194:197], v174 offset:3072
	ds_read_b128 v[198:201], v174 offset:4096
	ds_read_b128 v[202:205], v174 offset:5120
	ds_read_b128 v[206:209], v174 offset:6144
	ds_read_b128 v[210:213], v174 offset:7168
	s_nop 0
	global_load_lds_dwordx4 v1, s[30:31]
	s_mov_b32 m0, s77
	s_nop 0
	global_load_lds_dwordx4 v165, s[30:31]
	s_waitcnt vmcnt(8)
	s_waitcnt lgkmcnt(0)
	s_setprio 1
	s_waitcnt lgkmcnt(0)
	s_barrier
	v_mfma_f32_16x16x32_bf16 v[34:37], v[18:21], v[182:185], v[34:37]
	v_mfma_f32_16x16x32_bf16 v[30:33], v[138:141], v[182:185], v[30:33]
	v_mfma_f32_16x16x32_bf16 v[46:49], v[18:21], v[190:193], v[46:49]
	v_mfma_f32_16x16x32_bf16 v[62:65], v[138:141], v[190:193], v[62:65]
	v_mfma_f32_16x16x32_bf16 v[78:81], v[18:21], v[198:201], v[78:81]
	v_mfma_f32_16x16x32_bf16 v[90:93], v[138:141], v[198:201], v[90:93]
	v_mfma_f32_16x16x32_bf16 v[106:109], v[18:21], v[206:209], v[106:109]
	v_mfma_f32_16x16x32_bf16 v[114:117], v[138:141], v[206:209], v[114:117]
	v_mfma_f32_16x16x32_bf16 v[26:29], v[146:149], v[182:185], v[26:29]
	v_mfma_f32_16x16x32_bf16 v[50:53], v[154:157], v[182:185], v[50:53]
	v_mfma_f32_16x16x32_bf16 v[58:61], v[146:149], v[190:193], v[58:61]
	v_mfma_f32_16x16x32_bf16 v[82:85], v[154:157], v[190:193], v[82:85]
	v_mfma_f32_16x16x32_bf16 v[110:113], v[146:149], v[198:201], v[110:113]
	v_mfma_f32_16x16x32_bf16 v[118:121], v[154:157], v[198:201], v[118:121]
	v_mfma_f32_16x16x32_bf16 v[122:125], v[146:149], v[206:209], v[122:125]
	v_mfma_f32_16x16x32_bf16 v[126:129], v[154:157], v[206:209], v[126:129]
	v_mfma_f32_16x16x32_bf16 v[34:37], v[134:137], v[186:189], v[34:37]
	v_mfma_f32_16x16x32_bf16 v[30:33], v[142:145], v[186:189], v[30:33]
	v_mfma_f32_16x16x32_bf16 v[46:49], v[134:137], v[194:197], v[46:49]
	v_mfma_f32_16x16x32_bf16 v[62:65], v[142:145], v[194:197], v[62:65]
	v_mfma_f32_16x16x32_bf16 v[78:81], v[134:137], v[202:205], v[78:81]
	v_mfma_f32_16x16x32_bf16 v[90:93], v[142:145], v[202:205], v[90:93]
	v_mfma_f32_16x16x32_bf16 v[106:109], v[134:137], v[210:213], v[106:109]
	v_mfma_f32_16x16x32_bf16 v[114:117], v[142:145], v[210:213], v[114:117]
	v_mfma_f32_16x16x32_bf16 v[26:29], v[150:153], v[186:189], v[26:29]
	v_mfma_f32_16x16x32_bf16 v[50:53], v[178:181], v[186:189], v[50:53]
	v_mfma_f32_16x16x32_bf16 v[58:61], v[150:153], v[194:197], v[58:61]
	v_mfma_f32_16x16x32_bf16 v[82:85], v[178:181], v[194:197], v[82:85]
	v_mfma_f32_16x16x32_bf16 v[110:113], v[150:153], v[202:205], v[110:113]
	v_mfma_f32_16x16x32_bf16 v[118:121], v[178:181], v[202:205], v[118:121]
	v_mfma_f32_16x16x32_bf16 v[122:125], v[150:153], v[210:213], v[122:125]
	v_mfma_f32_16x16x32_bf16 v[126:129], v[178:181], v[210:213], v[126:129]
	s_barrier
	s_setprio 0
	s_mov_b32 m0, s80
	s_mov_b64 s[30:31], s[24:25]
	ds_read_b128 v[182:185], v174 offset:16384
	ds_read_b128 v[186:189], v174 offset:17408
	ds_read_b128 v[190:193], v174 offset:18432
	ds_read_b128 v[194:197], v174 offset:19456
	ds_read_b128 v[198:201], v174 offset:20480
	ds_read_b128 v[202:205], v174 offset:21504
	ds_read_b128 v[206:209], v174 offset:22528
	ds_read_b128 v[210:213], v174 offset:23552
	s_nop 0
	global_load_lds_dwordx4 v164, s[30:31]
	s_mov_b32 m0, s81
	s_nop 0
	global_load_lds_dwordx4 v166, s[30:31]
	s_add_u32 s30, s24, 0x100000
	s_addc_u32 s31, s25, 0
	s_mov_b32 m0, s82
	s_nop 0
	global_load_lds_dwordx4 v164, s[30:31]
	s_mov_b32 m0, s83
	s_nop 0
	global_load_lds_dwordx4 v166, s[30:31]
	s_mov_b64 s[30:31], s[26:27]
	s_mov_b32 m0, s46
	s_nop 0
	global_load_lds_dwordx4 v1, s[30:31]
	s_mov_b32 m0, s47
	s_nop 0
	global_load_lds_dwordx4 v165, s[30:31]
	s_waitcnt vmcnt(8)
	s_waitcnt lgkmcnt(0)
	s_setprio 1
	s_waitcnt lgkmcnt(0)
	s_barrier
	v_mfma_f32_16x16x32_bf16 v[102:105], v[18:21], v[182:185], v[102:105]
	v_mfma_f32_16x16x32_bf16 v[98:101], v[138:141], v[182:185], v[98:101]
	v_mfma_f32_16x16x32_bf16 v[74:77], v[18:21], v[190:193], v[74:77]
	v_mfma_f32_16x16x32_bf16 v[70:73], v[138:141], v[190:193], v[70:73]
	v_mfma_f32_16x16x32_bf16 v[42:45], v[18:21], v[198:201], v[42:45]
	v_mfma_f32_16x16x32_bf16 v[38:41], v[138:141], v[198:201], v[38:41]
	v_mfma_f32_16x16x32_bf16 v[14:17], v[18:21], v[206:209], v[14:17]
	v_mfma_f32_16x16x32_bf16 v[10:13], v[138:141], v[206:209], v[10:13]
	v_mfma_f32_16x16x32_bf16 v[18:21], v[146:149], v[182:185], v[94:97]
	v_mfma_f32_16x16x32_bf16 v[86:89], v[154:157], v[182:185], v[86:89]
	v_mfma_f32_16x16x32_bf16 v[66:69], v[146:149], v[190:193], v[66:69]
	v_mfma_f32_16x16x32_bf16 v[54:57], v[154:157], v[190:193], v[54:57]
	v_mfma_f32_16x16x32_bf16 v[22:25], v[146:149], v[198:201], v[22:25]
	v_mfma_f32_16x16x32_bf16 v[94:97], v[154:157], v[198:201], v[130:133]
	v_mfma_f32_16x16x32_bf16 v[6:9], v[146:149], v[206:209], v[6:9]
	v_mfma_f32_16x16x32_bf16 v[2:5], v[154:157], v[206:209], v[2:5]
	v_mfma_f32_16x16x32_bf16 v[102:105], v[134:137], v[186:189], v[102:105]
	v_mfma_f32_16x16x32_bf16 v[98:101], v[142:145], v[186:189], v[98:101]
	v_mfma_f32_16x16x32_bf16 v[74:77], v[134:137], v[194:197], v[74:77]
	v_mfma_f32_16x16x32_bf16 v[70:73], v[142:145], v[194:197], v[70:73]
	v_mfma_f32_16x16x32_bf16 v[42:45], v[134:137], v[202:205], v[42:45]
	v_mfma_f32_16x16x32_bf16 v[38:41], v[142:145], v[202:205], v[38:41]
	v_mfma_f32_16x16x32_bf16 v[14:17], v[134:137], v[210:213], v[14:17]
	v_mfma_f32_16x16x32_bf16 v[10:13], v[142:145], v[210:213], v[10:13]
	v_mfma_f32_16x16x32_bf16 v[86:89], v[178:181], v[186:189], v[86:89]
	v_mfma_f32_16x16x32_bf16 v[66:69], v[150:153], v[194:197], v[66:69]
	v_mfma_f32_16x16x32_bf16 v[54:57], v[178:181], v[194:197], v[54:57]
	v_mfma_f32_16x16x32_bf16 v[22:25], v[150:153], v[202:205], v[22:25]
	v_mfma_f32_16x16x32_bf16 v[130:133], v[178:181], v[202:205], v[94:97]
	v_mfma_f32_16x16x32_bf16 v[6:9], v[150:153], v[210:213], v[6:9]
	v_mfma_f32_16x16x32_bf16 v[2:5], v[178:181], v[210:213], v[2:5]
	v_mfma_f32_16x16x32_bf16 v[18:21], v[150:153], v[186:189], v[18:21]
	s_barrier
; #define PG8_BAR __builtin_amdgcn_s_barrier()
; #define PG8_BAR __builtin_amdgcn_s_barrier()
; template <class Epi, class Sched>
; __device__ __forceinline__ void gemm_phase_dual(PG8_LAS unsigned char* lds, const Gemm g  , const bf16_t* A0, const bf16_t* Bt0, int K0, const Sched& S, const Epi& E) {
;     ...
;         if (wr == 0) PG8_BAR;
	s_setprio 0
	ds_read_b128 v[94:97], v175
	ds_read_b128 v[134:137], v175 offset:1024
	ds_read_b128 v[138:141], v175 offset:2048
	ds_read_b128 v[142:145], v175 offset:3072
	ds_read_b128 v[146:149], v176
	ds_read_b128 v[150:153], v176 offset:1024
	ds_read_b128 v[154:157], v176 offset:2048
	ds_read_b128 v[178:181], v176 offset:3072
	s_add_u32 s26, s26, 0x100000
	s_addc_u32 s27, s27, 0
	s_mov_b32 m0, s48
	ds_read_b128 v[182:185], v174 offset:32768
	ds_read_b128 v[186:189], v174 offset:33792
	ds_read_b128 v[190:193], v174 offset:34816
	ds_read_b128 v[194:197], v174 offset:35840
	ds_read_b128 v[198:201], v174 offset:36864
	ds_read_b128 v[202:205], v174 offset:37888
	ds_read_b128 v[206:209], v174 offset:38912
	ds_read_b128 v[210:213], v174 offset:39936
	s_nop 0
	global_load_lds_dwordx4 v1, s[26:27]
	s_mov_b32 m0, s49
	s_nop 0
	global_load_lds_dwordx4 v165, s[26:27]
	s_waitcnt vmcnt(8)
	s_waitcnt lgkmcnt(0)
	s_setprio 1
	s_waitcnt lgkmcnt(0)
	s_barrier
	v_mfma_f32_16x16x32_bf16 v[34:37], v[94:97], v[182:185], v[34:37]
	v_mfma_f32_16x16x32_bf16 v[30:33], v[138:141], v[182:185], v[30:33]
	v_mfma_f32_16x16x32_bf16 v[46:49], v[94:97], v[190:193], v[46:49]
	v_mfma_f32_16x16x32_bf16 v[62:65], v[138:141], v[190:193], v[62:65]
	v_mfma_f32_16x16x32_bf16 v[78:81], v[94:97], v[198:201], v[78:81]
	v_mfma_f32_16x16x32_bf16 v[90:93], v[138:141], v[198:201], v[90:93]
	v_mfma_f32_16x16x32_bf16 v[106:109], v[94:97], v[206:209], v[106:109]
	v_mfma_f32_16x16x32_bf16 v[114:117], v[138:141], v[206:209], v[114:117]
	v_mfma_f32_16x16x32_bf16 v[26:29], v[146:149], v[182:185], v[26:29]
	v_mfma_f32_16x16x32_bf16 v[50:53], v[154:157], v[182:185], v[50:53]
	v_mfma_f32_16x16x32_bf16 v[58:61], v[146:149], v[190:193], v[58:61]
	v_mfma_f32_16x16x32_bf16 v[82:85], v[154:157], v[190:193], v[82:85]
	v_mfma_f32_16x16x32_bf16 v[110:113], v[146:149], v[198:201], v[110:113]
	v_mfma_f32_16x16x32_bf16 v[118:121], v[154:157], v[198:201], v[118:121]
	v_mfma_f32_16x16x32_bf16 v[122:125], v[146:149], v[206:209], v[122:125]
	v_mfma_f32_16x16x32_bf16 v[126:129], v[154:157], v[206:209], v[126:129]
	v_mfma_f32_16x16x32_bf16 v[34:37], v[134:137], v[186:189], v[34:37]
	v_mfma_f32_16x16x32_bf16 v[30:33], v[142:145], v[186:189], v[30:33]
	v_mfma_f32_16x16x32_bf16 v[46:49], v[134:137], v[194:197], v[46:49]
	v_mfma_f32_16x16x32_bf16 v[62:65], v[142:145], v[194:197], v[62:65]
	v_mfma_f32_16x16x32_bf16 v[78:81], v[134:137], v[202:205], v[78:81]
	v_mfma_f32_16x16x32_bf16 v[90:93], v[142:145], v[202:205], v[90:93]
	v_mfma_f32_16x16x32_bf16 v[106:109], v[134:137], v[210:213], v[106:109]
	v_mfma_f32_16x16x32_bf16 v[114:117], v[142:145], v[210:213], v[114:117]
	v_mfma_f32_16x16x32_bf16 v[26:29], v[150:153], v[186:189], v[26:29]
	v_mfma_f32_16x16x32_bf16 v[50:53], v[178:181], v[186:189], v[50:53]
	v_mfma_f32_16x16x32_bf16 v[58:61], v[150:153], v[194:197], v[58:61]
	v_mfma_f32_16x16x32_bf16 v[82:85], v[178:181], v[194:197], v[82:85]
	v_mfma_f32_16x16x32_bf16 v[110:113], v[150:153], v[202:205], v[110:113]
	v_mfma_f32_16x16x32_bf16 v[118:121], v[178:181], v[202:205], v[118:121]
	v_mfma_f32_16x16x32_bf16 v[122:125], v[150:153], v[210:213], v[122:125]
	v_mfma_f32_16x16x32_bf16 v[126:129], v[178:181], v[210:213], v[126:129]
	s_barrier
	s_setprio 0
	s_add_u32 s26, s24, 0x80
	s_mov_b32 m0, s84
	s_addc_u32 s27, s25, 0
	ds_read_b128 v[182:185], v174 offset:49152
	ds_read_b128 v[186:189], v174 offset:50176
	ds_read_b128 v[190:193], v174 offset:51200
	ds_read_b128 v[194:197], v174 offset:52224
	ds_read_b128 v[198:201], v174 offset:53248
	ds_read_b128 v[202:205], v174 offset:54272
	ds_read_b128 v[206:209], v174 offset:55296
	ds_read_b128 v[210:213], v174 offset:56320
	s_add_u32 s24, s24, 0x100080
	global_load_lds_dwordx4 v164, s[26:27]
	s_mov_b32 m0, s85
	s_addc_u32 s25, s25, 0
	global_load_lds_dwordx4 v166, s[26:27]
	s_mov_b32 m0, s86
	s_nop 0
	global_load_lds_dwordx4 v164, s[24:25]
	s_mov_b32 m0, s87
	s_nop 0
	global_load_lds_dwordx4 v166, s[24:25]
	s_mov_b32 m0, s57
	s_nop 0
	global_load_lds_dwordx4 v1, s[16:17]
	s_mov_b32 m0, s62
	s_nop 0
	global_load_lds_dwordx4 v165, s[16:17]
	s_waitcnt vmcnt(8)
	s_waitcnt lgkmcnt(0)
	s_setprio 1
	s_waitcnt lgkmcnt(0)
	s_barrier
	v_mfma_f32_16x16x32_bf16 v[18:21], v[146:149], v[182:185], v[18:21]
	v_mfma_f32_16x16x32_bf16 v[102:105], v[94:97], v[182:185], v[102:105]
	v_mfma_f32_16x16x32_bf16 v[74:77], v[94:97], v[190:193], v[74:77]
	v_mfma_f32_16x16x32_bf16 v[42:45], v[94:97], v[198:201], v[42:45]
	v_mfma_f32_16x16x32_bf16 v[14:17], v[94:97], v[206:209], v[14:17]
	v_mfma_f32_16x16x32_bf16 v[94:97], v[150:153], v[186:189], v[18:21]
	v_mfma_f32_16x16x32_bf16 v[18:21], v[154:157], v[182:185], v[86:89]
	v_mfma_f32_16x16x32_bf16 v[86:89], v[178:181], v[186:189], v[18:21]
	v_mfma_f32_16x16x32_bf16 v[18:21], v[146:149], v[190:193], v[66:69]
	v_mfma_f32_16x16x32_bf16 v[66:69], v[150:153], v[194:197], v[18:21]
	v_mfma_f32_16x16x32_bf16 v[18:21], v[154:157], v[190:193], v[54:57]
	v_mfma_f32_16x16x32_bf16 v[54:57], v[178:181], v[194:197], v[18:21]
	v_mfma_f32_16x16x32_bf16 v[18:21], v[146:149], v[198:201], v[22:25]
	v_mfma_f32_16x16x32_bf16 v[98:101], v[138:141], v[182:185], v[98:101]
	v_mfma_f32_16x16x32_bf16 v[70:73], v[138:141], v[190:193], v[70:73]
	v_mfma_f32_16x16x32_bf16 v[38:41], v[138:141], v[198:201], v[38:41]
	v_mfma_f32_16x16x32_bf16 v[10:13], v[138:141], v[206:209], v[10:13]
	v_mfma_f32_16x16x32_bf16 v[22:25], v[150:153], v[202:205], v[18:21]
	v_mfma_f32_16x16x32_bf16 v[18:21], v[154:157], v[198:201], v[130:133]
	v_mfma_f32_16x16x32_bf16 v[6:9], v[146:149], v[206:209], v[6:9]
	v_mfma_f32_16x16x32_bf16 v[2:5], v[154:157], v[206:209], v[2:5]
	v_mfma_f32_16x16x32_bf16 v[102:105], v[134:137], v[186:189], v[102:105]
	v_mfma_f32_16x16x32_bf16 v[98:101], v[142:145], v[186:189], v[98:101]
	v_mfma_f32_16x16x32_bf16 v[74:77], v[134:137], v[194:197], v[74:77]
	v_mfma_f32_16x16x32_bf16 v[70:73], v[142:145], v[194:197], v[70:73]
	v_mfma_f32_16x16x32_bf16 v[42:45], v[134:137], v[202:205], v[42:45]
	v_mfma_f32_16x16x32_bf16 v[38:41], v[142:145], v[202:205], v[38:41]
	v_mfma_f32_16x16x32_bf16 v[14:17], v[134:137], v[210:213], v[14:17]
	v_mfma_f32_16x16x32_bf16 v[10:13], v[142:145], v[210:213], v[10:13]
	v_mfma_f32_16x16x32_bf16 v[130:133], v[178:181], v[202:205], v[18:21]
	v_mfma_f32_16x16x32_bf16 v[6:9], v[150:153], v[210:213], v[6:9]
	v_mfma_f32_16x16x32_bf16 v[2:5], v[178:181], v[210:213], v[2:5]
	s_barrier
	s_setprio 0
	s_add_i32 s37, s37, 2
	s_add_u32 s34, s34, 0x100
	s_addc_u32 s35, s35, 0
	s_cmp_gt_u32 s37, 61
	s_mov_b64 s[30:31], s[2:3]
	s_cbranch_scc0 .LBB0_754
	s_and_b64 vcc, exec, s[18:19]
	s_cbranch_vccz .LBB0_757
	s_barrier

; #define PG8_STAGE(bufoff, gbase, voff) do { const char* _gb = (const char*)(gbase); asm volatile("" : "+s"(_gb)); _Pragma("unroll") for (int _i = 0; _i < 2; ++_i) { asm volatile("" : "+v"((voff)[_i])); \
;         __builtin_amdgcn_global_load_lds((const unsigned*)(_gb + (voff)[_i]), (PG8_LAS unsigned*)(lds + (bufoff) + ldsw + _i * 8192), 16, 0, 0); } } while (0)
; #define PG8_LDA(dst, b, h) do { _Pragma("unroll") for (int m = 0; m < 4; ++m) _Pragma("unroll") for (int k = 0; k < 2; ++k) dst[m][k] = *(const PG8_LAS bf16x8*)(lds + PG8_SA(b, h) + aoff + m * 2048 + k * 1024); } while (0)
; #define PG8_LDB(dst, b, h) do { _Pragma("unroll") for (int n = 0; n < 2; ++n) _Pragma("unroll") for (int k = 0; k < 2; ++k) dst[n][k] = *(const PG8_LAS bf16x8*)(lds + PG8_SB(b, h) + boff + n * 2048 + k * 1024); } while (0)
; #define PG8_WAIT_V(n) asm volatile("s_waitcnt vmcnt(" #n ")" ::: "memory")
; #define PG8_WAIT_L(n) asm volatile("s_waitcnt lgkmcnt(" #n ")" ::: "memory")
; #define PG8_BAR __builtin_amdgcn_s_barrier()
; #define PG8_SCHED __builtin_amdgcn_sched_barrier(0)
; #define PG8_LDA(dst, b, h) do { _Pragma("unroll") for (int m = 0; m < 4; ++m) _Pragma("unroll") for (int k = 0; k < 2; ++k) dst[m][k] = *(const PG8_LAS bf16x8*)(lds + PG8_SA(b, h) + aoff + m * 2048 + k * 1024); } while (0)
; template <class Epi, class Sched, bool ALIGN_EPI = false, bool SP2 = false>
; __device__ __forceinline__ void gemm_phase(PG8_LAS unsigned char* lds, const Gemm g, const Sched& S, const Epi& E) {
;     ...
;             PG8_LDB(B0, 0, 0); PG8_LDB(B1, 0, 1); PG8_SCHED; PG8_LDA(At, 0, 0); PG8_STAGE(PG8_SA(1, 1), a1 + hstep, voffA);
;             PG8_WAIT_V(8); PG8_WAIT_L(0); PG8_BAR; PG8_MMA2(0); PG8_BAR; PG8_SCHED;
;             PG8_LDA(At, 0, 1); PG8_STAGE(PG8_SB(0, 0), b2, voffB); PG8_STAGE(PG8_SB(0, 1), b2 + hstep, voffB); PG8_STAGE(PG8_SA(0, 0), a2, voffA);
;             PG8_WAIT_V(8); PG8_WAIT_L(0); PG8_BAR; PG8_MMA2(1); PG8_BAR; PG8_SCHED;
;             PG8_LDB(B0, 1, 0); PG8_LDB(B1, 1, 1); PG8_SCHED; PG8_LDA(At, 1, 0); PG8_STAGE(PG8_SA(0, 1), a2 + hstep, voffA);
;             PG8_WAIT_V(8); PG8_WAIT_L(0); PG8_BAR; PG8_MMA2(0); PG8_BAR; PG8_SCHED;
;             PG8_LDA(At, 1, 1); PG8_STAGE(PG8_SB(1, 0), b3, voffB); PG8_STAGE(PG8_SB(1, 1), b3 + hstep, voffB); PG8_STAGE(PG8_SA(1, 0), a3, voffA);
;             PG8_WAIT_V(8); PG8_WAIT_L(0); PG8_BAR; PG8_MMA2(1); PG8_BAR; PG8_SCHED;
.LBB0_833:
	ds_read_b128 v[130:133], v180
	ds_read_b128 v[134:137], v180 offset:1024
	ds_read_b128 v[138:141], v180 offset:2048
	ds_read_b128 v[142:145], v180 offset:3072
	ds_read_b128 v[146:149], v181
	ds_read_b128 v[150:153], v181 offset:1024
	ds_read_b128 v[154:157], v181 offset:2048
	ds_read_b128 v[158:161], v181 offset:3072
	s_add_u32 s24, s16, 0x100
	s_addc_u32 s25, s17, 0
	s_cmp_eq_u32 s87, 60
	s_cselect_b32 s28, s83, s24
	s_cselect_b32 s29, s55, s25
	s_cselect_b32 s26, s84, s85
	s_cselect_b32 s27, s53, s86
	s_add_u32 s2, s28, 0x80
	s_addc_u32 s3, s29, 0
	s_add_u32 s16, s16, 0x100080
	s_addc_u32 s17, s17, 0
	s_add_i32 m0, s69, 0xc000
	ds_read_b128 v[166:169], v182
	ds_read_b128 v[170:173], v182 offset:1024
	ds_read_b128 v[184:187], v182 offset:2048
	ds_read_b128 v[188:191], v182 offset:3072
	ds_read_b128 v[192:195], v182 offset:4096
	ds_read_b128 v[196:199], v182 offset:5120
	ds_read_b128 v[200:203], v182 offset:6144
	ds_read_b128 v[204:207], v182 offset:7168
	s_nop 0
	global_load_lds_dwordx4 v1, s[16:17]
	s_add_i32 m0, s69, 0xe000
	s_nop 0
	global_load_lds_dwordx4 v175, s[16:17]
	s_waitcnt vmcnt(8)
	s_waitcnt lgkmcnt(0)
	s_setprio 1
	s_waitcnt lgkmcnt(0)
	s_barrier
	v_mfma_f32_16x16x32_bf16 v[126:129], v[130:133], v[166:169], v[126:129]
	v_mfma_f32_16x16x32_bf16 v[122:125], v[138:141], v[166:169], v[122:125]
	v_mfma_f32_16x16x32_bf16 v[110:113], v[130:133], v[184:187], v[110:113]
	v_mfma_f32_16x16x32_bf16 v[106:109], v[138:141], v[184:187], v[106:109]
	v_mfma_f32_16x16x32_bf16 v[94:97], v[130:133], v[192:195], v[94:97]
	v_mfma_f32_16x16x32_bf16 v[90:93], v[138:141], v[192:195], v[90:93]
	v_mfma_f32_16x16x32_bf16 v[78:81], v[130:133], v[200:203], v[78:81]
	v_mfma_f32_16x16x32_bf16 v[74:77], v[138:141], v[200:203], v[74:77]
	v_mfma_f32_16x16x32_bf16 v[118:121], v[146:149], v[166:169], v[118:121]
	v_mfma_f32_16x16x32_bf16 v[114:117], v[154:157], v[166:169], v[114:117]
	v_mfma_f32_16x16x32_bf16 v[102:105], v[146:149], v[184:187], v[102:105]
	v_mfma_f32_16x16x32_bf16 v[98:101], v[154:157], v[184:187], v[98:101]
	v_mfma_f32_16x16x32_bf16 v[86:89], v[146:149], v[192:195], v[86:89]
	v_mfma_f32_16x16x32_bf16 v[82:85], v[154:157], v[192:195], v[82:85]
	v_mfma_f32_16x16x32_bf16 v[70:73], v[146:149], v[200:203], v[70:73]
	v_mfma_f32_16x16x32_bf16 v[66:69], v[154:157], v[200:203], v[66:69]
	v_mfma_f32_16x16x32_bf16 v[126:129], v[134:137], v[170:173], v[126:129]
	v_mfma_f32_16x16x32_bf16 v[122:125], v[142:145], v[170:173], v[122:125]
	v_mfma_f32_16x16x32_bf16 v[110:113], v[134:137], v[188:191], v[110:113]
	v_mfma_f32_16x16x32_bf16 v[106:109], v[142:145], v[188:191], v[106:109]
	v_mfma_f32_16x16x32_bf16 v[94:97], v[134:137], v[196:199], v[94:97]
	v_mfma_f32_16x16x32_bf16 v[90:93], v[142:145], v[196:199], v[90:93]
	v_mfma_f32_16x16x32_bf16 v[78:81], v[134:137], v[204:207], v[78:81]
	v_mfma_f32_16x16x32_bf16 v[74:77], v[142:145], v[204:207], v[74:77]
	v_mfma_f32_16x16x32_bf16 v[118:121], v[150:153], v[170:173], v[118:121]
	v_mfma_f32_16x16x32_bf16 v[114:117], v[158:161], v[170:173], v[114:117]
	v_mfma_f32_16x16x32_bf16 v[102:105], v[150:153], v[188:191], v[102:105]
	v_mfma_f32_16x16x32_bf16 v[98:101], v[158:161], v[188:191], v[98:101]
	v_mfma_f32_16x16x32_bf16 v[86:89], v[150:153], v[196:199], v[86:89]
	v_mfma_f32_16x16x32_bf16 v[82:85], v[158:161], v[196:199], v[82:85]
	v_mfma_f32_16x16x32_bf16 v[70:73], v[150:153], v[204:207], v[70:73]
	v_mfma_f32_16x16x32_bf16 v[66:69], v[158:161], v[204:207], v[66:69]
	s_barrier
	s_setprio 0
	s_add_i32 s88, s81, s73
	s_mov_b64 s[16:17], s[26:27]
	s_mov_b32 m0, s88
	ds_read_b128 v[166:169], v182 offset:16384
	ds_read_b128 v[170:173], v182 offset:17408
	ds_read_b128 v[184:187], v182 offset:18432
	ds_read_b128 v[188:191], v182 offset:19456
	ds_read_b128 v[192:195], v182 offset:20480
	ds_read_b128 v[196:199], v182 offset:21504
	ds_read_b128 v[200:203], v182 offset:22528
	ds_read_b128 v[204:207], v182 offset:23552
	s_nop 0
	global_load_lds_dwordx4 v174, s[16:17]
	s_add_i32 m0, s88, 0x2000
	s_nop 0
	global_load_lds_dwordx4 v176, s[16:17]
	s_add_u32 s16, s26, 0x100000
	s_addc_u32 s17, s27, 0
	s_add_i32 s88, s82, s73
	s_mov_b32 m0, s88
	s_nop 0
	global_load_lds_dwordx4 v174, s[16:17]
	s_add_i32 m0, s88, 0x2000
	s_nop 0
	global_load_lds_dwordx4 v176, s[16:17]
	s_mov_b64 s[16:17], s[28:29]
	s_mov_b32 m0, s69
	s_nop 0
	global_load_lds_dwordx4 v1, s[16:17]
	s_mov_b32 m0, s71
	s_nop 0
	global_load_lds_dwordx4 v175, s[16:17]
	s_waitcnt vmcnt(8)
	s_waitcnt lgkmcnt(0)
	s_setprio 1
	s_waitcnt lgkmcnt(0)
	s_barrier
	v_mfma_f32_16x16x32_bf16 v[62:65], v[130:133], v[166:169], v[62:65]
	v_mfma_f32_16x16x32_bf16 v[58:61], v[138:141], v[166:169], v[58:61]
	v_mfma_f32_16x16x32_bf16 v[46:49], v[130:133], v[184:187], v[46:49]
	v_mfma_f32_16x16x32_bf16 v[42:45], v[138:141], v[184:187], v[42:45]
	v_mfma_f32_16x16x32_bf16 v[30:33], v[130:133], v[192:195], v[30:33]
	v_mfma_f32_16x16x32_bf16 v[26:29], v[138:141], v[192:195], v[26:29]
	v_mfma_f32_16x16x32_bf16 v[14:17], v[130:133], v[200:203], v[14:17]
	v_mfma_f32_16x16x32_bf16 v[10:13], v[138:141], v[200:203], v[10:13]
	v_mfma_f32_16x16x32_bf16 v[54:57], v[146:149], v[166:169], v[54:57]
	v_mfma_f32_16x16x32_bf16 v[50:53], v[154:157], v[166:169], v[50:53]
	v_mfma_f32_16x16x32_bf16 v[38:41], v[146:149], v[184:187], v[38:41]
	v_mfma_f32_16x16x32_bf16 v[34:37], v[154:157], v[184:187], v[34:37]
	v_mfma_f32_16x16x32_bf16 v[22:25], v[146:149], v[192:195], v[22:25]
	v_mfma_f32_16x16x32_bf16 v[18:21], v[154:157], v[192:195], v[18:21]
	v_mfma_f32_16x16x32_bf16 v[6:9], v[146:149], v[200:203], v[6:9]
	v_mfma_f32_16x16x32_bf16 v[2:5], v[154:157], v[200:203], v[2:5]
	v_mfma_f32_16x16x32_bf16 v[62:65], v[134:137], v[170:173], v[62:65]
	v_mfma_f32_16x16x32_bf16 v[58:61], v[142:145], v[170:173], v[58:61]
	v_mfma_f32_16x16x32_bf16 v[46:49], v[134:137], v[188:191], v[46:49]
	v_mfma_f32_16x16x32_bf16 v[42:45], v[142:145], v[188:191], v[42:45]
	v_mfma_f32_16x16x32_bf16 v[30:33], v[134:137], v[196:199], v[30:33]
	v_mfma_f32_16x16x32_bf16 v[26:29], v[142:145], v[196:199], v[26:29]
	v_mfma_f32_16x16x32_bf16 v[14:17], v[134:137], v[204:207], v[14:17]
	v_mfma_f32_16x16x32_bf16 v[10:13], v[142:145], v[204:207], v[10:13]
	v_mfma_f32_16x16x32_bf16 v[54:57], v[150:153], v[170:173], v[54:57]
	v_mfma_f32_16x16x32_bf16 v[50:53], v[158:161], v[170:173], v[50:53]
	v_mfma_f32_16x16x32_bf16 v[38:41], v[150:153], v[188:191], v[38:41]
	v_mfma_f32_16x16x32_bf16 v[34:37], v[158:161], v[188:191], v[34:37]
	v_mfma_f32_16x16x32_bf16 v[22:25], v[150:153], v[196:199], v[22:25]
	v_mfma_f32_16x16x32_bf16 v[18:21], v[158:161], v[196:199], v[18:21]
	v_mfma_f32_16x16x32_bf16 v[6:9], v[150:153], v[204:207], v[6:9]
	v_mfma_f32_16x16x32_bf16 v[2:5], v[158:161], v[204:207], v[2:5]
	s_barrier
; #define PG8_STAGE(bufoff, gbase, voff) do { const char* _gb = (const char*)(gbase); asm volatile("" : "+s"(_gb)); _Pragma("unroll") for (int _i = 0; _i < 2; ++_i) { asm volatile("" : "+v"((voff)[_i])); \
;         __builtin_amdgcn_global_load_lds((const unsigned*)(_gb + (voff)[_i]), (PG8_LAS unsigned*)(lds + (bufoff) + ldsw + _i * 8192), 16, 0, 0); } } while (0)
; #define PG8_LDA(dst, b, h) do { _Pragma("unroll") for (int m = 0; m < 4; ++m) _Pragma("unroll") for (int k = 0; k < 2; ++k) dst[m][k] = *(const PG8_LAS bf16x8*)(lds + PG8_SA(b, h) + aoff + m * 2048 + k * 1024); } while (0)
; #define PG8_LDB(dst, b, h) do { _Pragma("unroll") for (int n = 0; n < 2; ++n) _Pragma("unroll") for (int k = 0; k < 2; ++k) dst[n][k] = *(const PG8_LAS bf16x8*)(lds + PG8_SB(b, h) + boff + n * 2048 + k * 1024); } while (0)
; #define PG8_WAIT_V(n) asm volatile("s_waitcnt vmcnt(" #n ")" ::: "memory")
; #define PG8_WAIT_L(n) asm volatile("s_waitcnt lgkmcnt(" #n ")" ::: "memory")
; #define PG8_BAR __builtin_amdgcn_s_barrier()
; #define PG8_SCHED __builtin_amdgcn_sched_barrier(0)
; #define PG8_WAIT_V(n) asm volatile("s_waitcnt vmcnt(" #n ")" ::: "memory")
; #define PG8_WAIT_L(n) asm volatile("s_waitcnt lgkmcnt(" #n ")" ::: "memory")
; template <class Epi, class Sched, bool ALIGN_EPI = false, bool SP2 = false>
; __device__ __forceinline__ void gemm_phase(PG8_LAS unsigned char* lds, const Gemm g, const Sched& S, const Epi& E) {
;     ...
;             PG8_LDB(B0, 0, 0); PG8_LDB(B1, 0, 1); PG8_SCHED; PG8_LDA(At, 0, 0); PG8_STAGE(PG8_SA(1, 1), a1 + hstep, voffA);
;             PG8_WAIT_V(8); PG8_WAIT_L(0); PG8_BAR; PG8_MMA2(0); PG8_BAR; PG8_SCHED;
;             PG8_LDA(At, 0, 1); PG8_STAGE(PG8_SB(0, 0), b2, voffB); PG8_STAGE(PG8_SB(0, 1), b2 + hstep, voffB); PG8_STAGE(PG8_SA(0, 0), a2, voffA);
;             PG8_WAIT_V(8); PG8_WAIT_L(0); PG8_BAR; PG8_MMA2(1); PG8_BAR; PG8_SCHED;
;             PG8_LDB(B0, 1, 0); PG8_LDB(B1, 1, 1); PG8_SCHED; PG8_LDA(At, 1, 0); PG8_STAGE(PG8_SA(0, 1), a2 + hstep, voffA);
;             PG8_WAIT_V(8); PG8_WAIT_L(0); PG8_BAR; PG8_MMA2(0); PG8_BAR; PG8_SCHED;
;             PG8_LDA(At, 1, 1); PG8_STAGE(PG8_SB(1, 0), b3, voffB); PG8_STAGE(PG8_SB(1, 1), b3 + hstep, voffB); PG8_STAGE(PG8_SA(1, 0), a3, voffA);
;             PG8_WAIT_V(8); PG8_WAIT_L(0); PG8_BAR; PG8_MMA2(1); PG8_BAR; PG8_SCHED;
;     ...
;         if constexpr (ALIGN_EPI) { if (wr == 0) PG8_BAR; }
	s_setprio 0
	s_add_i32 s88, 0, 0x18000
	s_add_i32 s89, 0, 0x1c000
	v_add_u32_e32 v142, s88, v178
	v_add_u32_e32 v158, s89, v178
	ds_read_b128 v[130:133], v142
	ds_read_b128 v[134:137], v142 offset:1024
	ds_read_b128 v[138:141], v142 offset:2048
	ds_read_b128 v[142:145], v142 offset:3072
	ds_read_b128 v[146:149], v158
	ds_read_b128 v[150:153], v158 offset:1024
	ds_read_b128 v[154:157], v158 offset:2048
	ds_read_b128 v[158:161], v158 offset:3072
	s_add_u32 s16, s28, 0x100000
	s_addc_u32 s17, s29, 0
	s_mov_b32 m0, s74
	ds_read_b128 v[166:169], v182 offset:32768
	ds_read_b128 v[170:173], v182 offset:33792
	ds_read_b128 v[184:187], v182 offset:34816
	ds_read_b128 v[188:191], v182 offset:35840
	ds_read_b128 v[192:195], v182 offset:36864
	ds_read_b128 v[196:199], v182 offset:37888
	ds_read_b128 v[200:203], v182 offset:38912
	ds_read_b128 v[204:207], v182 offset:39936
	s_nop 0
	global_load_lds_dwordx4 v1, s[16:17]
	s_mov_b32 m0, s75
	s_nop 0
	global_load_lds_dwordx4 v175, s[16:17]
	s_waitcnt vmcnt(8)
	s_waitcnt lgkmcnt(0)
	s_setprio 1
	s_waitcnt lgkmcnt(0)
	s_barrier
	v_mfma_f32_16x16x32_bf16 v[126:129], v[130:133], v[166:169], v[126:129]
	v_mfma_f32_16x16x32_bf16 v[122:125], v[138:141], v[166:169], v[122:125]
	v_mfma_f32_16x16x32_bf16 v[110:113], v[130:133], v[184:187], v[110:113]
	v_mfma_f32_16x16x32_bf16 v[106:109], v[138:141], v[184:187], v[106:109]
	v_mfma_f32_16x16x32_bf16 v[94:97], v[130:133], v[192:195], v[94:97]
	v_mfma_f32_16x16x32_bf16 v[90:93], v[138:141], v[192:195], v[90:93]
	v_mfma_f32_16x16x32_bf16 v[78:81], v[130:133], v[200:203], v[78:81]
	v_mfma_f32_16x16x32_bf16 v[74:77], v[138:141], v[200:203], v[74:77]
	v_mfma_f32_16x16x32_bf16 v[118:121], v[146:149], v[166:169], v[118:121]
	v_mfma_f32_16x16x32_bf16 v[114:117], v[154:157], v[166:169], v[114:117]
	v_mfma_f32_16x16x32_bf16 v[102:105], v[146:149], v[184:187], v[102:105]
	v_mfma_f32_16x16x32_bf16 v[98:101], v[154:157], v[184:187], v[98:101]
	v_mfma_f32_16x16x32_bf16 v[86:89], v[146:149], v[192:195], v[86:89]
	v_mfma_f32_16x16x32_bf16 v[82:85], v[154:157], v[192:195], v[82:85]
	v_mfma_f32_16x16x32_bf16 v[70:73], v[146:149], v[200:203], v[70:73]
	v_mfma_f32_16x16x32_bf16 v[66:69], v[154:157], v[200:203], v[66:69]
	v_mfma_f32_16x16x32_bf16 v[126:129], v[134:137], v[170:173], v[126:129]
	v_mfma_f32_16x16x32_bf16 v[122:125], v[142:145], v[170:173], v[122:125]
	v_mfma_f32_16x16x32_bf16 v[110:113], v[134:137], v[188:191], v[110:113]
	v_mfma_f32_16x16x32_bf16 v[106:109], v[142:145], v[188:191], v[106:109]
	v_mfma_f32_16x16x32_bf16 v[94:97], v[134:137], v[196:199], v[94:97]
	v_mfma_f32_16x16x32_bf16 v[90:93], v[142:145], v[196:199], v[90:93]
	v_mfma_f32_16x16x32_bf16 v[78:81], v[134:137], v[204:207], v[78:81]
	v_mfma_f32_16x16x32_bf16 v[74:77], v[142:145], v[204:207], v[74:77]
	v_mfma_f32_16x16x32_bf16 v[118:121], v[150:153], v[170:173], v[118:121]
	v_mfma_f32_16x16x32_bf16 v[114:117], v[158:161], v[170:173], v[114:117]
	v_mfma_f32_16x16x32_bf16 v[102:105], v[150:153], v[188:191], v[102:105]
	v_mfma_f32_16x16x32_bf16 v[98:101], v[158:161], v[188:191], v[98:101]
	v_mfma_f32_16x16x32_bf16 v[86:89], v[150:153], v[196:199], v[86:89]
	v_mfma_f32_16x16x32_bf16 v[82:85], v[158:161], v[196:199], v[82:85]
	v_mfma_f32_16x16x32_bf16 v[70:73], v[150:153], v[204:207], v[70:73]
	v_mfma_f32_16x16x32_bf16 v[66:69], v[158:161], v[204:207], v[66:69]
	s_barrier
	s_setprio 0
	s_add_u32 s16, s26, 0x80
	s_addc_u32 s17, s27, 0
	s_add_i32 s28, s88, s73
	s_mov_b32 m0, s28
	ds_read_b128 v[166:169], v182 offset:49152
	ds_read_b128 v[170:173], v182 offset:50176
	ds_read_b128 v[184:187], v182 offset:51200
	ds_read_b128 v[188:191], v182 offset:52224
	ds_read_b128 v[192:195], v182 offset:53248
	ds_read_b128 v[196:199], v182 offset:54272
	ds_read_b128 v[200:203], v182 offset:55296
	ds_read_b128 v[204:207], v182 offset:56320
	s_nop 0
	global_load_lds_dwordx4 v174, s[16:17]
	s_add_i32 m0, s28, 0x2000
	s_nop 0
	global_load_lds_dwordx4 v176, s[16:17]
	s_add_u32 s16, s26, 0x100080
	s_addc_u32 s17, s27, 0
	s_add_i32 s26, s89, s73
	s_mov_b32 m0, s26
	s_nop 0
	global_load_lds_dwordx4 v174, s[16:17]
	s_add_i32 m0, s26, 0x2000
	s_nop 0
	global_load_lds_dwordx4 v176, s[16:17]
	s_mov_b32 m0, s77
	s_nop 0
	global_load_lds_dwordx4 v1, s[2:3]
	s_mov_b32 m0, s78
	s_nop 0
	global_load_lds_dwordx4 v175, s[2:3]
	s_waitcnt vmcnt(8)
	s_waitcnt lgkmcnt(0)
	s_setprio 1
	s_waitcnt lgkmcnt(0)
	s_barrier
	v_mfma_f32_16x16x32_bf16 v[62:65], v[130:133], v[166:169], v[62:65]
	v_mfma_f32_16x16x32_bf16 v[58:61], v[138:141], v[166:169], v[58:61]
	v_mfma_f32_16x16x32_bf16 v[46:49], v[130:133], v[184:187], v[46:49]
	v_mfma_f32_16x16x32_bf16 v[42:45], v[138:141], v[184:187], v[42:45]
	v_mfma_f32_16x16x32_bf16 v[30:33], v[130:133], v[192:195], v[30:33]
	v_mfma_f32_16x16x32_bf16 v[26:29], v[138:141], v[192:195], v[26:29]
	v_mfma_f32_16x16x32_bf16 v[14:17], v[130:133], v[200:203], v[14:17]
	v_mfma_f32_16x16x32_bf16 v[10:13], v[138:141], v[200:203], v[10:13]
	v_mfma_f32_16x16x32_bf16 v[54:57], v[146:149], v[166:169], v[54:57]
	v_mfma_f32_16x16x32_bf16 v[50:53], v[154:157], v[166:169], v[50:53]
	v_mfma_f32_16x16x32_bf16 v[38:41], v[146:149], v[184:187], v[38:41]
	v_mfma_f32_16x16x32_bf16 v[34:37], v[154:157], v[184:187], v[34:37]
	v_mfma_f32_16x16x32_bf16 v[22:25], v[146:149], v[192:195], v[22:25]
	v_mfma_f32_16x16x32_bf16 v[18:21], v[154:157], v[192:195], v[18:21]
	v_mfma_f32_16x16x32_bf16 v[6:9], v[146:149], v[200:203], v[6:9]
	v_mfma_f32_16x16x32_bf16 v[2:5], v[154:157], v[200:203], v[2:5]
	v_mfma_f32_16x16x32_bf16 v[62:65], v[134:137], v[170:173], v[62:65]
	v_mfma_f32_16x16x32_bf16 v[58:61], v[142:145], v[170:173], v[58:61]
	v_mfma_f32_16x16x32_bf16 v[46:49], v[134:137], v[188:191], v[46:49]
	v_mfma_f32_16x16x32_bf16 v[42:45], v[142:145], v[188:191], v[42:45]
	v_mfma_f32_16x16x32_bf16 v[30:33], v[134:137], v[196:199], v[30:33]
	v_mfma_f32_16x16x32_bf16 v[26:29], v[142:145], v[196:199], v[26:29]
	v_mfma_f32_16x16x32_bf16 v[14:17], v[134:137], v[204:207], v[14:17]
	v_mfma_f32_16x16x32_bf16 v[10:13], v[142:145], v[204:207], v[10:13]
	v_mfma_f32_16x16x32_bf16 v[54:57], v[150:153], v[170:173], v[54:57]
	v_mfma_f32_16x16x32_bf16 v[50:53], v[158:161], v[170:173], v[50:53]
	v_mfma_f32_16x16x32_bf16 v[38:41], v[150:153], v[188:191], v[38:41]
	v_mfma_f32_16x16x32_bf16 v[34:37], v[158:161], v[188:191], v[34:37]
	v_mfma_f32_16x16x32_bf16 v[22:25], v[150:153], v[196:199], v[22:25]
	v_mfma_f32_16x16x32_bf16 v[18:21], v[158:161], v[196:199], v[18:21]
	v_mfma_f32_16x16x32_bf16 v[6:9], v[150:153], v[204:207], v[6:9]
	v_mfma_f32_16x16x32_bf16 v[2:5], v[158:161], v[204:207], v[2:5]
	s_barrier
	s_setprio 0
	s_add_i32 s87, s87, 2
	s_add_u32 s85, s85, 0x100
	s_addc_u32 s86, s86, 0
	s_cmp_gt_u32 s87, 61
	s_mov_b64 s[16:17], s[24:25]
	s_cbranch_scc0 .LBB0_833
	s_and_b64 vcc, exec, s[12:13]
	s_cbranch_vccz .LBB0_836
	s_barrier

; #define PG8_STAGE(bufoff, gbase, voff) do { const char* _gb = (const char*)(gbase); asm volatile("" : "+s"(_gb)); _Pragma("unroll") for (int _i = 0; _i < 2; ++_i) { asm volatile("" : "+v"((voff)[_i])); \
;         __builtin_amdgcn_global_load_lds((const unsigned*)(_gb + (voff)[_i]), (PG8_LAS unsigned*)(lds + (bufoff) + ldsw + _i * 8192), 16, 0, 0); } } while (0)
; #define PG8_LDA(dst, b, h) do { _Pragma("unroll") for (int m = 0; m < 4; ++m) _Pragma("unroll") for (int k = 0; k < 2; ++k) dst[m][k] = *(const PG8_LAS bf16x8*)(lds + PG8_SA(b, h) + aoff + m * 2048 + k * 1024); } while (0)
; #define PG8_LDB(dst, b, h) do { _Pragma("unroll") for (int n = 0; n < 2; ++n) _Pragma("unroll") for (int k = 0; k < 2; ++k) dst[n][k] = *(const PG8_LAS bf16x8*)(lds + PG8_SB(b, h) + boff + n * 2048 + k * 1024); } while (0)
; #define PG8_WAIT_V(n) asm volatile("s_waitcnt vmcnt(" #n ")" ::: "memory")
; #define PG8_WAIT_L(n) asm volatile("s_waitcnt lgkmcnt(" #n ")" ::: "memory")
; #define PG8_BAR __builtin_amdgcn_s_barrier()
; #define PG8_SCHED __builtin_amdgcn_sched_barrier(0)
; #define PG8_LDA(dst, b, h) do { _Pragma("unroll") for (int m = 0; m < 4; ++m) _Pragma("unroll") for (int k = 0; k < 2; ++k) dst[m][k] = *(const PG8_LAS bf16x8*)(lds + PG8_SA(b, h) + aoff + m * 2048 + k * 1024); } while (0)
; template <class Epi, class Sched, bool ALIGN_EPI = false, bool SP2 = false>
; __device__ __forceinline__ void gemm_phase(PG8_LAS unsigned char* lds, const Gemm g, const Sched& S, const Epi& E) {
;     ...
;             PG8_LDB(B0, 0, 0); PG8_LDB(B1, 0, 1); PG8_SCHED; PG8_LDA(At, 0, 0); PG8_STAGE(PG8_SA(1, 1), a1 + hstep, voffA);
;             PG8_WAIT_V(8); PG8_WAIT_L(0); PG8_BAR; PG8_MMA2(0); PG8_BAR; PG8_SCHED;
;             PG8_LDA(At, 0, 1); PG8_STAGE(PG8_SB(0, 0), b2, voffB); PG8_STAGE(PG8_SB(0, 1), b2 + hstep, voffB); PG8_STAGE(PG8_SA(0, 0), a2, voffA);
;             PG8_WAIT_V(8); PG8_WAIT_L(0); PG8_BAR; PG8_MMA2(1); PG8_BAR; PG8_SCHED;
;             PG8_LDB(B0, 1, 0); PG8_LDB(B1, 1, 1); PG8_SCHED; PG8_LDA(At, 1, 0); PG8_STAGE(PG8_SA(0, 1), a2 + hstep, voffA);
;             PG8_WAIT_V(8); PG8_WAIT_L(0); PG8_BAR; PG8_MMA2(0); PG8_BAR; PG8_SCHED;
;             PG8_LDA(At, 1, 1); PG8_STAGE(PG8_SB(1, 0), b3, voffB); PG8_STAGE(PG8_SB(1, 1), b3 + hstep, voffB); PG8_STAGE(PG8_SA(1, 0), a3, voffA);
;             PG8_WAIT_V(8); PG8_WAIT_L(0); PG8_BAR; PG8_MMA2(1); PG8_BAR; PG8_SCHED;
.LBB0_933:
	v_add_u32_e32 v142, s78, v201
	v_add_u32_e32 v147, s79, v201
	s_nop 0
	ds_read_b128 v[6:9], v142
	ds_read_b128 v[62:65], v142 offset:1024
	ds_read_b128 v[138:141], v142 offset:2048
	ds_read_b128 v[142:145], v142 offset:3072
	ds_read_b128 v[164:167], v147
	ds_read_b128 v[168:171], v147 offset:1024
	ds_read_b128 v[172:175], v147 offset:2048
	ds_read_b128 v[176:179], v147 offset:3072
	s_add_u32 s14, s12, 0x100
	s_addc_u32 s15, s13, 0
	s_cmp_eq_u32 s83, 60
	s_cselect_b32 s18, s21, s14
	s_cselect_b32 s19, s20, s15
	s_cselect_b32 s16, s51, s62
	s_cselect_b32 s17, s49, s63
	s_add_u32 s2, s18, 0x80
	s_addc_u32 s3, s19, 0
	s_add_u32 s12, s12, 0x100080
	s_addc_u32 s13, s13, 0
	s_add_i32 m0, s33, 0xc000
	ds_read_b128 v[180:183], v219
	ds_read_b128 v[184:187], v219 offset:1024
	ds_read_b128 v[188:191], v219 offset:2048
	ds_read_b128 v[192:195], v219 offset:3072
	ds_read_b128 v[222:225], v219 offset:4096
	ds_read_b128 v[226:229], v219 offset:5120
	ds_read_b128 v[230:233], v219 offset:6144
	ds_read_b128 v[234:237], v219 offset:7168
	s_nop 0
	global_load_lds_dwordx4 v1, s[12:13]
	s_add_i32 m0, s33, 0xe000
	s_nop 0
	global_load_lds_dwordx4 v199, s[12:13]
	s_waitcnt vmcnt(8)
	s_waitcnt lgkmcnt(0)
	s_setprio 1
	s_waitcnt lgkmcnt(0)
	s_barrier
	v_mfma_f32_16x16x32_bf16 v[118:121], v[6:9], v[180:183], v[118:121]
	v_mfma_f32_16x16x32_bf16 v[114:117], v[138:141], v[180:183], v[114:117]
	v_mfma_f32_16x16x32_bf16 v[106:109], v[6:9], v[188:191], v[106:109]
	v_mfma_f32_16x16x32_bf16 v[86:89], v[138:141], v[188:191], v[86:89]
	v_mfma_f32_16x16x32_bf16 v[134:137], v[6:9], v[222:225], v[134:137]
	v_mfma_f32_16x16x32_bf16 v[90:93], v[138:141], v[222:225], v[90:93]
	v_mfma_f32_16x16x32_bf16 v[130:133], v[6:9], v[230:233], v[130:133]
	v_mfma_f32_16x16x32_bf16 v[110:113], v[138:141], v[230:233], v[110:113]
	v_mfma_f32_16x16x32_bf16 v[94:97], v[164:167], v[180:183], v[94:97]
	v_mfma_f32_16x16x32_bf16 v[82:85], v[172:175], v[180:183], v[82:85]
	v_mfma_f32_16x16x32_bf16 v[78:81], v[164:167], v[188:191], v[78:81]
	v_mfma_f32_16x16x32_bf16 v[74:77], v[172:175], v[188:191], v[74:77]
	v_mfma_f32_16x16x32_bf16 v[126:129], v[164:167], v[222:225], v[126:129]
	v_mfma_f32_16x16x32_bf16 v[98:101], v[172:175], v[222:225], v[98:101]
	v_mfma_f32_16x16x32_bf16 v[122:125], v[164:167], v[230:233], v[122:125]
	v_mfma_f32_16x16x32_bf16 v[102:105], v[172:175], v[230:233], v[102:105]
	v_mfma_f32_16x16x32_bf16 v[118:121], v[62:65], v[184:187], v[118:121]
	v_mfma_f32_16x16x32_bf16 v[114:117], v[142:145], v[184:187], v[114:117]
	v_mfma_f32_16x16x32_bf16 v[106:109], v[62:65], v[192:195], v[106:109]
	v_mfma_f32_16x16x32_bf16 v[86:89], v[142:145], v[192:195], v[86:89]
	v_mfma_f32_16x16x32_bf16 v[134:137], v[62:65], v[226:229], v[134:137]
	v_mfma_f32_16x16x32_bf16 v[90:93], v[142:145], v[226:229], v[90:93]
	v_mfma_f32_16x16x32_bf16 v[130:133], v[62:65], v[234:237], v[130:133]
	v_mfma_f32_16x16x32_bf16 v[110:113], v[142:145], v[234:237], v[110:113]
	v_mfma_f32_16x16x32_bf16 v[94:97], v[168:171], v[184:187], v[94:97]
	v_mfma_f32_16x16x32_bf16 v[82:85], v[176:179], v[184:187], v[82:85]
	v_mfma_f32_16x16x32_bf16 v[78:81], v[168:171], v[192:195], v[78:81]
	v_mfma_f32_16x16x32_bf16 v[74:77], v[176:179], v[192:195], v[74:77]
	v_mfma_f32_16x16x32_bf16 v[126:129], v[168:171], v[226:229], v[126:129]
	v_mfma_f32_16x16x32_bf16 v[98:101], v[176:179], v[226:229], v[98:101]
	v_mfma_f32_16x16x32_bf16 v[122:125], v[168:171], v[234:237], v[122:125]
	v_mfma_f32_16x16x32_bf16 v[102:105], v[176:179], v[234:237], v[102:105]
	s_barrier
	s_setprio 0
	s_add_i32 s84, s78, s25
	s_mov_b64 s[12:13], s[16:17]
	s_mov_b32 m0, s84
	ds_read_b128 v[180:183], v219 offset:16384
	ds_read_b128 v[184:187], v219 offset:17408
	ds_read_b128 v[188:191], v219 offset:18432
	ds_read_b128 v[192:195], v219 offset:19456
	ds_read_b128 v[222:225], v219 offset:20480
	ds_read_b128 v[226:229], v219 offset:21504
	ds_read_b128 v[230:233], v219 offset:22528
	ds_read_b128 v[234:237], v219 offset:23552
	s_nop 0
	global_load_lds_dwordx4 v198, s[12:13]
	s_add_i32 m0, s84, 0x2000
	s_nop 0
	global_load_lds_dwordx4 v200, s[12:13]
	s_add_u32 s12, s16, 0x100000
	s_addc_u32 s13, s17, 0
	s_add_i32 s84, s79, s25
	s_mov_b32 m0, s84
	s_nop 0
	global_load_lds_dwordx4 v198, s[12:13]
	s_add_i32 m0, s84, 0x2000
	s_nop 0
	global_load_lds_dwordx4 v200, s[12:13]
	s_mov_b64 s[12:13], s[18:19]
	s_mov_b32 m0, s33
	s_nop 0
	global_load_lds_dwordx4 v1, s[12:13]
	s_mov_b32 m0, s45
	s_nop 0
	global_load_lds_dwordx4 v199, s[12:13]
	s_waitcnt vmcnt(8)
	s_waitcnt lgkmcnt(0)
	s_setprio 1
	s_waitcnt lgkmcnt(0)
	s_barrier
; #define PG8_STAGE(bufoff, gbase, voff) do { const char* _gb = (const char*)(gbase); asm volatile("" : "+s"(_gb)); _Pragma("unroll") for (int _i = 0; _i < 2; ++_i) { asm volatile("" : "+v"((voff)[_i])); \
;         __builtin_amdgcn_global_load_lds((const unsigned*)(_gb + (voff)[_i]), (PG8_LAS unsigned*)(lds + (bufoff) + ldsw + _i * 8192), 16, 0, 0); } } while (0)
; #define PG8_LDA(dst, b, h) do { _Pragma("unroll") for (int m = 0; m < 4; ++m) _Pragma("unroll") for (int k = 0; k < 2; ++k) dst[m][k] = *(const PG8_LAS bf16x8*)(lds + PG8_SA(b, h) + aoff + m * 2048 + k * 1024); } while (0)
; #define PG8_LDB(dst, b, h) do { _Pragma("unroll") for (int n = 0; n < 2; ++n) _Pragma("unroll") for (int k = 0; k < 2; ++k) dst[n][k] = *(const PG8_LAS bf16x8*)(lds + PG8_SB(b, h) + boff + n * 2048 + k * 1024); } while (0)
; #define PG8_WAIT_V(n) asm volatile("s_waitcnt vmcnt(" #n ")" ::: "memory")
; #define PG8_WAIT_L(n) asm volatile("s_waitcnt lgkmcnt(" #n ")" ::: "memory")
; #define PG8_BAR __builtin_amdgcn_s_barrier()
; #define PG8_SCHED __builtin_amdgcn_sched_barrier(0)
; #define PG8_LDA(dst, b, h) do { _Pragma("unroll") for (int m = 0; m < 4; ++m) _Pragma("unroll") for (int k = 0; k < 2; ++k) dst[m][k] = *(const PG8_LAS bf16x8*)(lds + PG8_SA(b, h) + aoff + m * 2048 + k * 1024); } while (0)
; template <class Epi, class Sched, bool ALIGN_EPI = false, bool SP2 = false>
; __device__ __forceinline__ void gemm_phase(PG8_LAS unsigned char* lds, const Gemm g, const Sched& S, const Epi& E) {
;     ...
;             PG8_LDB(B0, 0, 0); PG8_LDB(B1, 0, 1); PG8_SCHED; PG8_LDA(At, 0, 0); PG8_STAGE(PG8_SA(1, 1), a1 + hstep, voffA);
;             PG8_WAIT_V(8); PG8_WAIT_L(0); PG8_BAR; PG8_MMA2(0); PG8_BAR; PG8_SCHED;
;             PG8_LDA(At, 0, 1); PG8_STAGE(PG8_SB(0, 0), b2, voffB); PG8_STAGE(PG8_SB(0, 1), b2 + hstep, voffB); PG8_STAGE(PG8_SA(0, 0), a2, voffA);
;             PG8_WAIT_V(8); PG8_WAIT_L(0); PG8_BAR; PG8_MMA2(1); PG8_BAR; PG8_SCHED;
;             PG8_LDB(B0, 1, 0); PG8_LDB(B1, 1, 1); PG8_SCHED; PG8_LDA(At, 1, 0); PG8_STAGE(PG8_SA(0, 1), a2 + hstep, voffA);
;             PG8_WAIT_V(8); PG8_WAIT_L(0); PG8_BAR; PG8_MMA2(0); PG8_BAR; PG8_SCHED;
;             PG8_LDA(At, 1, 1); PG8_STAGE(PG8_SB(1, 0), b3, voffB); PG8_STAGE(PG8_SB(1, 1), b3 + hstep, voffB); PG8_STAGE(PG8_SA(1, 0), a3, voffA);
;             PG8_WAIT_V(8); PG8_WAIT_L(0); PG8_BAR; PG8_MMA2(1); PG8_BAR; PG8_SCHED;
	v_mfma_f32_16x16x32_bf16 v[34:37], v[6:9], v[180:183], v[34:37]
	v_mfma_f32_16x16x32_bf16 v[30:33], v[138:141], v[180:183], v[30:33]
	v_mfma_f32_16x16x32_bf16 v[26:29], v[6:9], v[188:191], v[26:29]
	v_mfma_f32_16x16x32_bf16 v[22:25], v[138:141], v[188:191], v[22:25]
	v_mfma_f32_16x16x32_bf16 v[70:73], v[6:9], v[222:225], v[70:73]
	v_mfma_f32_16x16x32_bf16 v[66:69], v[138:141], v[222:225], v[66:69]
	v_mfma_f32_16x16x32_bf16 v[50:53], v[138:141], v[230:233], v[50:53]
	v_mfma_f32_16x16x32_bf16 v[18:21], v[164:167], v[180:183], v[18:21]
	v_mfma_f32_16x16x32_bf16 v[14:17], v[172:175], v[180:183], v[14:17]
	v_mfma_f32_16x16x32_bf16 v[10:13], v[164:167], v[188:191], v[10:13]
	v_mfma_f32_16x16x32_bf16 v[2:5], v[172:175], v[188:191], v[2:5]
	v_mfma_f32_16x16x32_bf16 v[54:57], v[164:167], v[222:225], v[54:57]
	v_mfma_f32_16x16x32_bf16 v[46:49], v[172:175], v[222:225], v[46:49]
	v_mfma_f32_16x16x32_bf16 v[42:45], v[164:167], v[230:233], v[42:45]
	v_mfma_f32_16x16x32_bf16 v[38:41], v[172:175], v[230:233], v[38:41]
	v_mfma_f32_16x16x32_bf16 v[34:37], v[62:65], v[184:187], v[34:37]
	v_mfma_f32_16x16x32_bf16 v[30:33], v[142:145], v[184:187], v[30:33]
	v_mfma_f32_16x16x32_bf16 v[26:29], v[62:65], v[192:195], v[26:29]
	v_mfma_f32_16x16x32_bf16 v[22:25], v[142:145], v[192:195], v[22:25]
	v_mfma_f32_16x16x32_bf16 v[70:73], v[62:65], v[226:229], v[70:73]
	v_mfma_f32_16x16x32_bf16 v[66:69], v[142:145], v[226:229], v[66:69]
	v_mfma_f32_16x16x32_bf16 v[6:9], v[6:9], v[230:233], v[58:61]
	v_mfma_f32_16x16x32_bf16 v[50:53], v[142:145], v[234:237], v[50:53]
	v_mfma_f32_16x16x32_bf16 v[18:21], v[168:171], v[184:187], v[18:21]
	v_mfma_f32_16x16x32_bf16 v[14:17], v[176:179], v[184:187], v[14:17]
	v_mfma_f32_16x16x32_bf16 v[10:13], v[168:171], v[192:195], v[10:13]
	v_mfma_f32_16x16x32_bf16 v[2:5], v[176:179], v[192:195], v[2:5]
	v_mfma_f32_16x16x32_bf16 v[54:57], v[168:171], v[226:229], v[54:57]
	v_mfma_f32_16x16x32_bf16 v[46:49], v[176:179], v[226:229], v[46:49]
	v_mfma_f32_16x16x32_bf16 v[42:45], v[168:171], v[234:237], v[42:45]
	v_mfma_f32_16x16x32_bf16 v[38:41], v[176:179], v[234:237], v[38:41]
	v_mfma_f32_16x16x32_bf16 v[6:9], v[62:65], v[234:237], v[6:9]
	s_barrier
	s_setprio 0
	s_add_i32 s84, 0, 0x18000
	s_add_i32 s85, 0, 0x1c000
	v_add_u32_e32 v142, s84, v201
	v_add_u32_e32 v147, s85, v201
	ds_read_b128 v[58:61], v142
	ds_read_b128 v[62:65], v142 offset:1024
	ds_read_b128 v[138:141], v142 offset:2048
	ds_read_b128 v[142:145], v142 offset:3072
	ds_read_b128 v[164:167], v147
	ds_read_b128 v[168:171], v147 offset:1024
	ds_read_b128 v[172:175], v147 offset:2048
	ds_read_b128 v[176:179], v147 offset:3072
	s_add_u32 s12, s18, 0x100000
	s_addc_u32 s13, s19, 0
	s_mov_b32 m0, s47
	ds_read_b128 v[180:183], v219 offset:32768
	ds_read_b128 v[184:187], v219 offset:33792
	ds_read_b128 v[188:191], v219 offset:34816
	ds_read_b128 v[192:195], v219 offset:35840
	ds_read_b128 v[222:225], v219 offset:36864
	ds_read_b128 v[226:229], v219 offset:37888
	ds_read_b128 v[230:233], v219 offset:38912
	ds_read_b128 v[234:237], v219 offset:39936
	s_nop 0
	global_load_lds_dwordx4 v1, s[12:13]
	s_mov_b32 m0, s87
	s_nop 0
	global_load_lds_dwordx4 v199, s[12:13]
	s_waitcnt vmcnt(8)
	s_waitcnt lgkmcnt(0)
	s_setprio 1
	s_waitcnt lgkmcnt(0)
	s_barrier
	v_mfma_f32_16x16x32_bf16 v[118:121], v[58:61], v[180:183], v[118:121]
	v_mfma_f32_16x16x32_bf16 v[114:117], v[138:141], v[180:183], v[114:117]
	v_mfma_f32_16x16x32_bf16 v[106:109], v[58:61], v[188:191], v[106:109]
	v_mfma_f32_16x16x32_bf16 v[86:89], v[138:141], v[188:191], v[86:89]
	v_mfma_f32_16x16x32_bf16 v[134:137], v[58:61], v[222:225], v[134:137]
	v_mfma_f32_16x16x32_bf16 v[90:93], v[138:141], v[222:225], v[90:93]
	v_mfma_f32_16x16x32_bf16 v[130:133], v[58:61], v[230:233], v[130:133]
	v_mfma_f32_16x16x32_bf16 v[110:113], v[138:141], v[230:233], v[110:113]
	v_mfma_f32_16x16x32_bf16 v[94:97], v[164:167], v[180:183], v[94:97]
	v_mfma_f32_16x16x32_bf16 v[82:85], v[172:175], v[180:183], v[82:85]
	v_mfma_f32_16x16x32_bf16 v[78:81], v[164:167], v[188:191], v[78:81]
	v_mfma_f32_16x16x32_bf16 v[74:77], v[172:175], v[188:191], v[74:77]
	v_mfma_f32_16x16x32_bf16 v[126:129], v[164:167], v[222:225], v[126:129]
	v_mfma_f32_16x16x32_bf16 v[98:101], v[172:175], v[222:225], v[98:101]
	v_mfma_f32_16x16x32_bf16 v[122:125], v[164:167], v[230:233], v[122:125]
	v_mfma_f32_16x16x32_bf16 v[102:105], v[172:175], v[230:233], v[102:105]
	v_mfma_f32_16x16x32_bf16 v[118:121], v[62:65], v[184:187], v[118:121]
	v_mfma_f32_16x16x32_bf16 v[114:117], v[142:145], v[184:187], v[114:117]
	v_mfma_f32_16x16x32_bf16 v[106:109], v[62:65], v[192:195], v[106:109]
	v_mfma_f32_16x16x32_bf16 v[86:89], v[142:145], v[192:195], v[86:89]
	v_mfma_f32_16x16x32_bf16 v[134:137], v[62:65], v[226:229], v[134:137]
	v_mfma_f32_16x16x32_bf16 v[90:93], v[142:145], v[226:229], v[90:93]
	v_mfma_f32_16x16x32_bf16 v[130:133], v[62:65], v[234:237], v[130:133]
	v_mfma_f32_16x16x32_bf16 v[110:113], v[142:145], v[234:237], v[110:113]
	v_mfma_f32_16x16x32_bf16 v[94:97], v[168:171], v[184:187], v[94:97]
	v_mfma_f32_16x16x32_bf16 v[82:85], v[176:179], v[184:187], v[82:85]
	v_mfma_f32_16x16x32_bf16 v[78:81], v[168:171], v[192:195], v[78:81]
	v_mfma_f32_16x16x32_bf16 v[74:77], v[176:179], v[192:195], v[74:77]
	v_mfma_f32_16x16x32_bf16 v[126:129], v[168:171], v[226:229], v[126:129]
	v_mfma_f32_16x16x32_bf16 v[98:101], v[176:179], v[226:229], v[98:101]
	v_mfma_f32_16x16x32_bf16 v[122:125], v[168:171], v[234:237], v[122:125]
	v_mfma_f32_16x16x32_bf16 v[102:105], v[176:179], v[234:237], v[102:105]
	s_barrier
; #define PG8_STAGE(bufoff, gbase, voff) do { const char* _gb = (const char*)(gbase); asm volatile("" : "+s"(_gb)); _Pragma("unroll") for (int _i = 0; _i < 2; ++_i) { asm volatile("" : "+v"((voff)[_i])); \
;         __builtin_amdgcn_global_load_lds((const unsigned*)(_gb + (voff)[_i]), (PG8_LAS unsigned*)(lds + (bufoff) + ldsw + _i * 8192), 16, 0, 0); } } while (0)
; #define PG8_LDA(dst, b, h) do { _Pragma("unroll") for (int m = 0; m < 4; ++m) _Pragma("unroll") for (int k = 0; k < 2; ++k) dst[m][k] = *(const PG8_LAS bf16x8*)(lds + PG8_SA(b, h) + aoff + m * 2048 + k * 1024); } while (0)
; #define PG8_LDB(dst, b, h) do { _Pragma("unroll") for (int n = 0; n < 2; ++n) _Pragma("unroll") for (int k = 0; k < 2; ++k) dst[n][k] = *(const PG8_LAS bf16x8*)(lds + PG8_SB(b, h) + boff + n * 2048 + k * 1024); } while (0)
; #define PG8_WAIT_V(n) asm volatile("s_waitcnt vmcnt(" #n ")" ::: "memory")
; #define PG8_WAIT_L(n) asm volatile("s_waitcnt lgkmcnt(" #n ")" ::: "memory")
; #define PG8_BAR __builtin_amdgcn_s_barrier()
; #define PG8_SCHED __builtin_amdgcn_sched_barrier(0)
; #define PG8_WAIT_V(n) asm volatile("s_waitcnt vmcnt(" #n ")" ::: "memory")
; #define PG8_WAIT_L(n) asm volatile("s_waitcnt lgkmcnt(" #n ")" ::: "memory")
; template <class Epi, class Sched, bool ALIGN_EPI = false, bool SP2 = false>
; __device__ __forceinline__ void gemm_phase(PG8_LAS unsigned char* lds, const Gemm g, const Sched& S, const Epi& E) {
;     ...
;             PG8_LDB(B0, 0, 0); PG8_LDB(B1, 0, 1); PG8_SCHED; PG8_LDA(At, 0, 0); PG8_STAGE(PG8_SA(1, 1), a1 + hstep, voffA);
;             PG8_WAIT_V(8); PG8_WAIT_L(0); PG8_BAR; PG8_MMA2(0); PG8_BAR; PG8_SCHED;
;             PG8_LDA(At, 0, 1); PG8_STAGE(PG8_SB(0, 0), b2, voffB); PG8_STAGE(PG8_SB(0, 1), b2 + hstep, voffB); PG8_STAGE(PG8_SA(0, 0), a2, voffA);
;             PG8_WAIT_V(8); PG8_WAIT_L(0); PG8_BAR; PG8_MMA2(1); PG8_BAR; PG8_SCHED;
;             PG8_LDB(B0, 1, 0); PG8_LDB(B1, 1, 1); PG8_SCHED; PG8_LDA(At, 1, 0); PG8_STAGE(PG8_SA(0, 1), a2 + hstep, voffA);
;             PG8_WAIT_V(8); PG8_WAIT_L(0); PG8_BAR; PG8_MMA2(0); PG8_BAR; PG8_SCHED;
;             PG8_LDA(At, 1, 1); PG8_STAGE(PG8_SB(1, 0), b3, voffB); PG8_STAGE(PG8_SB(1, 1), b3 + hstep, voffB); PG8_STAGE(PG8_SA(1, 0), a3, voffA);
;             PG8_WAIT_V(8); PG8_WAIT_L(0); PG8_BAR; PG8_MMA2(1); PG8_BAR; PG8_SCHED;
;     ...
;         if constexpr (ALIGN_EPI) { if (wr == 0) PG8_BAR; }
	s_setprio 0
	s_add_u32 s12, s16, 0x80
	s_addc_u32 s13, s17, 0
	s_add_i32 s18, s84, s25
	s_mov_b32 m0, s18
	ds_read_b128 v[180:183], v219 offset:49152
	ds_read_b128 v[184:187], v219 offset:50176
	ds_read_b128 v[188:191], v219 offset:51200
	ds_read_b128 v[192:195], v219 offset:52224
	ds_read_b128 v[222:225], v219 offset:53248
	ds_read_b128 v[226:229], v219 offset:54272
	ds_read_b128 v[230:233], v219 offset:55296
	ds_read_b128 v[234:237], v219 offset:56320
	s_nop 0
	global_load_lds_dwordx4 v198, s[12:13]
	s_add_i32 m0, s18, 0x2000
	s_nop 0
	global_load_lds_dwordx4 v200, s[12:13]
	s_add_u32 s12, s16, 0x100080
	s_addc_u32 s13, s17, 0
	s_add_i32 s16, s85, s25
	s_mov_b32 m0, s16
	s_nop 0
	global_load_lds_dwordx4 v198, s[12:13]
	s_add_i32 m0, s16, 0x2000
	s_nop 0
	global_load_lds_dwordx4 v200, s[12:13]
	s_mov_b32 m0, s71
	s_nop 0
	global_load_lds_dwordx4 v1, s[2:3]
	s_mov_b32 m0, s72
	s_nop 0
	global_load_lds_dwordx4 v199, s[2:3]
	s_waitcnt vmcnt(8)
	s_waitcnt lgkmcnt(0)
	s_setprio 1
	s_waitcnt lgkmcnt(0)
	s_barrier
	v_mfma_f32_16x16x32_bf16 v[6:9], v[58:61], v[230:233], v[6:9]
	v_mfma_f32_16x16x32_bf16 v[34:37], v[58:61], v[180:183], v[34:37]
	v_mfma_f32_16x16x32_bf16 v[26:29], v[58:61], v[188:191], v[26:29]
	v_mfma_f32_16x16x32_bf16 v[70:73], v[58:61], v[222:225], v[70:73]
	v_mfma_f32_16x16x32_bf16 v[58:61], v[62:65], v[234:237], v[6:9]
	v_mfma_f32_16x16x32_bf16 v[6:9], v[138:141], v[230:233], v[50:53]
	v_mfma_f32_16x16x32_bf16 v[50:53], v[142:145], v[234:237], v[6:9]
	v_mfma_f32_16x16x32_bf16 v[6:9], v[164:167], v[180:183], v[18:21]
	v_mfma_f32_16x16x32_bf16 v[18:21], v[168:171], v[184:187], v[6:9]
	v_mfma_f32_16x16x32_bf16 v[6:9], v[172:175], v[180:183], v[14:17]
	v_mfma_f32_16x16x32_bf16 v[14:17], v[176:179], v[184:187], v[6:9]
	v_mfma_f32_16x16x32_bf16 v[6:9], v[164:167], v[188:191], v[10:13]
	v_mfma_f32_16x16x32_bf16 v[10:13], v[168:171], v[192:195], v[6:9]
	v_mfma_f32_16x16x32_bf16 v[6:9], v[164:167], v[222:225], v[54:57]
	v_mfma_f32_16x16x32_bf16 v[54:57], v[168:171], v[226:229], v[6:9]
	v_mfma_f32_16x16x32_bf16 v[6:9], v[172:175], v[222:225], v[46:49]
	v_mfma_f32_16x16x32_bf16 v[46:49], v[176:179], v[226:229], v[6:9]
	v_mfma_f32_16x16x32_bf16 v[6:9], v[164:167], v[230:233], v[42:45]
	v_mfma_f32_16x16x32_bf16 v[30:33], v[138:141], v[180:183], v[30:33]
	v_mfma_f32_16x16x32_bf16 v[22:25], v[138:141], v[188:191], v[22:25]
	v_mfma_f32_16x16x32_bf16 v[66:69], v[138:141], v[222:225], v[66:69]
	v_mfma_f32_16x16x32_bf16 v[2:5], v[172:175], v[188:191], v[2:5]
	v_mfma_f32_16x16x32_bf16 v[42:45], v[168:171], v[234:237], v[6:9]
	v_mfma_f32_16x16x32_bf16 v[6:9], v[172:175], v[230:233], v[38:41]
	v_mfma_f32_16x16x32_bf16 v[34:37], v[62:65], v[184:187], v[34:37]
	v_mfma_f32_16x16x32_bf16 v[30:33], v[142:145], v[184:187], v[30:33]
	v_mfma_f32_16x16x32_bf16 v[26:29], v[62:65], v[192:195], v[26:29]
	v_mfma_f32_16x16x32_bf16 v[22:25], v[142:145], v[192:195], v[22:25]
	v_mfma_f32_16x16x32_bf16 v[70:73], v[62:65], v[226:229], v[70:73]
	v_mfma_f32_16x16x32_bf16 v[66:69], v[142:145], v[226:229], v[66:69]
	v_mfma_f32_16x16x32_bf16 v[2:5], v[176:179], v[192:195], v[2:5]
	v_mfma_f32_16x16x32_bf16 v[38:41], v[176:179], v[234:237], v[6:9]
	s_barrier
	s_setprio 0
	s_add_i32 s83, s83, 2
	s_add_u32 s62, s62, 0x100
	s_addc_u32 s63, s63, 0
	s_cmp_gt_u32 s83, 61
	s_mov_b64 s[12:13], s[14:15]
	s_cbranch_scc0 .LBB0_933
	s_and_b64 vcc, exec, s[38:39]
	s_cbranch_vccz .LBB0_936
	s_barrier

; #define PG8_STAGE(bufoff, gbase, voff) do { const char* _gb = (const char*)(gbase); asm volatile("" : "+s"(_gb)); _Pragma("unroll") for (int _i = 0; _i < 2; ++_i) { asm volatile("" : "+v"((voff)[_i])); \
;         __builtin_amdgcn_global_load_lds((const unsigned*)(_gb + (voff)[_i]), (PG8_LAS unsigned*)(lds + (bufoff) + ldsw + _i * 8192), 16, 0, 0); } } while (0)
; #define PG8_LDA(dst, b, h) do { _Pragma("unroll") for (int m = 0; m < 4; ++m) _Pragma("unroll") for (int k = 0; k < 2; ++k) dst[m][k] = *(const PG8_LAS bf16x8*)(lds + PG8_SA(b, h) + aoff + m * 2048 + k * 1024); } while (0)
; #define PG8_LDB(dst, b, h) do { _Pragma("unroll") for (int n = 0; n < 2; ++n) _Pragma("unroll") for (int k = 0; k < 2; ++k) dst[n][k] = *(const PG8_LAS bf16x8*)(lds + PG8_SB(b, h) + boff + n * 2048 + k * 1024); } while (0)
; #define PG8_WAIT_V(n) asm volatile("s_waitcnt vmcnt(" #n ")" ::: "memory")
; #define PG8_WAIT_L(n) asm volatile("s_waitcnt lgkmcnt(" #n ")" ::: "memory")
; #define PG8_BAR __builtin_amdgcn_s_barrier()
; #define PG8_SCHED __builtin_amdgcn_sched_barrier(0)
; #define PG8_LDA(dst, b, h) do { _Pragma("unroll") for (int m = 0; m < 4; ++m) _Pragma("unroll") for (int k = 0; k < 2; ++k) dst[m][k] = *(const PG8_LAS bf16x8*)(lds + PG8_SA(b, h) + aoff + m * 2048 + k * 1024); } while (0)
; template <class Epi, class Sched, bool ALIGN_EPI = false, bool SP2 = false>
; __device__ __forceinline__ void gemm_phase(PG8_LAS unsigned char* lds, const Gemm g, const Sched& S, const Epi& E) {
;     ...
;             PG8_LDB(B0, 0, 0); PG8_LDB(B1, 0, 1); PG8_SCHED; PG8_LDA(At, 0, 0); PG8_STAGE(PG8_SA(1, 1), a1 + hstep, voffA);
;             PG8_WAIT_V(8); PG8_WAIT_L(0); PG8_BAR; PG8_MMA2(0); PG8_BAR; PG8_SCHED;
;             PG8_LDA(At, 0, 1); PG8_STAGE(PG8_SB(0, 0), b2, voffB); PG8_STAGE(PG8_SB(0, 1), b2 + hstep, voffB); PG8_STAGE(PG8_SA(0, 0), a2, voffA);
;             PG8_WAIT_V(8); PG8_WAIT_L(0); PG8_BAR; PG8_MMA2(1); PG8_BAR; PG8_SCHED;
;             PG8_LDB(B0, 1, 0); PG8_LDB(B1, 1, 1); PG8_SCHED; PG8_LDA(At, 1, 0); PG8_STAGE(PG8_SA(0, 1), a2 + hstep, voffA);
;             PG8_WAIT_V(8); PG8_WAIT_L(0); PG8_BAR; PG8_MMA2(0); PG8_BAR; PG8_SCHED;
;             PG8_LDA(At, 1, 1); PG8_STAGE(PG8_SB(1, 0), b3, voffB); PG8_STAGE(PG8_SB(1, 1), b3 + hstep, voffB); PG8_STAGE(PG8_SA(1, 0), a3, voffA);
;             PG8_WAIT_V(8); PG8_WAIT_L(0); PG8_BAR; PG8_MMA2(1); PG8_BAR; PG8_SCHED;
.LBB0_1125:
	ds_read_b128 v[130:133], v162
	ds_read_b128 v[134:137], v162 offset:1024
	ds_read_b128 v[138:141], v162 offset:2048
	ds_read_b128 v[142:145], v162 offset:3072
	ds_read_b128 v[150:153], v163
	ds_read_b128 v[166:169], v163 offset:1024
	ds_read_b128 v[170:173], v163 offset:2048
	ds_read_b128 v[174:177], v163 offset:3072
	s_add_u32 s20, s16, 0x100
	s_addc_u32 s21, s17, 0
	s_cmpk_eq_i32 s53, 0xbc
	s_cselect_b32 s26, s6, s20
	s_cselect_b32 s27, s7, s21
	s_cselect_b32 s24, s18, s51
	s_cselect_b32 s25, s19, s52
	s_add_u32 s2, s26, 0x80
	s_addc_u32 s3, s27, 0
	s_add_u32 s16, s16, 0x300080
	s_addc_u32 s17, s17, 0
	s_add_i32 m0, s34, 0xc000
	ds_read_b128 v[178:181], v164
	ds_read_b128 v[182:185], v164 offset:1024
	ds_read_b128 v[186:189], v164 offset:2048
	ds_read_b128 v[190:193], v164 offset:3072
	ds_read_b128 v[194:197], v164 offset:4096
	ds_read_b128 v[198:201], v164 offset:5120
	ds_read_b128 v[202:205], v164 offset:6144
	ds_read_b128 v[206:209], v164 offset:7168
	s_nop 0
	global_load_lds_dwordx4 v1, s[16:17]
	s_add_i32 m0, s34, 0xe000
	s_nop 0
	global_load_lds_dwordx4 v157, s[16:17]
	s_waitcnt vmcnt(8)
	s_waitcnt lgkmcnt(0)
	s_setprio 1
	s_waitcnt lgkmcnt(0)
	s_barrier
	v_mfma_f32_16x16x32_bf16 v[126:129], v[130:133], v[178:181], v[126:129]
	v_mfma_f32_16x16x32_bf16 v[122:125], v[138:141], v[178:181], v[122:125]
	v_mfma_f32_16x16x32_bf16 v[110:113], v[130:133], v[186:189], v[110:113]
	v_mfma_f32_16x16x32_bf16 v[106:109], v[138:141], v[186:189], v[106:109]
	v_mfma_f32_16x16x32_bf16 v[94:97], v[130:133], v[194:197], v[94:97]
	v_mfma_f32_16x16x32_bf16 v[90:93], v[138:141], v[194:197], v[90:93]
	v_mfma_f32_16x16x32_bf16 v[78:81], v[130:133], v[202:205], v[78:81]
	v_mfma_f32_16x16x32_bf16 v[74:77], v[138:141], v[202:205], v[74:77]
	v_mfma_f32_16x16x32_bf16 v[118:121], v[150:153], v[178:181], v[118:121]
	v_mfma_f32_16x16x32_bf16 v[114:117], v[170:173], v[178:181], v[114:117]
	v_mfma_f32_16x16x32_bf16 v[102:105], v[150:153], v[186:189], v[102:105]
	v_mfma_f32_16x16x32_bf16 v[98:101], v[170:173], v[186:189], v[98:101]
	v_mfma_f32_16x16x32_bf16 v[86:89], v[150:153], v[194:197], v[86:89]
	v_mfma_f32_16x16x32_bf16 v[82:85], v[170:173], v[194:197], v[82:85]
	v_mfma_f32_16x16x32_bf16 v[70:73], v[150:153], v[202:205], v[70:73]
	v_mfma_f32_16x16x32_bf16 v[66:69], v[170:173], v[202:205], v[66:69]
	v_mfma_f32_16x16x32_bf16 v[126:129], v[134:137], v[182:185], v[126:129]
	v_mfma_f32_16x16x32_bf16 v[122:125], v[142:145], v[182:185], v[122:125]
	v_mfma_f32_16x16x32_bf16 v[110:113], v[134:137], v[190:193], v[110:113]
	v_mfma_f32_16x16x32_bf16 v[106:109], v[142:145], v[190:193], v[106:109]
	v_mfma_f32_16x16x32_bf16 v[94:97], v[134:137], v[198:201], v[94:97]
	v_mfma_f32_16x16x32_bf16 v[90:93], v[142:145], v[198:201], v[90:93]
	v_mfma_f32_16x16x32_bf16 v[78:81], v[134:137], v[206:209], v[78:81]
	v_mfma_f32_16x16x32_bf16 v[74:77], v[142:145], v[206:209], v[74:77]
	v_mfma_f32_16x16x32_bf16 v[118:121], v[166:169], v[182:185], v[118:121]
	v_mfma_f32_16x16x32_bf16 v[114:117], v[174:177], v[182:185], v[114:117]
	v_mfma_f32_16x16x32_bf16 v[102:105], v[166:169], v[190:193], v[102:105]
	v_mfma_f32_16x16x32_bf16 v[98:101], v[174:177], v[190:193], v[98:101]
	v_mfma_f32_16x16x32_bf16 v[86:89], v[166:169], v[198:201], v[86:89]
	v_mfma_f32_16x16x32_bf16 v[82:85], v[174:177], v[198:201], v[82:85]
	v_mfma_f32_16x16x32_bf16 v[70:73], v[166:169], v[206:209], v[70:73]
	v_mfma_f32_16x16x32_bf16 v[66:69], v[174:177], v[206:209], v[66:69]
	s_barrier
	s_setprio 0
	s_add_i32 s54, s43, s33
	s_mov_b64 s[16:17], s[24:25]
	s_mov_b32 m0, s54
	ds_read_b128 v[178:181], v164 offset:16384
	ds_read_b128 v[182:185], v164 offset:17408
	ds_read_b128 v[186:189], v164 offset:18432
	ds_read_b128 v[190:193], v164 offset:19456
	ds_read_b128 v[194:197], v164 offset:20480
	ds_read_b128 v[198:201], v164 offset:21504
	ds_read_b128 v[202:205], v164 offset:22528
	ds_read_b128 v[206:209], v164 offset:23552
	s_nop 0
	global_load_lds_dwordx4 v156, s[16:17]
	s_add_i32 m0, s54, 0x2000
	s_nop 0
	global_load_lds_dwordx4 v158, s[16:17]
	s_add_u32 s16, s24, 0x300000
	s_addc_u32 s17, s25, 0
	s_add_i32 s54, s44, s33
	s_mov_b32 m0, s54
	s_nop 0
	global_load_lds_dwordx4 v156, s[16:17]
	s_add_i32 m0, s54, 0x2000
	s_nop 0
	global_load_lds_dwordx4 v158, s[16:17]
	s_mov_b64 s[16:17], s[26:27]
	s_mov_b32 m0, s34
	s_nop 0
	global_load_lds_dwordx4 v1, s[16:17]
	s_mov_b32 m0, s35
	s_nop 0
	global_load_lds_dwordx4 v157, s[16:17]
	s_waitcnt vmcnt(8)
	s_waitcnt lgkmcnt(0)
	s_setprio 1
	s_waitcnt lgkmcnt(0)
	s_barrier
	v_mfma_f32_16x16x32_bf16 v[62:65], v[130:133], v[178:181], v[62:65]
	v_mfma_f32_16x16x32_bf16 v[58:61], v[138:141], v[178:181], v[58:61]
	v_mfma_f32_16x16x32_bf16 v[46:49], v[130:133], v[186:189], v[46:49]
	v_mfma_f32_16x16x32_bf16 v[42:45], v[138:141], v[186:189], v[42:45]
	v_mfma_f32_16x16x32_bf16 v[30:33], v[130:133], v[194:197], v[30:33]
	v_mfma_f32_16x16x32_bf16 v[26:29], v[138:141], v[194:197], v[26:29]
	v_mfma_f32_16x16x32_bf16 v[14:17], v[130:133], v[202:205], v[14:17]
	v_mfma_f32_16x16x32_bf16 v[10:13], v[138:141], v[202:205], v[10:13]
	v_mfma_f32_16x16x32_bf16 v[54:57], v[150:153], v[178:181], v[54:57]
	v_mfma_f32_16x16x32_bf16 v[50:53], v[170:173], v[178:181], v[50:53]
	v_mfma_f32_16x16x32_bf16 v[38:41], v[150:153], v[186:189], v[38:41]
	v_mfma_f32_16x16x32_bf16 v[34:37], v[170:173], v[186:189], v[34:37]
	v_mfma_f32_16x16x32_bf16 v[22:25], v[150:153], v[194:197], v[22:25]
	v_mfma_f32_16x16x32_bf16 v[18:21], v[170:173], v[194:197], v[18:21]
	v_mfma_f32_16x16x32_bf16 v[6:9], v[150:153], v[202:205], v[6:9]
	v_mfma_f32_16x16x32_bf16 v[2:5], v[170:173], v[202:205], v[2:5]
	v_mfma_f32_16x16x32_bf16 v[62:65], v[134:137], v[182:185], v[62:65]
	v_mfma_f32_16x16x32_bf16 v[58:61], v[142:145], v[182:185], v[58:61]
	v_mfma_f32_16x16x32_bf16 v[46:49], v[134:137], v[190:193], v[46:49]
	v_mfma_f32_16x16x32_bf16 v[42:45], v[142:145], v[190:193], v[42:45]
	v_mfma_f32_16x16x32_bf16 v[30:33], v[134:137], v[198:201], v[30:33]
	v_mfma_f32_16x16x32_bf16 v[26:29], v[142:145], v[198:201], v[26:29]
	v_mfma_f32_16x16x32_bf16 v[14:17], v[134:137], v[206:209], v[14:17]
	v_mfma_f32_16x16x32_bf16 v[10:13], v[142:145], v[206:209], v[10:13]
	v_mfma_f32_16x16x32_bf16 v[54:57], v[166:169], v[182:185], v[54:57]
	v_mfma_f32_16x16x32_bf16 v[50:53], v[174:177], v[182:185], v[50:53]
	v_mfma_f32_16x16x32_bf16 v[38:41], v[166:169], v[190:193], v[38:41]
	v_mfma_f32_16x16x32_bf16 v[34:37], v[174:177], v[190:193], v[34:37]
	v_mfma_f32_16x16x32_bf16 v[22:25], v[166:169], v[198:201], v[22:25]
	v_mfma_f32_16x16x32_bf16 v[18:21], v[174:177], v[198:201], v[18:21]
	v_mfma_f32_16x16x32_bf16 v[6:9], v[166:169], v[206:209], v[6:9]
	v_mfma_f32_16x16x32_bf16 v[2:5], v[174:177], v[206:209], v[2:5]
	s_barrier
; #define PG8_STAGE(bufoff, gbase, voff) do { const char* _gb = (const char*)(gbase); asm volatile("" : "+s"(_gb)); _Pragma("unroll") for (int _i = 0; _i < 2; ++_i) { asm volatile("" : "+v"((voff)[_i])); \
;         __builtin_amdgcn_global_load_lds((const unsigned*)(_gb + (voff)[_i]), (PG8_LAS unsigned*)(lds + (bufoff) + ldsw + _i * 8192), 16, 0, 0); } } while (0)
; #define PG8_LDA(dst, b, h) do { _Pragma("unroll") for (int m = 0; m < 4; ++m) _Pragma("unroll") for (int k = 0; k < 2; ++k) dst[m][k] = *(const PG8_LAS bf16x8*)(lds + PG8_SA(b, h) + aoff + m * 2048 + k * 1024); } while (0)
; #define PG8_LDB(dst, b, h) do { _Pragma("unroll") for (int n = 0; n < 2; ++n) _Pragma("unroll") for (int k = 0; k < 2; ++k) dst[n][k] = *(const PG8_LAS bf16x8*)(lds + PG8_SB(b, h) + boff + n * 2048 + k * 1024); } while (0)
; #define PG8_WAIT_V(n) asm volatile("s_waitcnt vmcnt(" #n ")" ::: "memory")
; #define PG8_WAIT_L(n) asm volatile("s_waitcnt lgkmcnt(" #n ")" ::: "memory")
; #define PG8_BAR __builtin_amdgcn_s_barrier()
; #define PG8_SCHED __builtin_amdgcn_sched_barrier(0)
; #define PG8_WAIT_V(n) asm volatile("s_waitcnt vmcnt(" #n ")" ::: "memory")
; #define PG8_WAIT_L(n) asm volatile("s_waitcnt lgkmcnt(" #n ")" ::: "memory")
; template <class Epi, class Sched, bool ALIGN_EPI = false, bool SP2 = false>
; __device__ __forceinline__ void gemm_phase(PG8_LAS unsigned char* lds, const Gemm g, const Sched& S, const Epi& E) {
;     ...
;             PG8_LDB(B0, 0, 0); PG8_LDB(B1, 0, 1); PG8_SCHED; PG8_LDA(At, 0, 0); PG8_STAGE(PG8_SA(1, 1), a1 + hstep, voffA);
;             PG8_WAIT_V(8); PG8_WAIT_L(0); PG8_BAR; PG8_MMA2(0); PG8_BAR; PG8_SCHED;
;             PG8_LDA(At, 0, 1); PG8_STAGE(PG8_SB(0, 0), b2, voffB); PG8_STAGE(PG8_SB(0, 1), b2 + hstep, voffB); PG8_STAGE(PG8_SA(0, 0), a2, voffA);
;             PG8_WAIT_V(8); PG8_WAIT_L(0); PG8_BAR; PG8_MMA2(1); PG8_BAR; PG8_SCHED;
;             PG8_LDB(B0, 1, 0); PG8_LDB(B1, 1, 1); PG8_SCHED; PG8_LDA(At, 1, 0); PG8_STAGE(PG8_SA(0, 1), a2 + hstep, voffA);
;             PG8_WAIT_V(8); PG8_WAIT_L(0); PG8_BAR; PG8_MMA2(0); PG8_BAR; PG8_SCHED;
;             PG8_LDA(At, 1, 1); PG8_STAGE(PG8_SB(1, 0), b3, voffB); PG8_STAGE(PG8_SB(1, 1), b3 + hstep, voffB); PG8_STAGE(PG8_SA(1, 0), a3, voffA);
;             PG8_WAIT_V(8); PG8_WAIT_L(0); PG8_BAR; PG8_MMA2(1); PG8_BAR; PG8_SCHED;
;     ...
;         if constexpr (ALIGN_EPI) { if (wr == 0) PG8_BAR; }
	s_setprio 0
	s_add_i32 s54, 0, 0x18000
	s_add_i32 s55, 0, 0x1c000
	v_add_u32_e32 v142, s54, v160
	v_add_u32_e32 v154, s55, v160
	ds_read_b128 v[130:133], v142
	ds_read_b128 v[134:137], v142 offset:1024
	ds_read_b128 v[138:141], v142 offset:2048
	ds_read_b128 v[142:145], v142 offset:3072
	ds_read_b128 v[150:153], v154
	ds_read_b128 v[166:169], v154 offset:1024
	ds_read_b128 v[170:173], v154 offset:2048
	ds_read_b128 v[174:177], v154 offset:3072
	s_add_u32 s16, s26, 0x300000
	s_addc_u32 s17, s27, 0
	s_mov_b32 m0, s36
	ds_read_b128 v[178:181], v164 offset:32768
	ds_read_b128 v[182:185], v164 offset:33792
	ds_read_b128 v[186:189], v164 offset:34816
	ds_read_b128 v[190:193], v164 offset:35840
	ds_read_b128 v[194:197], v164 offset:36864
	ds_read_b128 v[198:201], v164 offset:37888
	ds_read_b128 v[202:205], v164 offset:38912
	ds_read_b128 v[206:209], v164 offset:39936
	s_nop 0
	global_load_lds_dwordx4 v1, s[16:17]
	s_mov_b32 m0, s37
	s_nop 0
	global_load_lds_dwordx4 v157, s[16:17]
	s_waitcnt vmcnt(8)
	s_waitcnt lgkmcnt(0)
	s_setprio 1
	s_waitcnt lgkmcnt(0)
	s_barrier
	v_mfma_f32_16x16x32_bf16 v[126:129], v[130:133], v[178:181], v[126:129]
	v_mfma_f32_16x16x32_bf16 v[122:125], v[138:141], v[178:181], v[122:125]
	v_mfma_f32_16x16x32_bf16 v[110:113], v[130:133], v[186:189], v[110:113]
	v_mfma_f32_16x16x32_bf16 v[106:109], v[138:141], v[186:189], v[106:109]
	v_mfma_f32_16x16x32_bf16 v[94:97], v[130:133], v[194:197], v[94:97]
	v_mfma_f32_16x16x32_bf16 v[90:93], v[138:141], v[194:197], v[90:93]
	v_mfma_f32_16x16x32_bf16 v[78:81], v[130:133], v[202:205], v[78:81]
	v_mfma_f32_16x16x32_bf16 v[74:77], v[138:141], v[202:205], v[74:77]
	v_mfma_f32_16x16x32_bf16 v[118:121], v[150:153], v[178:181], v[118:121]
	v_mfma_f32_16x16x32_bf16 v[114:117], v[170:173], v[178:181], v[114:117]
	v_mfma_f32_16x16x32_bf16 v[102:105], v[150:153], v[186:189], v[102:105]
	v_mfma_f32_16x16x32_bf16 v[98:101], v[170:173], v[186:189], v[98:101]
	v_mfma_f32_16x16x32_bf16 v[86:89], v[150:153], v[194:197], v[86:89]
	v_mfma_f32_16x16x32_bf16 v[82:85], v[170:173], v[194:197], v[82:85]
	v_mfma_f32_16x16x32_bf16 v[70:73], v[150:153], v[202:205], v[70:73]
	v_mfma_f32_16x16x32_bf16 v[66:69], v[170:173], v[202:205], v[66:69]
	v_mfma_f32_16x16x32_bf16 v[126:129], v[134:137], v[182:185], v[126:129]
	v_mfma_f32_16x16x32_bf16 v[122:125], v[142:145], v[182:185], v[122:125]
	v_mfma_f32_16x16x32_bf16 v[110:113], v[134:137], v[190:193], v[110:113]
	v_mfma_f32_16x16x32_bf16 v[106:109], v[142:145], v[190:193], v[106:109]
	v_mfma_f32_16x16x32_bf16 v[94:97], v[134:137], v[198:201], v[94:97]
	v_mfma_f32_16x16x32_bf16 v[90:93], v[142:145], v[198:201], v[90:93]
	v_mfma_f32_16x16x32_bf16 v[78:81], v[134:137], v[206:209], v[78:81]
	v_mfma_f32_16x16x32_bf16 v[74:77], v[142:145], v[206:209], v[74:77]
	v_mfma_f32_16x16x32_bf16 v[118:121], v[166:169], v[182:185], v[118:121]
	v_mfma_f32_16x16x32_bf16 v[114:117], v[174:177], v[182:185], v[114:117]
	v_mfma_f32_16x16x32_bf16 v[102:105], v[166:169], v[190:193], v[102:105]
	v_mfma_f32_16x16x32_bf16 v[98:101], v[174:177], v[190:193], v[98:101]
	v_mfma_f32_16x16x32_bf16 v[86:89], v[166:169], v[198:201], v[86:89]
	v_mfma_f32_16x16x32_bf16 v[82:85], v[174:177], v[198:201], v[82:85]
	v_mfma_f32_16x16x32_bf16 v[70:73], v[166:169], v[206:209], v[70:73]
	v_mfma_f32_16x16x32_bf16 v[66:69], v[174:177], v[206:209], v[66:69]
	s_barrier
	s_setprio 0
	s_add_u32 s16, s24, 0x80
	s_addc_u32 s17, s25, 0
	s_add_i32 s26, s54, s33
	s_mov_b32 m0, s26
	ds_read_b128 v[178:181], v164 offset:49152
	ds_read_b128 v[182:185], v164 offset:50176
	ds_read_b128 v[186:189], v164 offset:51200
	ds_read_b128 v[190:193], v164 offset:52224
	ds_read_b128 v[194:197], v164 offset:53248
	ds_read_b128 v[198:201], v164 offset:54272
	ds_read_b128 v[202:205], v164 offset:55296
	ds_read_b128 v[206:209], v164 offset:56320
	s_nop 0
	global_load_lds_dwordx4 v156, s[16:17]
	s_add_i32 m0, s26, 0x2000
	s_nop 0
	global_load_lds_dwordx4 v158, s[16:17]
	s_add_u32 s16, s24, 0x300080
	s_addc_u32 s17, s25, 0
	s_add_i32 s24, s55, s33
	s_mov_b32 m0, s24
	s_nop 0
	global_load_lds_dwordx4 v156, s[16:17]
	s_add_i32 m0, s24, 0x2000
	s_nop 0
	global_load_lds_dwordx4 v158, s[16:17]
	s_mov_b32 m0, s39
	s_nop 0
	global_load_lds_dwordx4 v1, s[2:3]
	s_mov_b32 m0, s40
	s_nop 0
	global_load_lds_dwordx4 v157, s[2:3]
	s_waitcnt vmcnt(8)
	s_waitcnt lgkmcnt(0)
	s_setprio 1
	s_waitcnt lgkmcnt(0)
	s_barrier
	v_mfma_f32_16x16x32_bf16 v[62:65], v[130:133], v[178:181], v[62:65]
	v_mfma_f32_16x16x32_bf16 v[58:61], v[138:141], v[178:181], v[58:61]
	v_mfma_f32_16x16x32_bf16 v[46:49], v[130:133], v[186:189], v[46:49]
	v_mfma_f32_16x16x32_bf16 v[42:45], v[138:141], v[186:189], v[42:45]
	v_mfma_f32_16x16x32_bf16 v[30:33], v[130:133], v[194:197], v[30:33]
	v_mfma_f32_16x16x32_bf16 v[26:29], v[138:141], v[194:197], v[26:29]
	v_mfma_f32_16x16x32_bf16 v[14:17], v[130:133], v[202:205], v[14:17]
	v_mfma_f32_16x16x32_bf16 v[10:13], v[138:141], v[202:205], v[10:13]
	v_mfma_f32_16x16x32_bf16 v[54:57], v[150:153], v[178:181], v[54:57]
	v_mfma_f32_16x16x32_bf16 v[50:53], v[170:173], v[178:181], v[50:53]
	v_mfma_f32_16x16x32_bf16 v[38:41], v[150:153], v[186:189], v[38:41]
	v_mfma_f32_16x16x32_bf16 v[34:37], v[170:173], v[186:189], v[34:37]
	v_mfma_f32_16x16x32_bf16 v[22:25], v[150:153], v[194:197], v[22:25]
	v_mfma_f32_16x16x32_bf16 v[18:21], v[170:173], v[194:197], v[18:21]
	v_mfma_f32_16x16x32_bf16 v[6:9], v[150:153], v[202:205], v[6:9]
	v_mfma_f32_16x16x32_bf16 v[2:5], v[170:173], v[202:205], v[2:5]
	v_mfma_f32_16x16x32_bf16 v[62:65], v[134:137], v[182:185], v[62:65]
	v_mfma_f32_16x16x32_bf16 v[58:61], v[142:145], v[182:185], v[58:61]
	v_mfma_f32_16x16x32_bf16 v[46:49], v[134:137], v[190:193], v[46:49]
	v_mfma_f32_16x16x32_bf16 v[42:45], v[142:145], v[190:193], v[42:45]
	v_mfma_f32_16x16x32_bf16 v[30:33], v[134:137], v[198:201], v[30:33]
	v_mfma_f32_16x16x32_bf16 v[26:29], v[142:145], v[198:201], v[26:29]
	v_mfma_f32_16x16x32_bf16 v[14:17], v[134:137], v[206:209], v[14:17]
	v_mfma_f32_16x16x32_bf16 v[10:13], v[142:145], v[206:209], v[10:13]
	v_mfma_f32_16x16x32_bf16 v[54:57], v[166:169], v[182:185], v[54:57]
	v_mfma_f32_16x16x32_bf16 v[50:53], v[174:177], v[182:185], v[50:53]
	v_mfma_f32_16x16x32_bf16 v[38:41], v[166:169], v[190:193], v[38:41]
	v_mfma_f32_16x16x32_bf16 v[34:37], v[174:177], v[190:193], v[34:37]
	v_mfma_f32_16x16x32_bf16 v[22:25], v[166:169], v[198:201], v[22:25]
	v_mfma_f32_16x16x32_bf16 v[18:21], v[174:177], v[198:201], v[18:21]
	v_mfma_f32_16x16x32_bf16 v[6:9], v[166:169], v[206:209], v[6:9]
	v_mfma_f32_16x16x32_bf16 v[2:5], v[174:177], v[206:209], v[2:5]
	s_barrier
	s_setprio 0
	s_add_i32 s53, s53, 2
	s_add_u32 s51, s51, 0x100
	s_addc_u32 s52, s52, 0
	s_cmpk_gt_u32 s53, 0xbd
	s_mov_b64 s[16:17], s[20:21]
	s_cbranch_scc0 .LBB0_1125
	s_and_b64 vcc, exec, s[14:15]
	s_cbranch_vccz .LBB0_1128
	s_barrier

; #define PG8_STAGE(bufoff, gbase, voff) do { const char* _gb = (const char*)(gbase); asm volatile("" : "+s"(_gb)); _Pragma("unroll") for (int _i = 0; _i < 2; ++_i) { asm volatile("" : "+v"((voff)[_i])); \
;         __builtin_amdgcn_global_load_lds((const unsigned*)(_gb + (voff)[_i]), (PG8_LAS unsigned*)(lds + (bufoff) + ldsw + _i * 8192), 16, 0, 0); } } while (0)
; #define PG8_LDA(dst, b, h) do { _Pragma("unroll") for (int m = 0; m < 4; ++m) _Pragma("unroll") for (int k = 0; k < 2; ++k) dst[m][k] = *(const PG8_LAS bf16x8*)(lds + PG8_SA(b, h) + aoff + m * 2048 + k * 1024); } while (0)
; #define PG8_LDB(dst, b, h) do { _Pragma("unroll") for (int n = 0; n < 2; ++n) _Pragma("unroll") for (int k = 0; k < 2; ++k) dst[n][k] = *(const PG8_LAS bf16x8*)(lds + PG8_SB(b, h) + boff + n * 2048 + k * 1024); } while (0)
; #define PG8_WAIT_V(n) asm volatile("s_waitcnt vmcnt(" #n ")" ::: "memory")
; #define PG8_WAIT_L(n) asm volatile("s_waitcnt lgkmcnt(" #n ")" ::: "memory")
; #define PG8_BAR __builtin_amdgcn_s_barrier()
; #define PG8_SCHED __builtin_amdgcn_sched_barrier(0)
; #define PG8_LDA(dst, b, h) do { _Pragma("unroll") for (int m = 0; m < 4; ++m) _Pragma("unroll") for (int k = 0; k < 2; ++k) dst[m][k] = *(const PG8_LAS bf16x8*)(lds + PG8_SA(b, h) + aoff + m * 2048 + k * 1024); } while (0)
; template <class Epi, class Sched, bool ALIGN_EPI = false, bool SP2 = false>
; __device__ __forceinline__ void gemm_phase(PG8_LAS unsigned char* lds, const Gemm g, const Sched& S, const Epi& E) {
;     ...
;             PG8_LDB(B0, 0, 0); PG8_LDB(B1, 0, 1); PG8_SCHED; PG8_LDA(At, 0, 0); PG8_STAGE(PG8_SA(1, 1), a1 + hstep, voffA);
;             PG8_WAIT_V(8); PG8_WAIT_L(0); PG8_BAR; PG8_MMA2(0); PG8_BAR; PG8_SCHED;
;             PG8_LDA(At, 0, 1); PG8_STAGE(PG8_SB(0, 0), b2, voffB); PG8_STAGE(PG8_SB(0, 1), b2 + hstep, voffB); PG8_STAGE(PG8_SA(0, 0), a2, voffA);
;             PG8_WAIT_V(8); PG8_WAIT_L(0); PG8_BAR; PG8_MMA2(1); PG8_BAR; PG8_SCHED;
;             PG8_LDB(B0, 1, 0); PG8_LDB(B1, 1, 1); PG8_SCHED; PG8_LDA(At, 1, 0); PG8_STAGE(PG8_SA(0, 1), a2 + hstep, voffA);
;             PG8_WAIT_V(8); PG8_WAIT_L(0); PG8_BAR; PG8_MMA2(0); PG8_BAR; PG8_SCHED;
;             PG8_LDA(At, 1, 1); PG8_STAGE(PG8_SB(1, 0), b3, voffB); PG8_STAGE(PG8_SB(1, 1), b3 + hstep, voffB); PG8_STAGE(PG8_SA(1, 0), a3, voffA);
;             PG8_WAIT_V(8); PG8_WAIT_L(0); PG8_BAR; PG8_MMA2(1); PG8_BAR; PG8_SCHED;
.LBB0_1217:
	ds_read_b128 v[128:131], v175
	ds_read_b128 v[132:135], v175 offset:1024
	ds_read_b128 v[136:139], v175 offset:2048
	ds_read_b128 v[140:143], v175 offset:3072
	ds_read_b128 v[152:155], v176
	ds_read_b128 v[156:159], v176 offset:1024
	ds_read_b128 v[160:163], v176 offset:2048
	ds_read_b128 v[184:187], v176 offset:3072
	s_add_u32 s28, s6, 0x100
	s_addc_u32 s29, s7, 0
	s_cmpk_eq_i32 s58, 0xbc
	s_cselect_b32 s36, s57, s28
	s_cselect_b32 s37, s56, s29
	s_cselect_b32 s34, s8, s4
	s_cselect_b32 s35, s9, s5
	s_add_u32 s30, s36, 0x80
	s_addc_u32 s31, s37, 0
	s_add_u32 s6, s6, 0x300080
	s_addc_u32 s7, s7, 0
	s_add_i32 m0, s41, 0xc000
	ds_read_b128 v[188:191], v177
	ds_read_b128 v[192:195], v177 offset:1024
	ds_read_b128 v[196:199], v177 offset:2048
	ds_read_b128 v[200:203], v177 offset:3072
	ds_read_b128 v[204:207], v177 offset:4096
	ds_read_b128 v[208:211], v177 offset:5120
	ds_read_b128 v[212:215], v177 offset:6144
	ds_read_b128 v[216:219], v177 offset:7168
	s_nop 0
	global_load_lds_dwordx4 v167, s[6:7]
	s_add_i32 m0, s41, 0xe000
	s_nop 0
	global_load_lds_dwordx4 v171, s[6:7]
	s_waitcnt vmcnt(8)
	s_waitcnt lgkmcnt(0)
	s_setprio 1
	s_waitcnt lgkmcnt(0)
	s_barrier
	v_mfma_f32_16x16x32_bf16 v[124:127], v[128:131], v[188:191], v[124:127]
	v_mfma_f32_16x16x32_bf16 v[120:123], v[136:139], v[188:191], v[120:123]
	v_mfma_f32_16x16x32_bf16 v[108:111], v[128:131], v[196:199], v[108:111]
	v_mfma_f32_16x16x32_bf16 v[104:107], v[136:139], v[196:199], v[104:107]
	v_mfma_f32_16x16x32_bf16 v[92:95], v[128:131], v[204:207], v[92:95]
	v_mfma_f32_16x16x32_bf16 v[88:91], v[136:139], v[204:207], v[88:91]
	v_mfma_f32_16x16x32_bf16 v[76:79], v[128:131], v[212:215], v[76:79]
	v_mfma_f32_16x16x32_bf16 v[72:75], v[136:139], v[212:215], v[72:75]
	v_mfma_f32_16x16x32_bf16 v[116:119], v[152:155], v[188:191], v[116:119]
	v_mfma_f32_16x16x32_bf16 v[112:115], v[160:163], v[188:191], v[112:115]
	v_mfma_f32_16x16x32_bf16 v[100:103], v[152:155], v[196:199], v[100:103]
	v_mfma_f32_16x16x32_bf16 v[96:99], v[160:163], v[196:199], v[96:99]
	v_mfma_f32_16x16x32_bf16 v[84:87], v[152:155], v[204:207], v[84:87]
	v_mfma_f32_16x16x32_bf16 v[80:83], v[160:163], v[204:207], v[80:83]
	v_mfma_f32_16x16x32_bf16 v[68:71], v[152:155], v[212:215], v[68:71]
	v_mfma_f32_16x16x32_bf16 v[64:67], v[160:163], v[212:215], v[64:67]
	v_mfma_f32_16x16x32_bf16 v[124:127], v[132:135], v[192:195], v[124:127]
	v_mfma_f32_16x16x32_bf16 v[120:123], v[140:143], v[192:195], v[120:123]
	v_mfma_f32_16x16x32_bf16 v[108:111], v[132:135], v[200:203], v[108:111]
	v_mfma_f32_16x16x32_bf16 v[104:107], v[140:143], v[200:203], v[104:107]
	v_mfma_f32_16x16x32_bf16 v[92:95], v[132:135], v[208:211], v[92:95]
	v_mfma_f32_16x16x32_bf16 v[88:91], v[140:143], v[208:211], v[88:91]
	v_mfma_f32_16x16x32_bf16 v[76:79], v[132:135], v[216:219], v[76:79]
	v_mfma_f32_16x16x32_bf16 v[72:75], v[140:143], v[216:219], v[72:75]
	v_mfma_f32_16x16x32_bf16 v[116:119], v[156:159], v[192:195], v[116:119]
	v_mfma_f32_16x16x32_bf16 v[112:115], v[184:187], v[192:195], v[112:115]
	v_mfma_f32_16x16x32_bf16 v[100:103], v[156:159], v[200:203], v[100:103]
	v_mfma_f32_16x16x32_bf16 v[96:99], v[184:187], v[200:203], v[96:99]
	v_mfma_f32_16x16x32_bf16 v[84:87], v[156:159], v[208:211], v[84:87]
	v_mfma_f32_16x16x32_bf16 v[80:83], v[184:187], v[208:211], v[80:83]
	v_mfma_f32_16x16x32_bf16 v[68:71], v[156:159], v[216:219], v[68:71]
	v_mfma_f32_16x16x32_bf16 v[64:67], v[184:187], v[216:219], v[64:67]
	s_barrier
	s_setprio 0
	s_add_i32 s59, s49, s39
	s_mov_b64 s[6:7], s[34:35]
	s_mov_b32 m0, s59
	ds_read_b128 v[188:191], v177 offset:16384
	ds_read_b128 v[192:195], v177 offset:17408
	ds_read_b128 v[196:199], v177 offset:18432
	ds_read_b128 v[200:203], v177 offset:19456
	ds_read_b128 v[204:207], v177 offset:20480
	ds_read_b128 v[208:211], v177 offset:21504
	ds_read_b128 v[212:215], v177 offset:22528
	ds_read_b128 v[216:219], v177 offset:23552
	s_nop 0
	global_load_lds_dwordx4 v169, s[6:7]
	s_add_i32 m0, s59, 0x2000
	s_nop 0
	global_load_lds_dwordx4 v172, s[6:7]
	s_add_u32 s6, s34, 0x300000
	s_addc_u32 s7, s35, 0
	s_add_i32 s59, s50, s39
	s_mov_b32 m0, s59
	s_nop 0
	global_load_lds_dwordx4 v169, s[6:7]
	s_add_i32 m0, s59, 0x2000
	s_nop 0
	global_load_lds_dwordx4 v172, s[6:7]
	s_mov_b64 s[6:7], s[36:37]
	s_mov_b32 m0, s41
	s_nop 0
	global_load_lds_dwordx4 v167, s[6:7]
	s_mov_b32 m0, s42
	s_nop 0
	global_load_lds_dwordx4 v171, s[6:7]
	s_waitcnt vmcnt(8)
	s_waitcnt lgkmcnt(0)
	s_setprio 1
	s_waitcnt lgkmcnt(0)
	s_barrier
	v_mfma_f32_16x16x32_bf16 v[60:63], v[128:131], v[188:191], v[60:63]
	v_mfma_f32_16x16x32_bf16 v[56:59], v[136:139], v[188:191], v[56:59]
	v_mfma_f32_16x16x32_bf16 v[44:47], v[128:131], v[196:199], v[44:47]
	v_mfma_f32_16x16x32_bf16 v[40:43], v[136:139], v[196:199], v[40:43]
	v_mfma_f32_16x16x32_bf16 v[28:31], v[128:131], v[204:207], v[28:31]
	v_mfma_f32_16x16x32_bf16 v[24:27], v[136:139], v[204:207], v[24:27]
	v_mfma_f32_16x16x32_bf16 v[12:15], v[128:131], v[212:215], v[12:15]
	v_mfma_f32_16x16x32_bf16 v[8:11], v[136:139], v[212:215], v[8:11]
	v_mfma_f32_16x16x32_bf16 v[52:55], v[152:155], v[188:191], v[52:55]
	v_mfma_f32_16x16x32_bf16 v[48:51], v[160:163], v[188:191], v[48:51]
	v_mfma_f32_16x16x32_bf16 v[36:39], v[152:155], v[196:199], v[36:39]
	v_mfma_f32_16x16x32_bf16 v[32:35], v[160:163], v[196:199], v[32:35]
	v_mfma_f32_16x16x32_bf16 v[20:23], v[152:155], v[204:207], v[20:23]
	v_mfma_f32_16x16x32_bf16 v[16:19], v[160:163], v[204:207], v[16:19]
	v_mfma_f32_16x16x32_bf16 v[4:7], v[152:155], v[212:215], v[4:7]
	v_mfma_f32_16x16x32_bf16 v[0:3], v[160:163], v[212:215], v[0:3]
	v_mfma_f32_16x16x32_bf16 v[60:63], v[132:135], v[192:195], v[60:63]
	v_mfma_f32_16x16x32_bf16 v[56:59], v[140:143], v[192:195], v[56:59]
	v_mfma_f32_16x16x32_bf16 v[44:47], v[132:135], v[200:203], v[44:47]
	v_mfma_f32_16x16x32_bf16 v[40:43], v[140:143], v[200:203], v[40:43]
	v_mfma_f32_16x16x32_bf16 v[28:31], v[132:135], v[208:211], v[28:31]
	v_mfma_f32_16x16x32_bf16 v[24:27], v[140:143], v[208:211], v[24:27]
	v_mfma_f32_16x16x32_bf16 v[12:15], v[132:135], v[216:219], v[12:15]
	v_mfma_f32_16x16x32_bf16 v[8:11], v[140:143], v[216:219], v[8:11]
	v_mfma_f32_16x16x32_bf16 v[52:55], v[156:159], v[192:195], v[52:55]
	v_mfma_f32_16x16x32_bf16 v[48:51], v[184:187], v[192:195], v[48:51]
	v_mfma_f32_16x16x32_bf16 v[36:39], v[156:159], v[200:203], v[36:39]
	v_mfma_f32_16x16x32_bf16 v[32:35], v[184:187], v[200:203], v[32:35]
	v_mfma_f32_16x16x32_bf16 v[20:23], v[156:159], v[208:211], v[20:23]
	v_mfma_f32_16x16x32_bf16 v[16:19], v[184:187], v[208:211], v[16:19]
	v_mfma_f32_16x16x32_bf16 v[4:7], v[156:159], v[216:219], v[4:7]
	v_mfma_f32_16x16x32_bf16 v[0:3], v[184:187], v[216:219], v[0:3]
	s_barrier
; #define PG8_STAGE(bufoff, gbase, voff) do { const char* _gb = (const char*)(gbase); asm volatile("" : "+s"(_gb)); _Pragma("unroll") for (int _i = 0; _i < 2; ++_i) { asm volatile("" : "+v"((voff)[_i])); \
;         __builtin_amdgcn_global_load_lds((const unsigned*)(_gb + (voff)[_i]), (PG8_LAS unsigned*)(lds + (bufoff) + ldsw + _i * 8192), 16, 0, 0); } } while (0)
; #define PG8_LDA(dst, b, h) do { _Pragma("unroll") for (int m = 0; m < 4; ++m) _Pragma("unroll") for (int k = 0; k < 2; ++k) dst[m][k] = *(const PG8_LAS bf16x8*)(lds + PG8_SA(b, h) + aoff + m * 2048 + k * 1024); } while (0)
; #define PG8_LDB(dst, b, h) do { _Pragma("unroll") for (int n = 0; n < 2; ++n) _Pragma("unroll") for (int k = 0; k < 2; ++k) dst[n][k] = *(const PG8_LAS bf16x8*)(lds + PG8_SB(b, h) + boff + n * 2048 + k * 1024); } while (0)
; #define PG8_WAIT_V(n) asm volatile("s_waitcnt vmcnt(" #n ")" ::: "memory")
; #define PG8_WAIT_L(n) asm volatile("s_waitcnt lgkmcnt(" #n ")" ::: "memory")
; #define PG8_BAR __builtin_amdgcn_s_barrier()
; #define PG8_SCHED __builtin_amdgcn_sched_barrier(0)
; #define PG8_WAIT_V(n) asm volatile("s_waitcnt vmcnt(" #n ")" ::: "memory")
; #define PG8_WAIT_L(n) asm volatile("s_waitcnt lgkmcnt(" #n ")" ::: "memory")
; template <class Epi, class Sched, bool ALIGN_EPI = false, bool SP2 = false>
; __device__ __forceinline__ void gemm_phase(PG8_LAS unsigned char* lds, const Gemm g, const Sched& S, const Epi& E) {
;     ...
;             PG8_LDB(B0, 0, 0); PG8_LDB(B1, 0, 1); PG8_SCHED; PG8_LDA(At, 0, 0); PG8_STAGE(PG8_SA(1, 1), a1 + hstep, voffA);
;             PG8_WAIT_V(8); PG8_WAIT_L(0); PG8_BAR; PG8_MMA2(0); PG8_BAR; PG8_SCHED;
;             PG8_LDA(At, 0, 1); PG8_STAGE(PG8_SB(0, 0), b2, voffB); PG8_STAGE(PG8_SB(0, 1), b2 + hstep, voffB); PG8_STAGE(PG8_SA(0, 0), a2, voffA);
;             PG8_WAIT_V(8); PG8_WAIT_L(0); PG8_BAR; PG8_MMA2(1); PG8_BAR; PG8_SCHED;
;             PG8_LDB(B0, 1, 0); PG8_LDB(B1, 1, 1); PG8_SCHED; PG8_LDA(At, 1, 0); PG8_STAGE(PG8_SA(0, 1), a2 + hstep, voffA);
;             PG8_WAIT_V(8); PG8_WAIT_L(0); PG8_BAR; PG8_MMA2(0); PG8_BAR; PG8_SCHED;
;             PG8_LDA(At, 1, 1); PG8_STAGE(PG8_SB(1, 0), b3, voffB); PG8_STAGE(PG8_SB(1, 1), b3 + hstep, voffB); PG8_STAGE(PG8_SA(1, 0), a3, voffA);
;             PG8_WAIT_V(8); PG8_WAIT_L(0); PG8_BAR; PG8_MMA2(1); PG8_BAR; PG8_SCHED;
;     ...
;         if constexpr (ALIGN_EPI) { if (wr == 0) PG8_BAR; }
	s_setprio 0
	s_add_i32 s59, 0, 0x18000
	s_add_i32 s60, 0, 0x1c000
	v_add_u32_e32 v140, s59, v174
	v_add_u32_e32 v164, s60, v174
	ds_read_b128 v[128:131], v140
	ds_read_b128 v[132:135], v140 offset:1024
	ds_read_b128 v[136:139], v140 offset:2048
	ds_read_b128 v[140:143], v140 offset:3072
	ds_read_b128 v[152:155], v164
	ds_read_b128 v[156:159], v164 offset:1024
	ds_read_b128 v[160:163], v164 offset:2048
	ds_read_b128 v[184:187], v164 offset:3072
	s_add_u32 s6, s36, 0x300000
	s_addc_u32 s7, s37, 0
	s_mov_b32 m0, s43
	ds_read_b128 v[188:191], v177 offset:32768
	ds_read_b128 v[192:195], v177 offset:33792
	ds_read_b128 v[196:199], v177 offset:34816
	ds_read_b128 v[200:203], v177 offset:35840
	ds_read_b128 v[204:207], v177 offset:36864
	ds_read_b128 v[208:211], v177 offset:37888
	ds_read_b128 v[212:215], v177 offset:38912
	ds_read_b128 v[216:219], v177 offset:39936
	s_nop 0
	global_load_lds_dwordx4 v167, s[6:7]
	s_mov_b32 m0, s44
	s_nop 0
	global_load_lds_dwordx4 v171, s[6:7]
	s_waitcnt vmcnt(8)
	s_waitcnt lgkmcnt(0)
	s_setprio 1
	s_waitcnt lgkmcnt(0)
	s_barrier
	v_mfma_f32_16x16x32_bf16 v[124:127], v[128:131], v[188:191], v[124:127]
	v_mfma_f32_16x16x32_bf16 v[120:123], v[136:139], v[188:191], v[120:123]
	v_mfma_f32_16x16x32_bf16 v[108:111], v[128:131], v[196:199], v[108:111]
	v_mfma_f32_16x16x32_bf16 v[104:107], v[136:139], v[196:199], v[104:107]
	v_mfma_f32_16x16x32_bf16 v[92:95], v[128:131], v[204:207], v[92:95]
	v_mfma_f32_16x16x32_bf16 v[88:91], v[136:139], v[204:207], v[88:91]
	v_mfma_f32_16x16x32_bf16 v[76:79], v[128:131], v[212:215], v[76:79]
	v_mfma_f32_16x16x32_bf16 v[72:75], v[136:139], v[212:215], v[72:75]
	v_mfma_f32_16x16x32_bf16 v[116:119], v[152:155], v[188:191], v[116:119]
	v_mfma_f32_16x16x32_bf16 v[112:115], v[160:163], v[188:191], v[112:115]
	v_mfma_f32_16x16x32_bf16 v[100:103], v[152:155], v[196:199], v[100:103]
	v_mfma_f32_16x16x32_bf16 v[96:99], v[160:163], v[196:199], v[96:99]
	v_mfma_f32_16x16x32_bf16 v[84:87], v[152:155], v[204:207], v[84:87]
	v_mfma_f32_16x16x32_bf16 v[80:83], v[160:163], v[204:207], v[80:83]
	v_mfma_f32_16x16x32_bf16 v[68:71], v[152:155], v[212:215], v[68:71]
	v_mfma_f32_16x16x32_bf16 v[64:67], v[160:163], v[212:215], v[64:67]
	v_mfma_f32_16x16x32_bf16 v[124:127], v[132:135], v[192:195], v[124:127]
	v_mfma_f32_16x16x32_bf16 v[120:123], v[140:143], v[192:195], v[120:123]
	v_mfma_f32_16x16x32_bf16 v[108:111], v[132:135], v[200:203], v[108:111]
	v_mfma_f32_16x16x32_bf16 v[104:107], v[140:143], v[200:203], v[104:107]
	v_mfma_f32_16x16x32_bf16 v[92:95], v[132:135], v[208:211], v[92:95]
	v_mfma_f32_16x16x32_bf16 v[88:91], v[140:143], v[208:211], v[88:91]
	v_mfma_f32_16x16x32_bf16 v[76:79], v[132:135], v[216:219], v[76:79]
	v_mfma_f32_16x16x32_bf16 v[72:75], v[140:143], v[216:219], v[72:75]
	v_mfma_f32_16x16x32_bf16 v[116:119], v[156:159], v[192:195], v[116:119]
	v_mfma_f32_16x16x32_bf16 v[112:115], v[184:187], v[192:195], v[112:115]
	v_mfma_f32_16x16x32_bf16 v[100:103], v[156:159], v[200:203], v[100:103]
	v_mfma_f32_16x16x32_bf16 v[96:99], v[184:187], v[200:203], v[96:99]
	v_mfma_f32_16x16x32_bf16 v[84:87], v[156:159], v[208:211], v[84:87]
	v_mfma_f32_16x16x32_bf16 v[80:83], v[184:187], v[208:211], v[80:83]
	v_mfma_f32_16x16x32_bf16 v[68:71], v[156:159], v[216:219], v[68:71]
	v_mfma_f32_16x16x32_bf16 v[64:67], v[184:187], v[216:219], v[64:67]
	s_barrier
	s_setprio 0
	s_add_u32 s6, s34, 0x80
	s_addc_u32 s7, s35, 0
	s_add_i32 s36, s59, s39
	s_mov_b32 m0, s36
	ds_read_b128 v[188:191], v177 offset:49152
	ds_read_b128 v[192:195], v177 offset:50176
	ds_read_b128 v[196:199], v177 offset:51200
	ds_read_b128 v[200:203], v177 offset:52224
	ds_read_b128 v[204:207], v177 offset:53248
	ds_read_b128 v[208:211], v177 offset:54272
	ds_read_b128 v[212:215], v177 offset:55296
	ds_read_b128 v[216:219], v177 offset:56320
	s_nop 0
	global_load_lds_dwordx4 v169, s[6:7]
	s_add_i32 m0, s36, 0x2000
	s_nop 0
	global_load_lds_dwordx4 v172, s[6:7]
	s_add_u32 s6, s34, 0x300080
	s_addc_u32 s7, s35, 0
	s_add_i32 s34, s60, s39
	s_mov_b32 m0, s34
	s_nop 0
	global_load_lds_dwordx4 v169, s[6:7]
	s_add_i32 m0, s34, 0x2000
	s_nop 0
	global_load_lds_dwordx4 v172, s[6:7]
	s_mov_b32 m0, s47
	s_nop 0
	global_load_lds_dwordx4 v167, s[30:31]
	s_mov_b32 m0, s48
	s_nop 0
	global_load_lds_dwordx4 v171, s[30:31]
	s_waitcnt vmcnt(8)
	s_waitcnt lgkmcnt(0)
	s_setprio 1
	s_waitcnt lgkmcnt(0)
	s_barrier
	v_mfma_f32_16x16x32_bf16 v[60:63], v[128:131], v[188:191], v[60:63]
	v_mfma_f32_16x16x32_bf16 v[56:59], v[136:139], v[188:191], v[56:59]
	v_mfma_f32_16x16x32_bf16 v[44:47], v[128:131], v[196:199], v[44:47]
	v_mfma_f32_16x16x32_bf16 v[40:43], v[136:139], v[196:199], v[40:43]
	v_mfma_f32_16x16x32_bf16 v[28:31], v[128:131], v[204:207], v[28:31]
	v_mfma_f32_16x16x32_bf16 v[24:27], v[136:139], v[204:207], v[24:27]
	v_mfma_f32_16x16x32_bf16 v[12:15], v[128:131], v[212:215], v[12:15]
	v_mfma_f32_16x16x32_bf16 v[8:11], v[136:139], v[212:215], v[8:11]
	v_mfma_f32_16x16x32_bf16 v[52:55], v[152:155], v[188:191], v[52:55]
	v_mfma_f32_16x16x32_bf16 v[48:51], v[160:163], v[188:191], v[48:51]
	v_mfma_f32_16x16x32_bf16 v[36:39], v[152:155], v[196:199], v[36:39]
	v_mfma_f32_16x16x32_bf16 v[32:35], v[160:163], v[196:199], v[32:35]
	v_mfma_f32_16x16x32_bf16 v[20:23], v[152:155], v[204:207], v[20:23]
	v_mfma_f32_16x16x32_bf16 v[16:19], v[160:163], v[204:207], v[16:19]
	v_mfma_f32_16x16x32_bf16 v[4:7], v[152:155], v[212:215], v[4:7]
	v_mfma_f32_16x16x32_bf16 v[0:3], v[160:163], v[212:215], v[0:3]
	v_mfma_f32_16x16x32_bf16 v[60:63], v[132:135], v[192:195], v[60:63]
	v_mfma_f32_16x16x32_bf16 v[56:59], v[140:143], v[192:195], v[56:59]
	v_mfma_f32_16x16x32_bf16 v[44:47], v[132:135], v[200:203], v[44:47]
	v_mfma_f32_16x16x32_bf16 v[40:43], v[140:143], v[200:203], v[40:43]
	v_mfma_f32_16x16x32_bf16 v[28:31], v[132:135], v[208:211], v[28:31]
	v_mfma_f32_16x16x32_bf16 v[24:27], v[140:143], v[208:211], v[24:27]
	v_mfma_f32_16x16x32_bf16 v[12:15], v[132:135], v[216:219], v[12:15]
	v_mfma_f32_16x16x32_bf16 v[8:11], v[140:143], v[216:219], v[8:11]
	v_mfma_f32_16x16x32_bf16 v[52:55], v[156:159], v[192:195], v[52:55]
	v_mfma_f32_16x16x32_bf16 v[48:51], v[184:187], v[192:195], v[48:51]
	v_mfma_f32_16x16x32_bf16 v[36:39], v[156:159], v[200:203], v[36:39]
	v_mfma_f32_16x16x32_bf16 v[32:35], v[184:187], v[200:203], v[32:35]
	v_mfma_f32_16x16x32_bf16 v[20:23], v[156:159], v[208:211], v[20:23]
	v_mfma_f32_16x16x32_bf16 v[16:19], v[184:187], v[208:211], v[16:19]
	v_mfma_f32_16x16x32_bf16 v[4:7], v[156:159], v[216:219], v[4:7]
	v_mfma_f32_16x16x32_bf16 v[0:3], v[184:187], v[216:219], v[0:3]
	s_barrier
	s_setprio 0
	s_add_i32 s58, s58, 2
	s_add_u32 s4, s4, 0x100
	s_addc_u32 s5, s5, 0
	s_cmpk_gt_u32 s58, 0xbd
	s_mov_b64 s[6:7], s[28:29]
	s_cbranch_scc0 .LBB0_1217
	s_and_b64 vcc, exec, s[18:19]
	s_cbranch_vccz .LBB0_1220
	s_barrier
